# all s_setprio flips deleted from the eight GEMM K-loops (A/B of the per-phase priority windows); on top of v64
# speedup vs baseline: 1.0085x; 1.0050x over previous
; #define PG8_STAGE(bufoff, gbase, voff) do { _Pragma("unroll") for (int _i = 0; _i < 2; ++_i) \
;         __builtin_amdgcn_global_load_lds((const unsigned*)((const char*)(gbase) + (voff)[_i]), (PG8_LAS unsigned*)(lds + (bufoff) + ldsw + _i * 8192), 16, 0, 0); } while (0)
; #define PG8_LDA(dst, b, h) do { _Pragma("unroll") for (int m = 0; m < 4; ++m) _Pragma("unroll") for (int k = 0; k < 2; ++k) dst[m][k] = *(const PG8_LAS bf16x8*)(lds + PG8_SA(b, h) + aoff + m * 2048 + k * 1024); } while (0)
; #define PG8_LDB(dst, b, h) do { _Pragma("unroll") for (int n = 0; n < 2; ++n) _Pragma("unroll") for (int k = 0; k < 2; ++k) dst[n][k] = *(const PG8_LAS bf16x8*)(lds + PG8_SB(b, h) + boff + n * 2048 + k * 1024); } while (0)
; #define PG8_MMA(ai, bj, At, Bt) do { __builtin_amdgcn_s_setprio(1); _Pragma("unroll") for (int m = 0; m < 4; ++m) _Pragma("unroll") for (int n = 0; n < 2; ++n) _Pragma("unroll") for (int k = 0; k < 2; ++k) \
;         acc[ai][bj][m][n] = __builtin_amdgcn_mfma_f32_16x16x32_bf16(Bt[n][k], At[m][k], acc[ai][bj][m][n], 0, 0, 0); __builtin_amdgcn_s_setprio(0); } while (0)
; template <class Epi, bool ALIGN_EPI, bool ABLK = false>
; __device__ __forceinline__ void gemm_phase(PG8_LAS unsigned char* lds, const Gemm g, const StaticOrder& S, const Epi& E) {
;     ...
;         for (int t = 0; t < nt; t += 2) {
;             const bool last = (t == nt - 2);
;             const char* a1 = cA + (size_t)(t + 1) * kstepA;
;             const char* a2 = last ? nA : cA + (size_t)(t + 2) * kstepA; const char* b2 = last ? nB : cB + (size_t)(t + 2) * kstepB;
;             const char* a3 = a2 + kstepA; const char* b3 = b2 + kstepB;
;             PG8_LDB(B0, 0, 0); PG8_LDB(B1, 0, 1); PG8_SCHED; PG8_LDA(At, 0, 0); PG8_STAGE(PG8_SA(1, 1), a1 + hstepA, voffA);
;             PG8_WAIT_V(8); PG8_WAIT_L(0); PG8_BAR; PG8_MMA(0, 0, At, B0); PG8_MMA(0, 1, At, B1); PG8_BAR; PG8_SCHED;
;             PG8_LDA(At, 0, 1); PG8_STAGE(PG8_SB(0, 0), b2, voffB); PG8_STAGE(PG8_SB(0, 1), b2 + hstepB, voffB); PG8_STAGE(PG8_SA(0, 0), a2, voffA);
;             PG8_WAIT_V(8); PG8_WAIT_L(0); PG8_BAR; PG8_MMA(1, 0, At, B0); PG8_MMA(1, 1, At, B1); PG8_BAR; PG8_SCHED;
;             PG8_LDB(B0, 1, 0); PG8_LDB(B1, 1, 1); PG8_SCHED; PG8_LDA(At, 1, 0); PG8_STAGE(PG8_SA(0, 1), a2 + hstepA, voffA);
;             PG8_WAIT_V(8); PG8_WAIT_L(0); PG8_BAR; PG8_MMA(0, 0, At, B0); PG8_MMA(0, 1, At, B1); PG8_BAR; PG8_SCHED;
.LBB0_402:
	ds_read_b128 v[132:135], v251
	ds_read_b128 v[136:139], v251 offset:1024
	ds_read_b128 v[140:143], v251 offset:2048
	ds_read_b128 v[186:189], v251 offset:3072
	ds_read_b128 v[190:193], v251 offset:16384
	ds_read_b128 v[194:197], v251 offset:17408
	ds_read_b128 v[198:201], v251 offset:18432
	ds_read_b128 v[202:205], v251 offset:19456
	s_add_u32 s48, s24, s46
	s_addc_u32 s49, s25, s47
	s_cmp_eq_u32 s70, 12
	s_cselect_b32 s85, s41, s49
	s_cselect_b32 s84, s66, s48
	s_cselect_b32 s49, s39, s69
	s_cselect_b32 s48, s67, s68
	s_mov_b64 s[74:75], 0xc000
	s_add_i32 m0, s55, 0xc000
	s_mov_b64 s[74:75], 0xe000
	ds_read_b128 v[206:209], v183
	ds_read_b128 v[210:213], v183 offset:1024
	ds_read_b128 v[214:217], v183 offset:2048
	ds_read_b128 v[218:221], v183 offset:3072
	ds_read_b128 v[222:225], v183 offset:4096
	ds_read_b128 v[226:229], v183 offset:5120
	ds_read_b128 v[230:233], v183 offset:6144
	ds_read_b128 v[234:237], v183 offset:7168
	global_load_lds_dwordx4 v249, s[82:83]
	s_add_i32 m0, s55, 0xe000
	s_nop 0
	global_load_lds_dwordx4 v250, s[82:83]
	s_waitcnt vmcnt(8)
	s_waitcnt lgkmcnt(0)
	s_barrier
	s_waitcnt lgkmcnt(0)
	v_mfma_f32_16x16x32_bf16 v[126:129], v[132:135], v[206:209], v[126:129]
	v_mfma_f32_16x16x32_bf16 v[122:125], v[140:143], v[206:209], v[122:125]
	v_mfma_f32_16x16x32_bf16 v[118:121], v[132:135], v[214:217], v[118:121]
	v_mfma_f32_16x16x32_bf16 v[114:117], v[140:143], v[214:217], v[114:117]
	v_mfma_f32_16x16x32_bf16 v[110:113], v[132:135], v[222:225], v[110:113]
	v_mfma_f32_16x16x32_bf16 v[106:109], v[140:143], v[222:225], v[106:109]
	v_mfma_f32_16x16x32_bf16 v[102:105], v[132:135], v[230:233], v[102:105]
	v_mfma_f32_16x16x32_bf16 v[98:101], v[140:143], v[230:233], v[98:101]
	v_mfma_f32_16x16x32_bf16 v[126:129], v[136:139], v[210:213], v[126:129]
	v_mfma_f32_16x16x32_bf16 v[122:125], v[186:189], v[210:213], v[122:125]
	v_mfma_f32_16x16x32_bf16 v[118:121], v[136:139], v[218:221], v[118:121]
	v_mfma_f32_16x16x32_bf16 v[114:117], v[186:189], v[218:221], v[114:117]
	v_mfma_f32_16x16x32_bf16 v[110:113], v[136:139], v[226:229], v[110:113]
	v_mfma_f32_16x16x32_bf16 v[106:109], v[186:189], v[226:229], v[106:109]
	v_mfma_f32_16x16x32_bf16 v[102:105], v[136:139], v[234:237], v[102:105]
	v_mfma_f32_16x16x32_bf16 v[98:101], v[186:189], v[234:237], v[98:101]
	v_mfma_f32_16x16x32_bf16 v[94:97], v[190:193], v[206:209], v[94:97]
	s_add_i32 s71, s64, s9
	v_mfma_f32_16x16x32_bf16 v[90:93], v[198:201], v[206:209], v[90:93]
	s_mov_b32 m0, s71
	v_mfma_f32_16x16x32_bf16 v[86:89], v[190:193], v[214:217], v[86:89]
	v_mfma_f32_16x16x32_bf16 v[82:85], v[198:201], v[214:217], v[82:85]
	v_mfma_f32_16x16x32_bf16 v[78:81], v[190:193], v[222:225], v[78:81]
	v_mfma_f32_16x16x32_bf16 v[74:77], v[198:201], v[222:225], v[74:77]
	v_mfma_f32_16x16x32_bf16 v[70:73], v[190:193], v[230:233], v[70:73]
	v_mfma_f32_16x16x32_bf16 v[66:69], v[198:201], v[230:233], v[66:69]
	v_mfma_f32_16x16x32_bf16 v[94:97], v[194:197], v[210:213], v[94:97]
	v_mfma_f32_16x16x32_bf16 v[90:93], v[202:205], v[210:213], v[90:93]
	v_mfma_f32_16x16x32_bf16 v[86:89], v[194:197], v[218:221], v[86:89]
	v_mfma_f32_16x16x32_bf16 v[82:85], v[202:205], v[218:221], v[82:85]
	v_mfma_f32_16x16x32_bf16 v[78:81], v[194:197], v[226:229], v[78:81]
	v_mfma_f32_16x16x32_bf16 v[74:77], v[202:205], v[226:229], v[74:77]
	v_mfma_f32_16x16x32_bf16 v[70:73], v[194:197], v[234:237], v[70:73]
	v_mfma_f32_16x16x32_bf16 v[66:69], v[202:205], v[234:237], v[66:69]
	s_barrier
	ds_read_b128 v[206:209], v183 offset:16384
	ds_read_b128 v[210:213], v183 offset:17408
	ds_read_b128 v[214:217], v183 offset:18432
	ds_read_b128 v[218:221], v183 offset:19456
	ds_read_b128 v[222:225], v183 offset:20480
	ds_read_b128 v[226:229], v183 offset:21504
	ds_read_b128 v[230:233], v183 offset:22528
	ds_read_b128 v[234:237], v183 offset:23552
	global_load_lds_dwordx4 v148, s[48:49]
	s_add_i32 m0, s71, 0x2000
	s_add_u32 s74, s48, 0x40000
	s_addc_u32 s75, s49, 0
	s_add_i32 s71, s65, s9
	global_load_lds_dwordx4 v150, s[48:49]
	s_mov_b32 m0, s71
	s_nop 0
	global_load_lds_dwordx4 v148, s[74:75]
	s_add_i32 m0, s71, 0x2000
	s_nop 0
	global_load_lds_dwordx4 v150, s[74:75]
	s_mov_b32 m0, s55
	s_mov_b64 s[72:73], 0x2000
	global_load_lds_dwordx4 v146, s[84:85]
	s_mov_b32 m0, s56
	s_nop 0
	global_load_lds_dwordx4 v244, s[84:85]
	s_waitcnt vmcnt(8)
	s_waitcnt lgkmcnt(0)
	s_barrier
	s_waitcnt lgkmcnt(0)
	v_mfma_f32_16x16x32_bf16 v[62:65], v[132:135], v[206:209], v[62:65]
	v_mfma_f32_16x16x32_bf16 v[58:61], v[140:143], v[206:209], v[58:61]
	v_mfma_f32_16x16x32_bf16 v[54:57], v[132:135], v[214:217], v[54:57]
	v_mfma_f32_16x16x32_bf16 v[50:53], v[140:143], v[214:217], v[50:53]
	v_mfma_f32_16x16x32_bf16 v[46:49], v[132:135], v[222:225], v[46:49]
	v_mfma_f32_16x16x32_bf16 v[42:45], v[140:143], v[222:225], v[42:45]
	v_mfma_f32_16x16x32_bf16 v[38:41], v[132:135], v[230:233], v[38:41]
	v_mfma_f32_16x16x32_bf16 v[34:37], v[140:143], v[230:233], v[34:37]
	v_mfma_f32_16x16x32_bf16 v[62:65], v[136:139], v[210:213], v[62:65]
	v_mfma_f32_16x16x32_bf16 v[58:61], v[186:189], v[210:213], v[58:61]
	v_mfma_f32_16x16x32_bf16 v[54:57], v[136:139], v[218:221], v[54:57]
	v_mfma_f32_16x16x32_bf16 v[50:53], v[186:189], v[218:221], v[50:53]
	v_mfma_f32_16x16x32_bf16 v[46:49], v[136:139], v[226:229], v[46:49]
	v_mfma_f32_16x16x32_bf16 v[42:45], v[186:189], v[226:229], v[42:45]
	v_mfma_f32_16x16x32_bf16 v[38:41], v[136:139], v[234:237], v[38:41]
	v_mfma_f32_16x16x32_bf16 v[34:37], v[186:189], v[234:237], v[34:37]
	v_mfma_f32_16x16x32_bf16 v[30:33], v[190:193], v[206:209], v[30:33]
	s_add_i32 s71, 0, 0x18000
	v_mfma_f32_16x16x32_bf16 v[26:29], v[198:201], v[206:209], v[26:29]
	s_add_i32 s74, 0, 0x1c000
	v_mfma_f32_16x16x32_bf16 v[22:25], v[190:193], v[214:217], v[22:25]
	v_mfma_f32_16x16x32_bf16 v[18:21], v[198:201], v[214:217], v[18:21]
	v_mfma_f32_16x16x32_bf16 v[14:17], v[190:193], v[222:225], v[14:17]
	v_mfma_f32_16x16x32_bf16 v[10:13], v[198:201], v[222:225], v[10:13]
	v_mfma_f32_16x16x32_bf16 v[6:9], v[190:193], v[230:233], v[6:9]
	v_mfma_f32_16x16x32_bf16 v[2:5], v[198:201], v[230:233], v[2:5]
	v_mfma_f32_16x16x32_bf16 v[30:33], v[194:197], v[210:213], v[30:33]
	v_mfma_f32_16x16x32_bf16 v[26:29], v[202:205], v[210:213], v[26:29]
	v_mfma_f32_16x16x32_bf16 v[22:25], v[194:197], v[218:221], v[22:25]
	v_mfma_f32_16x16x32_bf16 v[18:21], v[202:205], v[218:221], v[18:21]
	v_mfma_f32_16x16x32_bf16 v[14:17], v[194:197], v[226:229], v[14:17]
	v_mfma_f32_16x16x32_bf16 v[10:13], v[202:205], v[226:229], v[10:13]
	v_mfma_f32_16x16x32_bf16 v[6:9], v[194:197], v[234:237], v[6:9]
	v_mfma_f32_16x16x32_bf16 v[2:5], v[202:205], v[234:237], v[2:5]
	s_barrier
; #define PG8_STAGE(bufoff, gbase, voff) do { _Pragma("unroll") for (int _i = 0; _i < 2; ++_i) \
;         __builtin_amdgcn_global_load_lds((const unsigned*)((const char*)(gbase) + (voff)[_i]), (PG8_LAS unsigned*)(lds + (bufoff) + ldsw + _i * 8192), 16, 0, 0); } while (0)
; #define PG8_LDA(dst, b, h) do { _Pragma("unroll") for (int m = 0; m < 4; ++m) _Pragma("unroll") for (int k = 0; k < 2; ++k) dst[m][k] = *(const PG8_LAS bf16x8*)(lds + PG8_SA(b, h) + aoff + m * 2048 + k * 1024); } while (0)
; #define PG8_LDB(dst, b, h) do { _Pragma("unroll") for (int n = 0; n < 2; ++n) _Pragma("unroll") for (int k = 0; k < 2; ++k) dst[n][k] = *(const PG8_LAS bf16x8*)(lds + PG8_SB(b, h) + boff + n * 2048 + k * 1024); } while (0)
; #define PG8_MMA(ai, bj, At, Bt) do { __builtin_amdgcn_s_setprio(1); _Pragma("unroll") for (int m = 0; m < 4; ++m) _Pragma("unroll") for (int n = 0; n < 2; ++n) _Pragma("unroll") for (int k = 0; k < 2; ++k) \
;         acc[ai][bj][m][n] = __builtin_amdgcn_mfma_f32_16x16x32_bf16(Bt[n][k], At[m][k], acc[ai][bj][m][n], 0, 0, 0); __builtin_amdgcn_s_setprio(0); } while (0)
; #define PG8_WAIT_V(n) asm volatile("s_waitcnt vmcnt(" #n ")" ::: "memory")
; #define PG8_WAIT_L(n) asm volatile("s_waitcnt lgkmcnt(" #n ")" ::: "memory")
; #define PG8_BAR __builtin_amdgcn_s_barrier()
; #define PG8_SCHED __builtin_amdgcn_sched_barrier(0)
; template <class Epi, bool ALIGN_EPI, bool ABLK = false>
; __device__ __forceinline__ void gemm_phase(PG8_LAS unsigned char* lds, const Gemm g, const StaticOrder& S, const Epi& E) {
;     ...
;             PG8_LDB(B0, 1, 0); PG8_LDB(B1, 1, 1); PG8_SCHED; PG8_LDA(At, 1, 0); PG8_STAGE(PG8_SA(0, 1), a2 + hstepA, voffA);
;             PG8_WAIT_V(8); PG8_WAIT_L(0); PG8_BAR; PG8_MMA(0, 0, At, B0); PG8_MMA(0, 1, At, B1); PG8_BAR; PG8_SCHED;
;             PG8_LDA(At, 1, 1); PG8_STAGE(PG8_SB(1, 0), b3, voffB); PG8_STAGE(PG8_SB(1, 1), b3 + hstepB, voffB); PG8_STAGE(PG8_SA(1, 0), a3, voffA);
;             PG8_WAIT_V(8); PG8_WAIT_L(0); PG8_BAR; PG8_MMA(1, 0, At, B0); PG8_MMA(1, 1, At, B1); PG8_BAR; PG8_SCHED;
;         }
;         if constexpr (ALIGN_EPI) { if (wr == 0) PG8_BAR; }
	ds_read_b128 v[132:135], v251 offset:32768
	ds_read_b128 v[136:139], v251 offset:33792
	ds_read_b128 v[140:143], v251 offset:34816
	ds_read_b128 v[186:189], v251 offset:35840
	ds_read_b128 v[190:193], v251 offset:49152
	ds_read_b128 v[194:197], v251 offset:50176
	ds_read_b128 v[198:201], v251 offset:51200
	ds_read_b128 v[202:205], v251 offset:52224
	s_mov_b64 s[72:73], 0x4000
	s_mov_b32 m0, s57
	s_mov_b64 s[72:73], 0x6000
	ds_read_b128 v[206:209], v183 offset:32768
	ds_read_b128 v[210:213], v183 offset:33792
	ds_read_b128 v[214:217], v183 offset:34816
	ds_read_b128 v[218:221], v183 offset:35840
	ds_read_b128 v[222:225], v183 offset:36864
	ds_read_b128 v[226:229], v183 offset:37888
	ds_read_b128 v[230:233], v183 offset:38912
	ds_read_b128 v[234:237], v183 offset:39936
	global_load_lds_dwordx4 v245, s[84:85]
	s_mov_b32 m0, s58
	s_nop 0
	global_load_lds_dwordx4 v246, s[84:85]
	s_waitcnt vmcnt(8)
	s_waitcnt lgkmcnt(0)
	s_barrier
	s_waitcnt lgkmcnt(0)
	v_mfma_f32_16x16x32_bf16 v[126:129], v[132:135], v[206:209], v[126:129]
	v_mfma_f32_16x16x32_bf16 v[122:125], v[140:143], v[206:209], v[122:125]
	v_mfma_f32_16x16x32_bf16 v[118:121], v[132:135], v[214:217], v[118:121]
	v_mfma_f32_16x16x32_bf16 v[114:117], v[140:143], v[214:217], v[114:117]
	v_mfma_f32_16x16x32_bf16 v[110:113], v[132:135], v[222:225], v[110:113]
	v_mfma_f32_16x16x32_bf16 v[106:109], v[140:143], v[222:225], v[106:109]
	v_mfma_f32_16x16x32_bf16 v[102:105], v[132:135], v[230:233], v[102:105]
	v_mfma_f32_16x16x32_bf16 v[98:101], v[140:143], v[230:233], v[98:101]
	v_mfma_f32_16x16x32_bf16 v[126:129], v[136:139], v[210:213], v[126:129]
	v_mfma_f32_16x16x32_bf16 v[122:125], v[186:189], v[210:213], v[122:125]
	v_mfma_f32_16x16x32_bf16 v[118:121], v[136:139], v[218:221], v[118:121]
	v_mfma_f32_16x16x32_bf16 v[114:117], v[186:189], v[218:221], v[114:117]
	v_mfma_f32_16x16x32_bf16 v[110:113], v[136:139], v[226:229], v[110:113]
	v_mfma_f32_16x16x32_bf16 v[106:109], v[186:189], v[226:229], v[106:109]
	v_mfma_f32_16x16x32_bf16 v[102:105], v[136:139], v[234:237], v[102:105]
	v_mfma_f32_16x16x32_bf16 v[98:101], v[186:189], v[234:237], v[98:101]
	v_mfma_f32_16x16x32_bf16 v[94:97], v[190:193], v[206:209], v[94:97]
	s_add_i32 s71, s71, s9
	v_mfma_f32_16x16x32_bf16 v[90:93], v[198:201], v[206:209], v[90:93]
	s_add_u32 s86, s48, s28
	v_mfma_f32_16x16x32_bf16 v[86:89], v[190:193], v[214:217], v[86:89]
	s_addc_u32 s87, s49, s29
	v_mfma_f32_16x16x32_bf16 v[82:85], v[198:201], v[214:217], v[82:85]
	s_mov_b32 m0, s71
	v_mfma_f32_16x16x32_bf16 v[78:81], v[190:193], v[222:225], v[78:81]
	v_mfma_f32_16x16x32_bf16 v[74:77], v[198:201], v[222:225], v[74:77]
	v_mfma_f32_16x16x32_bf16 v[70:73], v[190:193], v[230:233], v[70:73]
	v_mfma_f32_16x16x32_bf16 v[66:69], v[198:201], v[230:233], v[66:69]
	v_mfma_f32_16x16x32_bf16 v[94:97], v[194:197], v[210:213], v[94:97]
	v_mfma_f32_16x16x32_bf16 v[90:93], v[202:205], v[210:213], v[90:93]
	v_mfma_f32_16x16x32_bf16 v[86:89], v[194:197], v[218:221], v[86:89]
	v_mfma_f32_16x16x32_bf16 v[82:85], v[202:205], v[218:221], v[82:85]
	v_mfma_f32_16x16x32_bf16 v[78:81], v[194:197], v[226:229], v[78:81]
	v_mfma_f32_16x16x32_bf16 v[74:77], v[202:205], v[226:229], v[74:77]
	v_mfma_f32_16x16x32_bf16 v[70:73], v[194:197], v[234:237], v[70:73]
	v_mfma_f32_16x16x32_bf16 v[66:69], v[202:205], v[234:237], v[66:69]
	s_barrier
	ds_read_b128 v[206:209], v183 offset:49152
	ds_read_b128 v[210:213], v183 offset:50176
	ds_read_b128 v[214:217], v183 offset:51200
	ds_read_b128 v[218:221], v183 offset:52224
	ds_read_b128 v[222:225], v183 offset:53248
	ds_read_b128 v[226:229], v183 offset:54272
	ds_read_b128 v[230:233], v183 offset:55296
	ds_read_b128 v[234:237], v183 offset:56320
	global_load_lds_dwordx4 v148, s[86:87]
	s_add_i32 m0, s71, 0x2000
	s_add_u32 s48, s48, 0x40080
	s_addc_u32 s49, s49, 0
	s_add_i32 s71, s74, s9
	global_load_lds_dwordx4 v150, s[86:87]
	s_mov_b32 m0, s71
	s_nop 0
	global_load_lds_dwordx4 v148, s[48:49]
	s_add_i32 m0, s71, 0x2000
	s_nop 0
	global_load_lds_dwordx4 v150, s[48:49]
	s_mov_b32 m0, s59
	s_nop 0
	global_load_lds_dwordx4 v247, s[84:85]
	s_mov_b32 m0, s61
	s_nop 0
	global_load_lds_dwordx4 v248, s[84:85]
	s_waitcnt vmcnt(8)
	s_waitcnt lgkmcnt(0)
	s_barrier
	s_waitcnt lgkmcnt(0)
	v_mfma_f32_16x16x32_bf16 v[62:65], v[132:135], v[206:209], v[62:65]
	v_mfma_f32_16x16x32_bf16 v[58:61], v[140:143], v[206:209], v[58:61]
	v_mfma_f32_16x16x32_bf16 v[54:57], v[132:135], v[214:217], v[54:57]
	v_mfma_f32_16x16x32_bf16 v[50:53], v[140:143], v[214:217], v[50:53]
	v_mfma_f32_16x16x32_bf16 v[46:49], v[132:135], v[222:225], v[46:49]
	v_mfma_f32_16x16x32_bf16 v[42:45], v[140:143], v[222:225], v[42:45]
	v_mfma_f32_16x16x32_bf16 v[38:41], v[132:135], v[230:233], v[38:41]
	v_mfma_f32_16x16x32_bf16 v[34:37], v[140:143], v[230:233], v[34:37]
	v_mfma_f32_16x16x32_bf16 v[62:65], v[136:139], v[210:213], v[62:65]
	v_mfma_f32_16x16x32_bf16 v[58:61], v[186:189], v[210:213], v[58:61]
	v_mfma_f32_16x16x32_bf16 v[54:57], v[136:139], v[218:221], v[54:57]
	v_mfma_f32_16x16x32_bf16 v[50:53], v[186:189], v[218:221], v[50:53]
	v_mfma_f32_16x16x32_bf16 v[46:49], v[136:139], v[226:229], v[46:49]
	v_mfma_f32_16x16x32_bf16 v[42:45], v[186:189], v[226:229], v[42:45]
	v_mfma_f32_16x16x32_bf16 v[38:41], v[136:139], v[234:237], v[38:41]
	v_mfma_f32_16x16x32_bf16 v[34:37], v[186:189], v[234:237], v[34:37]
	v_mfma_f32_16x16x32_bf16 v[30:33], v[190:193], v[206:209], v[30:33]
	s_add_i32 s70, s70, 2
	v_mfma_f32_16x16x32_bf16 v[26:29], v[198:201], v[206:209], v[26:29]
	s_add_u32 s68, s68, 0x100
	v_mfma_f32_16x16x32_bf16 v[22:25], v[190:193], v[214:217], v[22:25]
	s_addc_u32 s69, s69, 0
	v_mfma_f32_16x16x32_bf16 v[18:21], v[198:201], v[214:217], v[18:21]
	s_add_u32 s46, s46, 0x10000
	v_mfma_f32_16x16x32_bf16 v[14:17], v[190:193], v[222:225], v[14:17]
	s_addc_u32 s47, s47, 0
	v_mfma_f32_16x16x32_bf16 v[10:13], v[198:201], v[222:225], v[10:13]
	s_add_u32 s82, s82, 0x10000
	v_mfma_f32_16x16x32_bf16 v[6:9], v[190:193], v[230:233], v[6:9]
	s_addc_u32 s83, s83, 0
	v_mfma_f32_16x16x32_bf16 v[2:5], v[198:201], v[230:233], v[2:5]
	s_mov_b64 s[48:49], 0x10000
	v_mfma_f32_16x16x32_bf16 v[30:33], v[194:197], v[210:213], v[30:33]
	s_cmp_gt_u32 s70, 13
	v_mfma_f32_16x16x32_bf16 v[26:29], v[202:205], v[210:213], v[26:29]
	v_mfma_f32_16x16x32_bf16 v[22:25], v[194:197], v[218:221], v[22:25]
	v_mfma_f32_16x16x32_bf16 v[18:21], v[202:205], v[218:221], v[18:21]
	v_mfma_f32_16x16x32_bf16 v[14:17], v[194:197], v[226:229], v[14:17]
	v_mfma_f32_16x16x32_bf16 v[10:13], v[202:205], v[226:229], v[10:13]
	v_mfma_f32_16x16x32_bf16 v[6:9], v[194:197], v[234:237], v[6:9]
	v_mfma_f32_16x16x32_bf16 v[2:5], v[202:205], v[234:237], v[2:5]
	s_barrier
	s_cbranch_scc0 .LBB0_402
	s_and_b64 vcc, exec, s[36:37]
	s_cbranch_vccz .LBB0_405
	s_barrier

; #define PG8_STAGE(bufoff, gbase, voff) do { _Pragma("unroll") for (int _i = 0; _i < 2; ++_i) \
;         __builtin_amdgcn_global_load_lds((const unsigned*)((const char*)(gbase) + (voff)[_i]), (PG8_LAS unsigned*)(lds + (bufoff) + ldsw + _i * 8192), 16, 0, 0); } while (0)
; #define PG8_LDA(dst, b, h) do { _Pragma("unroll") for (int m = 0; m < 4; ++m) _Pragma("unroll") for (int k = 0; k < 2; ++k) dst[m][k] = *(const PG8_LAS bf16x8*)(lds + PG8_SA(b, h) + aoff + m * 2048 + k * 1024); } while (0)
; #define PG8_LDB(dst, b, h) do { _Pragma("unroll") for (int n = 0; n < 2; ++n) _Pragma("unroll") for (int k = 0; k < 2; ++k) dst[n][k] = *(const PG8_LAS bf16x8*)(lds + PG8_SB(b, h) + boff + n * 2048 + k * 1024); } while (0)
; #define PG8_MMA(ai, bj, At, Bt) do { __builtin_amdgcn_s_setprio(1); _Pragma("unroll") for (int m = 0; m < 4; ++m) _Pragma("unroll") for (int n = 0; n < 2; ++n) _Pragma("unroll") for (int k = 0; k < 2; ++k) \
;         acc[ai][bj][m][n] = __builtin_amdgcn_mfma_f32_16x16x32_bf16(Bt[n][k], At[m][k], acc[ai][bj][m][n], 0, 0, 0); __builtin_amdgcn_s_setprio(0); } while (0)
; template <class Epi, bool ALIGN_EPI, bool ABLK = false>
; __device__ __forceinline__ void gemm_phase(PG8_LAS unsigned char* lds, const Gemm g, const StaticOrder& S, const Epi& E) {
;     ...
;         for (int t = 0; t < nt; t += 2) {
;             const bool last = (t == nt - 2);
;             const char* a1 = cA + (size_t)(t + 1) * kstepA;
;             const char* a2 = last ? nA : cA + (size_t)(t + 2) * kstepA; const char* b2 = last ? nB : cB + (size_t)(t + 2) * kstepB;
;             const char* a3 = a2 + kstepA; const char* b3 = b2 + kstepB;
;             PG8_LDB(B0, 0, 0); PG8_LDB(B1, 0, 1); PG8_SCHED; PG8_LDA(At, 0, 0); PG8_STAGE(PG8_SA(1, 1), a1 + hstepA, voffA);
;             PG8_WAIT_V(8); PG8_WAIT_L(0); PG8_BAR; PG8_MMA(0, 0, At, B0); PG8_MMA(0, 1, At, B1); PG8_BAR; PG8_SCHED;
;             PG8_LDA(At, 0, 1); PG8_STAGE(PG8_SB(0, 0), b2, voffB); PG8_STAGE(PG8_SB(0, 1), b2 + hstepB, voffB); PG8_STAGE(PG8_SA(0, 0), a2, voffA);
;             PG8_WAIT_V(8); PG8_WAIT_L(0); PG8_BAR; PG8_MMA(1, 0, At, B0); PG8_MMA(1, 1, At, B1); PG8_BAR; PG8_SCHED;
;             PG8_LDB(B0, 1, 0); PG8_LDB(B1, 1, 1); PG8_SCHED; PG8_LDA(At, 1, 0); PG8_STAGE(PG8_SA(0, 1), a2 + hstepA, voffA);
;             PG8_WAIT_V(8); PG8_WAIT_L(0); PG8_BAR; PG8_MMA(0, 0, At, B0); PG8_MMA(0, 1, At, B1); PG8_BAR; PG8_SCHED;
.LBB0_540:
	ds_read_b128 v[98:101], v238
	ds_read_b128 v[110:113], v238 offset:1024
	ds_read_b128 v[122:125], v238 offset:2048
	ds_read_b128 v[126:129], v238 offset:3072
	ds_read_b128 v[134:137], v239
	ds_read_b128 v[142:145], v239 offset:1024
	ds_read_b128 v[146:149], v239 offset:2048
	ds_read_b128 v[150:153], v239 offset:3072
	s_cmp_eq_u32 s78, 40
	s_cselect_b32 s81, s9, s51
	s_cselect_b32 s80, s8, s50
	s_cselect_b32 s53, s49, s55
	s_cselect_b32 s52, s48, s54
	s_movk_i32 s82, 0xc000
	v_lshl_add_u64 v[242:243], s[50:51], 0, v[194:195]
	s_mov_b32 s83, -1
	v_lshl_add_u64 v[244:245], v[242:243], 0, s[82:83]
	s_movk_i32 s82, 0xe000
	s_add_i32 m0, s61, 0xc000
	s_mov_b32 s83, -1
	ds_read_b128 v[154:157], v240
	ds_read_b128 v[166:169], v240 offset:1024
	ds_read_b128 v[170:173], v240 offset:2048
	ds_read_b128 v[174:177], v240 offset:3072
	ds_read_b128 v[178:181], v240 offset:4096
	ds_read_b128 v[182:185], v240 offset:5120
	ds_read_b128 v[186:189], v240 offset:6144
	ds_read_b128 v[190:193], v240 offset:7168
	global_load_lds_dwordx4 v[244:245], off
	v_lshl_add_u64 v[242:243], v[242:243], 0, s[82:83]
	s_add_i32 m0, s61, 0xe000
	s_nop 0
	global_load_lds_dwordx4 v[242:243], off
	s_waitcnt vmcnt(8)
	s_waitcnt lgkmcnt(0)
	s_barrier
	s_waitcnt lgkmcnt(0)
	v_mfma_f32_16x16x32_bf16 v[162:165], v[98:101], v[154:157], v[162:165]
	v_mfma_f32_16x16x32_bf16 v[158:161], v[122:125], v[154:157], v[158:161]
	v_mfma_f32_16x16x32_bf16 v[118:121], v[98:101], v[170:173], v[118:121]
	v_mfma_f32_16x16x32_bf16 v[114:117], v[122:125], v[170:173], v[114:117]
	v_mfma_f32_16x16x32_bf16 v[94:97], v[98:101], v[178:181], v[94:97]
	v_mfma_f32_16x16x32_bf16 v[90:93], v[122:125], v[178:181], v[90:93]
	v_mfma_f32_16x16x32_bf16 v[78:81], v[98:101], v[186:189], v[78:81]
	v_mfma_f32_16x16x32_bf16 v[74:77], v[122:125], v[186:189], v[74:77]
	v_mfma_f32_16x16x32_bf16 v[162:165], v[110:113], v[166:169], v[162:165]
	v_mfma_f32_16x16x32_bf16 v[158:161], v[126:129], v[166:169], v[158:161]
	v_mfma_f32_16x16x32_bf16 v[118:121], v[110:113], v[174:177], v[118:121]
	v_mfma_f32_16x16x32_bf16 v[114:117], v[126:129], v[174:177], v[114:117]
	v_mfma_f32_16x16x32_bf16 v[94:97], v[110:113], v[182:185], v[94:97]
	v_mfma_f32_16x16x32_bf16 v[90:93], v[126:129], v[182:185], v[90:93]
	v_mfma_f32_16x16x32_bf16 v[78:81], v[110:113], v[190:193], v[78:81]
	v_mfma_f32_16x16x32_bf16 v[74:77], v[126:129], v[190:193], v[74:77]
	v_mfma_f32_16x16x32_bf16 v[138:141], v[134:137], v[154:157], v[138:141]
	s_add_i32 s79, s73, s59
	v_mfma_f32_16x16x32_bf16 v[130:133], v[146:149], v[154:157], v[130:133]
	s_mov_b32 m0, s79
	v_mfma_f32_16x16x32_bf16 v[106:109], v[134:137], v[170:173], v[106:109]
	v_mfma_f32_16x16x32_bf16 v[102:105], v[146:149], v[170:173], v[102:105]
	v_mfma_f32_16x16x32_bf16 v[86:89], v[134:137], v[178:181], v[86:89]
	v_mfma_f32_16x16x32_bf16 v[82:85], v[146:149], v[178:181], v[82:85]
	v_mfma_f32_16x16x32_bf16 v[70:73], v[134:137], v[186:189], v[70:73]
	v_mfma_f32_16x16x32_bf16 v[66:69], v[146:149], v[186:189], v[66:69]
	v_mfma_f32_16x16x32_bf16 v[138:141], v[142:145], v[166:169], v[138:141]
	v_mfma_f32_16x16x32_bf16 v[130:133], v[150:153], v[166:169], v[130:133]
	v_mfma_f32_16x16x32_bf16 v[106:109], v[142:145], v[174:177], v[106:109]
	v_mfma_f32_16x16x32_bf16 v[102:105], v[150:153], v[174:177], v[102:105]
	v_mfma_f32_16x16x32_bf16 v[86:89], v[142:145], v[182:185], v[86:89]
	v_mfma_f32_16x16x32_bf16 v[82:85], v[150:153], v[182:185], v[82:85]
	v_mfma_f32_16x16x32_bf16 v[70:73], v[142:145], v[190:193], v[70:73]
	v_mfma_f32_16x16x32_bf16 v[66:69], v[150:153], v[190:193], v[66:69]
	s_barrier
	v_lshl_add_u64 v[242:243], s[52:53], 0, v[196:197]
	ds_read_b128 v[154:157], v240 offset:16384
	ds_read_b128 v[166:169], v240 offset:17408
	ds_read_b128 v[170:173], v240 offset:18432
	ds_read_b128 v[174:177], v240 offset:19456
	ds_read_b128 v[178:181], v240 offset:20480
	ds_read_b128 v[182:185], v240 offset:21504
	ds_read_b128 v[186:189], v240 offset:22528
	ds_read_b128 v[190:193], v240 offset:23552
	global_load_lds_dwordx4 v[242:243], off
	s_add_i32 m0, s79, 0x2000
	s_add_u32 s82, s52, 0xb0000
	v_lshl_add_u64 v[244:245], s[52:53], 0, v[198:199]
	s_addc_u32 s83, s53, 0
	s_add_i32 s79, s74, s59
	global_load_lds_dwordx4 v[244:245], off
	v_lshl_add_u64 v[246:247], s[82:83], 0, v[196:197]
	s_mov_b32 m0, s79
	s_nop 0
	global_load_lds_dwordx4 v[246:247], off
	v_lshl_add_u64 v[246:247], s[82:83], 0, v[198:199]
	s_add_i32 m0, s79, 0x2000
	s_nop 0
	global_load_lds_dwordx4 v[246:247], off
	v_lshl_add_u64 v[246:247], s[80:81], 0, v[194:195]
	s_mov_b32 m0, s61
	v_lshl_add_u64 v[248:249], v[246:247], 0, s[10:11]
	global_load_lds_dwordx4 v[246:247], off
	s_mov_b32 m0, s62
	s_nop 0
	global_load_lds_dwordx4 v[248:249], off
	s_waitcnt vmcnt(8)
	s_waitcnt lgkmcnt(0)
	s_barrier
; #define PG8_STAGE(bufoff, gbase, voff) do { _Pragma("unroll") for (int _i = 0; _i < 2; ++_i) \
;         __builtin_amdgcn_global_load_lds((const unsigned*)((const char*)(gbase) + (voff)[_i]), (PG8_LAS unsigned*)(lds + (bufoff) + ldsw + _i * 8192), 16, 0, 0); } while (0)
; #define PG8_LDA(dst, b, h) do { _Pragma("unroll") for (int m = 0; m < 4; ++m) _Pragma("unroll") for (int k = 0; k < 2; ++k) dst[m][k] = *(const PG8_LAS bf16x8*)(lds + PG8_SA(b, h) + aoff + m * 2048 + k * 1024); } while (0)
; #define PG8_LDB(dst, b, h) do { _Pragma("unroll") for (int n = 0; n < 2; ++n) _Pragma("unroll") for (int k = 0; k < 2; ++k) dst[n][k] = *(const PG8_LAS bf16x8*)(lds + PG8_SB(b, h) + boff + n * 2048 + k * 1024); } while (0)
; #define PG8_MMA(ai, bj, At, Bt) do { __builtin_amdgcn_s_setprio(1); _Pragma("unroll") for (int m = 0; m < 4; ++m) _Pragma("unroll") for (int n = 0; n < 2; ++n) _Pragma("unroll") for (int k = 0; k < 2; ++k) \
;         acc[ai][bj][m][n] = __builtin_amdgcn_mfma_f32_16x16x32_bf16(Bt[n][k], At[m][k], acc[ai][bj][m][n], 0, 0, 0); __builtin_amdgcn_s_setprio(0); } while (0)
; #define PG8_WAIT_V(n) asm volatile("s_waitcnt vmcnt(" #n ")" ::: "memory")
; #define PG8_WAIT_L(n) asm volatile("s_waitcnt lgkmcnt(" #n ")" ::: "memory")
; #define PG8_BAR __builtin_amdgcn_s_barrier()
; #define PG8_SCHED __builtin_amdgcn_sched_barrier(0)
; template <class Epi, bool ALIGN_EPI, bool ABLK = false>
; __device__ __forceinline__ void gemm_phase(PG8_LAS unsigned char* lds, const Gemm g, const StaticOrder& S, const Epi& E) {
;     ...
;             PG8_WAIT_V(8); PG8_WAIT_L(0); PG8_BAR; PG8_MMA(1, 0, At, B0); PG8_MMA(1, 1, At, B1); PG8_BAR; PG8_SCHED;
;             PG8_LDB(B0, 1, 0); PG8_LDB(B1, 1, 1); PG8_SCHED; PG8_LDA(At, 1, 0); PG8_STAGE(PG8_SA(0, 1), a2 + hstepA, voffA);
;             PG8_WAIT_V(8); PG8_WAIT_L(0); PG8_BAR; PG8_MMA(0, 0, At, B0); PG8_MMA(0, 1, At, B1); PG8_BAR; PG8_SCHED;
;             PG8_LDA(At, 1, 1); PG8_STAGE(PG8_SB(1, 0), b3, voffB); PG8_STAGE(PG8_SB(1, 1), b3 + hstepB, voffB); PG8_STAGE(PG8_SA(1, 0), a3, voffA);
	s_waitcnt lgkmcnt(0)
	v_mfma_f32_16x16x32_bf16 v[62:65], v[98:101], v[154:157], v[62:65]
	v_mfma_f32_16x16x32_bf16 v[58:61], v[122:125], v[154:157], v[58:61]
	v_mfma_f32_16x16x32_bf16 v[46:49], v[98:101], v[170:173], v[46:49]
	v_mfma_f32_16x16x32_bf16 v[42:45], v[122:125], v[170:173], v[42:45]
	v_mfma_f32_16x16x32_bf16 v[30:33], v[98:101], v[178:181], v[30:33]
	v_mfma_f32_16x16x32_bf16 v[26:29], v[122:125], v[178:181], v[26:29]
	v_mfma_f32_16x16x32_bf16 v[14:17], v[98:101], v[186:189], v[14:17]
	v_mfma_f32_16x16x32_bf16 v[10:13], v[122:125], v[186:189], v[10:13]
	v_mfma_f32_16x16x32_bf16 v[62:65], v[110:113], v[166:169], v[62:65]
	v_mfma_f32_16x16x32_bf16 v[58:61], v[126:129], v[166:169], v[58:61]
	v_mfma_f32_16x16x32_bf16 v[46:49], v[110:113], v[174:177], v[46:49]
	v_mfma_f32_16x16x32_bf16 v[42:45], v[126:129], v[174:177], v[42:45]
	v_mfma_f32_16x16x32_bf16 v[30:33], v[110:113], v[182:185], v[30:33]
	v_mfma_f32_16x16x32_bf16 v[26:29], v[126:129], v[182:185], v[26:29]
	v_mfma_f32_16x16x32_bf16 v[14:17], v[110:113], v[190:193], v[14:17]
	v_mfma_f32_16x16x32_bf16 v[10:13], v[126:129], v[190:193], v[10:13]
	v_mfma_f32_16x16x32_bf16 v[54:57], v[134:137], v[154:157], v[54:57]
	s_add_i32 s79, 0, 0x18000
	v_mfma_f32_16x16x32_bf16 v[50:53], v[146:149], v[154:157], v[50:53]
	s_add_i32 s80, 0, 0x1c000
	v_mfma_f32_16x16x32_bf16 v[38:41], v[134:137], v[170:173], v[38:41]
	v_mfma_f32_16x16x32_bf16 v[34:37], v[146:149], v[170:173], v[34:37]
	v_mfma_f32_16x16x32_bf16 v[22:25], v[134:137], v[178:181], v[22:25]
	v_mfma_f32_16x16x32_bf16 v[18:21], v[146:149], v[178:181], v[18:21]
	v_mfma_f32_16x16x32_bf16 v[6:9], v[134:137], v[186:189], v[6:9]
	v_mfma_f32_16x16x32_bf16 v[2:5], v[146:149], v[186:189], v[2:5]
	v_mfma_f32_16x16x32_bf16 v[54:57], v[142:145], v[166:169], v[54:57]
	v_mfma_f32_16x16x32_bf16 v[50:53], v[150:153], v[166:169], v[50:53]
	v_mfma_f32_16x16x32_bf16 v[38:41], v[142:145], v[174:177], v[38:41]
	v_mfma_f32_16x16x32_bf16 v[34:37], v[150:153], v[174:177], v[34:37]
	v_mfma_f32_16x16x32_bf16 v[22:25], v[142:145], v[182:185], v[22:25]
	v_mfma_f32_16x16x32_bf16 v[18:21], v[150:153], v[182:185], v[18:21]
	v_mfma_f32_16x16x32_bf16 v[6:9], v[142:145], v[190:193], v[6:9]
	v_mfma_f32_16x16x32_bf16 v[2:5], v[150:153], v[190:193], v[2:5]
	s_barrier
	v_add_u32_e32 v126, s79, v230
	v_add_u32_e32 v150, s80, v230
	ds_read_b128 v[98:101], v126
	ds_read_b128 v[110:113], v126 offset:1024
	ds_read_b128 v[122:125], v126 offset:2048
	ds_read_b128 v[126:129], v126 offset:3072
	ds_read_b128 v[134:137], v150
	ds_read_b128 v[142:145], v150 offset:1024
	ds_read_b128 v[146:149], v150 offset:2048
	ds_read_b128 v[150:153], v150 offset:3072
	s_mov_b32 m0, s63
	v_lshl_add_u64 v[248:249], v[246:247], 0, s[12:13]
	ds_read_b128 v[154:157], v240 offset:32768
	ds_read_b128 v[166:169], v240 offset:33792
	ds_read_b128 v[170:173], v240 offset:34816
	ds_read_b128 v[174:177], v240 offset:35840
	ds_read_b128 v[178:181], v240 offset:36864
	ds_read_b128 v[182:185], v240 offset:37888
	ds_read_b128 v[186:189], v240 offset:38912
	ds_read_b128 v[190:193], v240 offset:39936
	global_load_lds_dwordx4 v[248:249], off
	v_lshl_add_u64 v[248:249], v[246:247], 0, s[24:25]
	s_mov_b32 m0, s64
	s_nop 0
	global_load_lds_dwordx4 v[248:249], off
	s_waitcnt vmcnt(8)
	s_waitcnt lgkmcnt(0)
	s_barrier
	s_waitcnt lgkmcnt(0)
	v_mfma_f32_16x16x32_bf16 v[162:165], v[98:101], v[154:157], v[162:165]
	v_mfma_f32_16x16x32_bf16 v[158:161], v[122:125], v[154:157], v[158:161]
	v_mfma_f32_16x16x32_bf16 v[118:121], v[98:101], v[170:173], v[118:121]
	v_mfma_f32_16x16x32_bf16 v[114:117], v[122:125], v[170:173], v[114:117]
	v_mfma_f32_16x16x32_bf16 v[94:97], v[98:101], v[178:181], v[94:97]
	v_mfma_f32_16x16x32_bf16 v[90:93], v[122:125], v[178:181], v[90:93]
	v_mfma_f32_16x16x32_bf16 v[78:81], v[98:101], v[186:189], v[78:81]
	v_mfma_f32_16x16x32_bf16 v[74:77], v[122:125], v[186:189], v[74:77]
	v_mfma_f32_16x16x32_bf16 v[162:165], v[110:113], v[166:169], v[162:165]
	v_mfma_f32_16x16x32_bf16 v[158:161], v[126:129], v[166:169], v[158:161]
	v_mfma_f32_16x16x32_bf16 v[118:121], v[110:113], v[174:177], v[118:121]
	v_mfma_f32_16x16x32_bf16 v[114:117], v[126:129], v[174:177], v[114:117]
	v_mfma_f32_16x16x32_bf16 v[94:97], v[110:113], v[182:185], v[94:97]
	v_mfma_f32_16x16x32_bf16 v[90:93], v[126:129], v[182:185], v[90:93]
	v_mfma_f32_16x16x32_bf16 v[78:81], v[110:113], v[190:193], v[78:81]
	v_mfma_f32_16x16x32_bf16 v[74:77], v[126:129], v[190:193], v[74:77]
	v_mfma_f32_16x16x32_bf16 v[138:141], v[134:137], v[154:157], v[138:141]
	s_add_i32 s79, s79, s59
	v_mfma_f32_16x16x32_bf16 v[130:133], v[146:149], v[154:157], v[130:133]
	s_mov_b32 m0, s79
	v_mfma_f32_16x16x32_bf16 v[106:109], v[134:137], v[170:173], v[106:109]
	v_mfma_f32_16x16x32_bf16 v[102:105], v[146:149], v[170:173], v[102:105]
	v_mfma_f32_16x16x32_bf16 v[86:89], v[134:137], v[178:181], v[86:89]
	v_mfma_f32_16x16x32_bf16 v[82:85], v[146:149], v[178:181], v[82:85]
	v_mfma_f32_16x16x32_bf16 v[70:73], v[134:137], v[186:189], v[70:73]
	v_mfma_f32_16x16x32_bf16 v[66:69], v[146:149], v[186:189], v[66:69]
	v_mfma_f32_16x16x32_bf16 v[138:141], v[142:145], v[166:169], v[138:141]
	v_mfma_f32_16x16x32_bf16 v[130:133], v[150:153], v[166:169], v[130:133]
	v_mfma_f32_16x16x32_bf16 v[106:109], v[142:145], v[174:177], v[106:109]
	v_mfma_f32_16x16x32_bf16 v[102:105], v[150:153], v[174:177], v[102:105]
	v_mfma_f32_16x16x32_bf16 v[86:89], v[142:145], v[182:185], v[86:89]
	v_mfma_f32_16x16x32_bf16 v[82:85], v[150:153], v[182:185], v[82:85]
	v_mfma_f32_16x16x32_bf16 v[70:73], v[142:145], v[190:193], v[70:73]
	v_mfma_f32_16x16x32_bf16 v[66:69], v[150:153], v[190:193], v[66:69]
	s_barrier
; #define PG8_STAGE(bufoff, gbase, voff) do { _Pragma("unroll") for (int _i = 0; _i < 2; ++_i) \
;         __builtin_amdgcn_global_load_lds((const unsigned*)((const char*)(gbase) + (voff)[_i]), (PG8_LAS unsigned*)(lds + (bufoff) + ldsw + _i * 8192), 16, 0, 0); } while (0)
; #define PG8_LDA(dst, b, h) do { _Pragma("unroll") for (int m = 0; m < 4; ++m) _Pragma("unroll") for (int k = 0; k < 2; ++k) dst[m][k] = *(const PG8_LAS bf16x8*)(lds + PG8_SA(b, h) + aoff + m * 2048 + k * 1024); } while (0)
; #define PG8_MMA(ai, bj, At, Bt) do { __builtin_amdgcn_s_setprio(1); _Pragma("unroll") for (int m = 0; m < 4; ++m) _Pragma("unroll") for (int n = 0; n < 2; ++n) _Pragma("unroll") for (int k = 0; k < 2; ++k) \
;         acc[ai][bj][m][n] = __builtin_amdgcn_mfma_f32_16x16x32_bf16(Bt[n][k], At[m][k], acc[ai][bj][m][n], 0, 0, 0); __builtin_amdgcn_s_setprio(0); } while (0)
; #define PG8_WAIT_V(n) asm volatile("s_waitcnt vmcnt(" #n ")" ::: "memory")
; #define PG8_WAIT_L(n) asm volatile("s_waitcnt lgkmcnt(" #n ")" ::: "memory")
; #define PG8_BAR __builtin_amdgcn_s_barrier()
; #define PG8_SCHED __builtin_amdgcn_sched_barrier(0)
; template <class Epi, bool ALIGN_EPI, bool ABLK = false>
; __device__ __forceinline__ void gemm_phase(PG8_LAS unsigned char* lds, const Gemm g, const StaticOrder& S, const Epi& E) {
;     ...
;             PG8_LDA(At, 1, 1); PG8_STAGE(PG8_SB(1, 0), b3, voffB); PG8_STAGE(PG8_SB(1, 1), b3 + hstepB, voffB); PG8_STAGE(PG8_SA(1, 0), a3, voffA);
;             PG8_WAIT_V(8); PG8_WAIT_L(0); PG8_BAR; PG8_MMA(1, 0, At, B0); PG8_MMA(1, 1, At, B1); PG8_BAR; PG8_SCHED;
;         }
;         if constexpr (ALIGN_EPI) { if (wr == 0) PG8_BAR; }
	v_lshl_add_u64 v[242:243], v[242:243], 0, s[34:35]
	ds_read_b128 v[154:157], v240 offset:49152
	ds_read_b128 v[166:169], v240 offset:50176
	ds_read_b128 v[170:173], v240 offset:51200
	ds_read_b128 v[174:177], v240 offset:52224
	ds_read_b128 v[178:181], v240 offset:53248
	ds_read_b128 v[182:185], v240 offset:54272
	ds_read_b128 v[186:189], v240 offset:55296
	ds_read_b128 v[190:193], v240 offset:56320
	global_load_lds_dwordx4 v[242:243], off
	s_add_i32 m0, s79, 0x2000
	s_add_u32 s52, s52, 0xb0080
	v_lshl_add_u64 v[242:243], v[244:245], 0, s[34:35]
	s_addc_u32 s53, s53, 0
	s_add_i32 s79, s80, s59
	global_load_lds_dwordx4 v[242:243], off
	v_lshl_add_u64 v[242:243], s[52:53], 0, v[196:197]
	s_mov_b32 m0, s79
	s_nop 0
	global_load_lds_dwordx4 v[242:243], off
	v_lshl_add_u64 v[242:243], s[52:53], 0, v[198:199]
	s_add_i32 m0, s79, 0x2000
	s_nop 0
	global_load_lds_dwordx4 v[242:243], off
	v_lshl_add_u64 v[242:243], v[246:247], 0, s[36:37]
	s_mov_b32 m0, s67
	s_nop 0
	global_load_lds_dwordx4 v[242:243], off
	v_lshl_add_u64 v[242:243], v[246:247], 0, s[38:39]
	s_mov_b32 m0, s68
	s_nop 0
	global_load_lds_dwordx4 v[242:243], off
	s_waitcnt vmcnt(8)
	s_waitcnt lgkmcnt(0)
	s_barrier
	s_waitcnt lgkmcnt(0)
	v_mfma_f32_16x16x32_bf16 v[62:65], v[98:101], v[154:157], v[62:65]
	v_mfma_f32_16x16x32_bf16 v[58:61], v[122:125], v[154:157], v[58:61]
	v_mfma_f32_16x16x32_bf16 v[46:49], v[98:101], v[170:173], v[46:49]
	v_mfma_f32_16x16x32_bf16 v[42:45], v[122:125], v[170:173], v[42:45]
	v_mfma_f32_16x16x32_bf16 v[30:33], v[98:101], v[178:181], v[30:33]
	v_mfma_f32_16x16x32_bf16 v[26:29], v[122:125], v[178:181], v[26:29]
	v_mfma_f32_16x16x32_bf16 v[14:17], v[98:101], v[186:189], v[14:17]
	v_mfma_f32_16x16x32_bf16 v[10:13], v[122:125], v[186:189], v[10:13]
	v_mfma_f32_16x16x32_bf16 v[62:65], v[110:113], v[166:169], v[62:65]
	v_mfma_f32_16x16x32_bf16 v[58:61], v[126:129], v[166:169], v[58:61]
	v_mfma_f32_16x16x32_bf16 v[46:49], v[110:113], v[174:177], v[46:49]
	v_mfma_f32_16x16x32_bf16 v[42:45], v[126:129], v[174:177], v[42:45]
	v_mfma_f32_16x16x32_bf16 v[30:33], v[110:113], v[182:185], v[30:33]
	v_mfma_f32_16x16x32_bf16 v[26:29], v[126:129], v[182:185], v[26:29]
	v_mfma_f32_16x16x32_bf16 v[14:17], v[110:113], v[190:193], v[14:17]
	v_mfma_f32_16x16x32_bf16 v[10:13], v[126:129], v[190:193], v[10:13]
	v_mfma_f32_16x16x32_bf16 v[54:57], v[134:137], v[154:157], v[54:57]
	s_add_i32 s78, s78, 2
	v_mfma_f32_16x16x32_bf16 v[50:53], v[146:149], v[154:157], v[50:53]
	s_add_u32 s54, s54, 0x100
	v_mfma_f32_16x16x32_bf16 v[38:41], v[134:137], v[170:173], v[38:41]
	s_addc_u32 s55, s55, 0
	v_mfma_f32_16x16x32_bf16 v[34:37], v[146:149], v[170:173], v[34:37]
	s_add_u32 s50, s50, 0x10000
	v_mfma_f32_16x16x32_bf16 v[22:25], v[134:137], v[178:181], v[22:25]
	s_addc_u32 s51, s51, 0
	v_mfma_f32_16x16x32_bf16 v[18:21], v[146:149], v[178:181], v[18:21]
	s_cmp_gt_u32 s78, 41
	v_mfma_f32_16x16x32_bf16 v[6:9], v[134:137], v[186:189], v[6:9]
	v_mfma_f32_16x16x32_bf16 v[2:5], v[146:149], v[186:189], v[2:5]
	v_mfma_f32_16x16x32_bf16 v[54:57], v[142:145], v[166:169], v[54:57]
	v_mfma_f32_16x16x32_bf16 v[50:53], v[150:153], v[166:169], v[50:53]
	v_mfma_f32_16x16x32_bf16 v[38:41], v[142:145], v[174:177], v[38:41]
	v_mfma_f32_16x16x32_bf16 v[34:37], v[150:153], v[174:177], v[34:37]
	v_mfma_f32_16x16x32_bf16 v[22:25], v[142:145], v[182:185], v[22:25]
	v_mfma_f32_16x16x32_bf16 v[18:21], v[150:153], v[182:185], v[18:21]
	v_mfma_f32_16x16x32_bf16 v[6:9], v[142:145], v[190:193], v[6:9]
	v_mfma_f32_16x16x32_bf16 v[2:5], v[150:153], v[190:193], v[2:5]
	s_barrier
	s_cbranch_scc0 .LBB0_540
	s_and_b64 vcc, exec, s[40:41]
	s_cbranch_vccz .LBB0_543
	s_barrier

; #define PG8_STAGE(bufoff, gbase, voff) do { _Pragma("unroll") for (int _i = 0; _i < 2; ++_i) \
;         __builtin_amdgcn_global_load_lds((const unsigned*)((const char*)(gbase) + (voff)[_i]), (PG8_LAS unsigned*)(lds + (bufoff) + ldsw + _i * 8192), 16, 0, 0); } while (0)
; #define PG8_LDA(dst, b, h) do { _Pragma("unroll") for (int m = 0; m < 4; ++m) _Pragma("unroll") for (int k = 0; k < 2; ++k) dst[m][k] = *(const PG8_LAS bf16x8*)(lds + PG8_SA(b, h) + aoff + m * 2048 + k * 1024); } while (0)
; #define PG8_LDB(dst, b, h) do { _Pragma("unroll") for (int n = 0; n < 2; ++n) _Pragma("unroll") for (int k = 0; k < 2; ++k) dst[n][k] = *(const PG8_LAS bf16x8*)(lds + PG8_SB(b, h) + boff + n * 2048 + k * 1024); } while (0)
; #define PG8_MMA(ai, bj, At, Bt) do { __builtin_amdgcn_s_setprio(1); _Pragma("unroll") for (int m = 0; m < 4; ++m) _Pragma("unroll") for (int n = 0; n < 2; ++n) _Pragma("unroll") for (int k = 0; k < 2; ++k) \
;         acc[ai][bj][m][n] = __builtin_amdgcn_mfma_f32_16x16x32_bf16(Bt[n][k], At[m][k], acc[ai][bj][m][n], 0, 0, 0); __builtin_amdgcn_s_setprio(0); } while (0)
; template <class Epi, bool ALIGN_EPI, bool ABLK = false>
; __device__ __forceinline__ void gemm_phase(PG8_LAS unsigned char* lds, const Gemm g, const StaticOrder& S, const Epi& E) {
;     ...
;         for (int t = 0; t < nt; t += 2) {
;             const bool last = (t == nt - 2);
;             const char* a1 = cA + (size_t)(t + 1) * kstepA;
;             const char* a2 = last ? nA : cA + (size_t)(t + 2) * kstepA; const char* b2 = last ? nB : cB + (size_t)(t + 2) * kstepB;
;             const char* a3 = a2 + kstepA; const char* b3 = b2 + kstepB;
;             PG8_LDB(B0, 0, 0); PG8_LDB(B1, 0, 1); PG8_SCHED; PG8_LDA(At, 0, 0); PG8_STAGE(PG8_SA(1, 1), a1 + hstepA, voffA);
;             PG8_WAIT_V(8); PG8_WAIT_L(0); PG8_BAR; PG8_MMA(0, 0, At, B0); PG8_MMA(0, 1, At, B1); PG8_BAR; PG8_SCHED;
;             PG8_LDA(At, 0, 1); PG8_STAGE(PG8_SB(0, 0), b2, voffB); PG8_STAGE(PG8_SB(0, 1), b2 + hstepB, voffB); PG8_STAGE(PG8_SA(0, 0), a2, voffA);
;             PG8_WAIT_V(8); PG8_WAIT_L(0); PG8_BAR; PG8_MMA(1, 0, At, B0); PG8_MMA(1, 1, At, B1); PG8_BAR; PG8_SCHED;
;             PG8_LDB(B0, 1, 0); PG8_LDB(B1, 1, 1); PG8_SCHED; PG8_LDA(At, 1, 0); PG8_STAGE(PG8_SA(0, 1), a2 + hstepA, voffA);
;             PG8_WAIT_V(8); PG8_WAIT_L(0); PG8_BAR; PG8_MMA(0, 0, At, B0); PG8_MMA(0, 1, At, B1); PG8_BAR; PG8_SCHED;
.LBB0_818:
	ds_read_b128 v[132:135], v153
	ds_read_b128 v[136:139], v153 offset:1024
	ds_read_b128 v[140:143], v153 offset:2048
	ds_read_b128 v[144:147], v153 offset:3072
	ds_read_b128 v[148:151], v153 offset:16384
	ds_read_b128 v[178:181], v153 offset:17408
	ds_read_b128 v[182:185], v153 offset:18432
	ds_read_b128 v[212:215], v153 offset:19456
	s_add_u32 s12, s38, s10
	s_addc_u32 s13, s39, s11
	s_sub_u32 s98, s12, 0x10000
	s_subb_u32 s99, s13, 0
	s_cmp_eq_u32 s65, 12
	s_cselect_b32 s101, s33, s13
	s_cselect_b32 s100, s57, s12
	s_cselect_b32 s13, s55, s64
	s_cselect_b32 s12, s62, s63
	s_mov_b64 s[68:69], 0xc000
	s_add_i32 m0, s35, 0xc000
	s_mov_b64 s[68:69], 0xe000
	ds_read_b128 v[216:219], v205
	ds_read_b128 v[220:223], v205 offset:1024
	ds_read_b128 v[224:227], v205 offset:2048
	ds_read_b128 v[228:231], v205 offset:3072
	ds_read_b128 v[232:235], v205 offset:4096
	ds_read_b128 v[236:239], v205 offset:5120
	ds_read_b128 v[240:243], v205 offset:6144
	ds_read_b128 v[244:247], v205 offset:7168
	global_load_lds_dwordx4 v253, s[98:99]
	s_add_i32 m0, s35, 0xe000
	s_nop 0
	global_load_lds_dwordx4 v152, s[98:99]
	s_waitcnt vmcnt(8)
	s_waitcnt lgkmcnt(0)
	s_barrier
	s_waitcnt lgkmcnt(0)
	v_mfma_f32_16x16x32_bf16 v[126:129], v[132:135], v[216:219], v[126:129]
	v_mfma_f32_16x16x32_bf16 v[122:125], v[140:143], v[216:219], v[122:125]
	v_mfma_f32_16x16x32_bf16 v[118:121], v[132:135], v[224:227], v[118:121]
	v_mfma_f32_16x16x32_bf16 v[114:117], v[140:143], v[224:227], v[114:117]
	v_mfma_f32_16x16x32_bf16 v[110:113], v[132:135], v[232:235], v[110:113]
	v_mfma_f32_16x16x32_bf16 v[106:109], v[140:143], v[232:235], v[106:109]
	v_mfma_f32_16x16x32_bf16 v[102:105], v[132:135], v[240:243], v[102:105]
	v_mfma_f32_16x16x32_bf16 v[98:101], v[140:143], v[240:243], v[98:101]
	v_mfma_f32_16x16x32_bf16 v[126:129], v[136:139], v[220:223], v[126:129]
	v_mfma_f32_16x16x32_bf16 v[122:125], v[144:147], v[220:223], v[122:125]
	v_mfma_f32_16x16x32_bf16 v[118:121], v[136:139], v[228:231], v[118:121]
	v_mfma_f32_16x16x32_bf16 v[114:117], v[144:147], v[228:231], v[114:117]
	v_mfma_f32_16x16x32_bf16 v[110:113], v[136:139], v[236:239], v[110:113]
	v_mfma_f32_16x16x32_bf16 v[106:109], v[144:147], v[236:239], v[106:109]
	v_mfma_f32_16x16x32_bf16 v[102:105], v[136:139], v[244:247], v[102:105]
	v_mfma_f32_16x16x32_bf16 v[98:101], v[144:147], v[244:247], v[98:101]
	v_mfma_f32_16x16x32_bf16 v[94:97], v[148:151], v[216:219], v[94:97]
	s_add_i32 s68, s42, s31
	v_mfma_f32_16x16x32_bf16 v[90:93], v[182:185], v[216:219], v[90:93]
	s_mov_b32 m0, s68
	v_mfma_f32_16x16x32_bf16 v[86:89], v[148:151], v[224:227], v[86:89]
	v_mfma_f32_16x16x32_bf16 v[82:85], v[182:185], v[224:227], v[82:85]
	v_mfma_f32_16x16x32_bf16 v[78:81], v[148:151], v[232:235], v[78:81]
	v_mfma_f32_16x16x32_bf16 v[74:77], v[182:185], v[232:235], v[74:77]
	v_mfma_f32_16x16x32_bf16 v[70:73], v[148:151], v[240:243], v[70:73]
	v_mfma_f32_16x16x32_bf16 v[66:69], v[182:185], v[240:243], v[66:69]
	v_mfma_f32_16x16x32_bf16 v[94:97], v[178:181], v[220:223], v[94:97]
	v_mfma_f32_16x16x32_bf16 v[90:93], v[212:215], v[220:223], v[90:93]
	v_mfma_f32_16x16x32_bf16 v[86:89], v[178:181], v[228:231], v[86:89]
	v_mfma_f32_16x16x32_bf16 v[82:85], v[212:215], v[228:231], v[82:85]
	v_mfma_f32_16x16x32_bf16 v[78:81], v[178:181], v[236:239], v[78:81]
	v_mfma_f32_16x16x32_bf16 v[74:77], v[212:215], v[236:239], v[74:77]
	v_mfma_f32_16x16x32_bf16 v[70:73], v[178:181], v[244:247], v[70:73]
	v_mfma_f32_16x16x32_bf16 v[66:69], v[212:215], v[244:247], v[66:69]
	s_barrier
	ds_read_b128 v[216:219], v205 offset:16384
	ds_read_b128 v[220:223], v205 offset:17408
	ds_read_b128 v[224:227], v205 offset:18432
	ds_read_b128 v[228:231], v205 offset:19456
	ds_read_b128 v[232:235], v205 offset:20480
	ds_read_b128 v[236:239], v205 offset:21504
	ds_read_b128 v[240:243], v205 offset:22528
	ds_read_b128 v[244:247], v205 offset:23552
	global_load_lds_dwordx4 v156, s[12:13]
	s_add_i32 m0, s68, 0x2000
	s_add_u32 s68, s12, 0x40000
	s_addc_u32 s69, s13, 0
	s_add_i32 s70, s43, s31
	global_load_lds_dwordx4 v158, s[12:13]
	s_mov_b32 m0, s70
	s_nop 0
	global_load_lds_dwordx4 v156, s[68:69]
	s_add_i32 m0, s70, 0x2000
	s_nop 0
	global_load_lds_dwordx4 v158, s[68:69]
	s_mov_b32 m0, s35
	s_mov_b64 s[66:67], 0x2000
	global_load_lds_dwordx4 v154, s[100:101]
	s_mov_b32 m0, s18
	s_nop 0
	global_load_lds_dwordx4 v248, s[100:101]
	s_waitcnt vmcnt(8)
	s_waitcnt lgkmcnt(0)
	s_barrier
	s_waitcnt lgkmcnt(0)
	v_mfma_f32_16x16x32_bf16 v[62:65], v[132:135], v[216:219], v[62:65]
	v_mfma_f32_16x16x32_bf16 v[58:61], v[140:143], v[216:219], v[58:61]
	v_mfma_f32_16x16x32_bf16 v[54:57], v[132:135], v[224:227], v[54:57]
	v_mfma_f32_16x16x32_bf16 v[50:53], v[140:143], v[224:227], v[50:53]
	v_mfma_f32_16x16x32_bf16 v[46:49], v[132:135], v[232:235], v[46:49]
	v_mfma_f32_16x16x32_bf16 v[42:45], v[140:143], v[232:235], v[42:45]
	v_mfma_f32_16x16x32_bf16 v[38:41], v[132:135], v[240:243], v[38:41]
	v_mfma_f32_16x16x32_bf16 v[34:37], v[140:143], v[240:243], v[34:37]
	v_mfma_f32_16x16x32_bf16 v[62:65], v[136:139], v[220:223], v[62:65]
	v_mfma_f32_16x16x32_bf16 v[58:61], v[144:147], v[220:223], v[58:61]
	v_mfma_f32_16x16x32_bf16 v[54:57], v[136:139], v[228:231], v[54:57]
	v_mfma_f32_16x16x32_bf16 v[50:53], v[144:147], v[228:231], v[50:53]
	v_mfma_f32_16x16x32_bf16 v[46:49], v[136:139], v[236:239], v[46:49]
	v_mfma_f32_16x16x32_bf16 v[42:45], v[144:147], v[236:239], v[42:45]
	v_mfma_f32_16x16x32_bf16 v[38:41], v[136:139], v[244:247], v[38:41]
	v_mfma_f32_16x16x32_bf16 v[34:37], v[144:147], v[244:247], v[34:37]
	v_mfma_f32_16x16x32_bf16 v[30:33], v[148:151], v[216:219], v[30:33]
	s_add_i32 s68, 0, 0x18000
	v_mfma_f32_16x16x32_bf16 v[26:29], v[182:185], v[216:219], v[26:29]
	s_add_i32 s69, 0, 0x1c000
	v_mfma_f32_16x16x32_bf16 v[22:25], v[148:151], v[224:227], v[22:25]
	v_mfma_f32_16x16x32_bf16 v[18:21], v[182:185], v[224:227], v[18:21]
	v_mfma_f32_16x16x32_bf16 v[14:17], v[148:151], v[232:235], v[14:17]
	v_mfma_f32_16x16x32_bf16 v[10:13], v[182:185], v[232:235], v[10:13]
	v_mfma_f32_16x16x32_bf16 v[6:9], v[148:151], v[240:243], v[6:9]
	v_mfma_f32_16x16x32_bf16 v[2:5], v[182:185], v[240:243], v[2:5]
	v_mfma_f32_16x16x32_bf16 v[30:33], v[178:181], v[220:223], v[30:33]
	v_mfma_f32_16x16x32_bf16 v[26:29], v[212:215], v[220:223], v[26:29]
	v_mfma_f32_16x16x32_bf16 v[22:25], v[178:181], v[228:231], v[22:25]
	v_mfma_f32_16x16x32_bf16 v[18:21], v[212:215], v[228:231], v[18:21]
	v_mfma_f32_16x16x32_bf16 v[14:17], v[178:181], v[236:239], v[14:17]
	v_mfma_f32_16x16x32_bf16 v[10:13], v[212:215], v[236:239], v[10:13]
	v_mfma_f32_16x16x32_bf16 v[6:9], v[178:181], v[244:247], v[6:9]
	v_mfma_f32_16x16x32_bf16 v[2:5], v[212:215], v[244:247], v[2:5]
	s_barrier
; #define PG8_STAGE(bufoff, gbase, voff) do { _Pragma("unroll") for (int _i = 0; _i < 2; ++_i) \
;         __builtin_amdgcn_global_load_lds((const unsigned*)((const char*)(gbase) + (voff)[_i]), (PG8_LAS unsigned*)(lds + (bufoff) + ldsw + _i * 8192), 16, 0, 0); } while (0)
; #define PG8_LDA(dst, b, h) do { _Pragma("unroll") for (int m = 0; m < 4; ++m) _Pragma("unroll") for (int k = 0; k < 2; ++k) dst[m][k] = *(const PG8_LAS bf16x8*)(lds + PG8_SA(b, h) + aoff + m * 2048 + k * 1024); } while (0)
; #define PG8_LDB(dst, b, h) do { _Pragma("unroll") for (int n = 0; n < 2; ++n) _Pragma("unroll") for (int k = 0; k < 2; ++k) dst[n][k] = *(const PG8_LAS bf16x8*)(lds + PG8_SB(b, h) + boff + n * 2048 + k * 1024); } while (0)
; #define PG8_MMA(ai, bj, At, Bt) do { __builtin_amdgcn_s_setprio(1); _Pragma("unroll") for (int m = 0; m < 4; ++m) _Pragma("unroll") for (int n = 0; n < 2; ++n) _Pragma("unroll") for (int k = 0; k < 2; ++k) \
;         acc[ai][bj][m][n] = __builtin_amdgcn_mfma_f32_16x16x32_bf16(Bt[n][k], At[m][k], acc[ai][bj][m][n], 0, 0, 0); __builtin_amdgcn_s_setprio(0); } while (0)
; #define PG8_WAIT_V(n) asm volatile("s_waitcnt vmcnt(" #n ")" ::: "memory")
; #define PG8_WAIT_L(n) asm volatile("s_waitcnt lgkmcnt(" #n ")" ::: "memory")
; #define PG8_BAR __builtin_amdgcn_s_barrier()
; #define PG8_SCHED __builtin_amdgcn_sched_barrier(0)
; template <class Epi, bool ALIGN_EPI, bool ABLK = false>
; __device__ __forceinline__ void gemm_phase(PG8_LAS unsigned char* lds, const Gemm g, const StaticOrder& S, const Epi& E) {
;     ...
;             PG8_LDB(B0, 1, 0); PG8_LDB(B1, 1, 1); PG8_SCHED; PG8_LDA(At, 1, 0); PG8_STAGE(PG8_SA(0, 1), a2 + hstepA, voffA);
;             PG8_WAIT_V(8); PG8_WAIT_L(0); PG8_BAR; PG8_MMA(0, 0, At, B0); PG8_MMA(0, 1, At, B1); PG8_BAR; PG8_SCHED;
;             PG8_LDA(At, 1, 1); PG8_STAGE(PG8_SB(1, 0), b3, voffB); PG8_STAGE(PG8_SB(1, 1), b3 + hstepB, voffB); PG8_STAGE(PG8_SA(1, 0), a3, voffA);
;             PG8_WAIT_V(8); PG8_WAIT_L(0); PG8_BAR; PG8_MMA(1, 0, At, B0); PG8_MMA(1, 1, At, B1); PG8_BAR; PG8_SCHED;
;         }
;         if constexpr (ALIGN_EPI) { if (wr == 0) PG8_BAR; }
	ds_read_b128 v[132:135], v153 offset:32768
	ds_read_b128 v[136:139], v153 offset:33792
	ds_read_b128 v[140:143], v153 offset:34816
	ds_read_b128 v[144:147], v153 offset:35840
	ds_read_b128 v[148:151], v153 offset:49152
	ds_read_b128 v[178:181], v153 offset:50176
	ds_read_b128 v[182:185], v153 offset:51200
	ds_read_b128 v[212:215], v153 offset:52224
	s_mov_b64 s[66:67], 0x4000
	s_mov_b32 m0, s28
	s_mov_b64 s[66:67], 0x6000
	ds_read_b128 v[216:219], v205 offset:32768
	ds_read_b128 v[220:223], v205 offset:33792
	ds_read_b128 v[224:227], v205 offset:34816
	ds_read_b128 v[228:231], v205 offset:35840
	ds_read_b128 v[232:235], v205 offset:36864
	ds_read_b128 v[236:239], v205 offset:37888
	ds_read_b128 v[240:243], v205 offset:38912
	ds_read_b128 v[244:247], v205 offset:39936
	global_load_lds_dwordx4 v249, s[100:101]
	s_mov_b32 m0, s29
	s_nop 0
	global_load_lds_dwordx4 v250, s[100:101]
	s_waitcnt vmcnt(8)
	s_waitcnt lgkmcnt(0)
	s_barrier
	s_waitcnt lgkmcnt(0)
	v_mfma_f32_16x16x32_bf16 v[126:129], v[132:135], v[216:219], v[126:129]
	v_mfma_f32_16x16x32_bf16 v[122:125], v[140:143], v[216:219], v[122:125]
	v_mfma_f32_16x16x32_bf16 v[118:121], v[132:135], v[224:227], v[118:121]
	v_mfma_f32_16x16x32_bf16 v[114:117], v[140:143], v[224:227], v[114:117]
	v_mfma_f32_16x16x32_bf16 v[110:113], v[132:135], v[232:235], v[110:113]
	v_mfma_f32_16x16x32_bf16 v[106:109], v[140:143], v[232:235], v[106:109]
	v_mfma_f32_16x16x32_bf16 v[102:105], v[132:135], v[240:243], v[102:105]
	v_mfma_f32_16x16x32_bf16 v[98:101], v[140:143], v[240:243], v[98:101]
	v_mfma_f32_16x16x32_bf16 v[126:129], v[136:139], v[220:223], v[126:129]
	v_mfma_f32_16x16x32_bf16 v[122:125], v[144:147], v[220:223], v[122:125]
	v_mfma_f32_16x16x32_bf16 v[118:121], v[136:139], v[228:231], v[118:121]
	v_mfma_f32_16x16x32_bf16 v[114:117], v[144:147], v[228:231], v[114:117]
	v_mfma_f32_16x16x32_bf16 v[110:113], v[136:139], v[236:239], v[110:113]
	v_mfma_f32_16x16x32_bf16 v[106:109], v[144:147], v[236:239], v[106:109]
	v_mfma_f32_16x16x32_bf16 v[102:105], v[136:139], v[244:247], v[102:105]
	v_mfma_f32_16x16x32_bf16 v[98:101], v[144:147], v[244:247], v[98:101]
	v_mfma_f32_16x16x32_bf16 v[94:97], v[148:151], v[216:219], v[94:97]
	s_add_i32 s66, s68, s31
	v_mfma_f32_16x16x32_bf16 v[90:93], v[182:185], v[216:219], v[90:93]
	s_add_u32 s12, s12, s46
	v_mfma_f32_16x16x32_bf16 v[86:89], v[148:151], v[224:227], v[86:89]
	s_addc_u32 s13, s13, s47
	v_mfma_f32_16x16x32_bf16 v[82:85], v[182:185], v[224:227], v[82:85]
	s_mov_b32 m0, s66
	v_mfma_f32_16x16x32_bf16 v[78:81], v[148:151], v[232:235], v[78:81]
	v_mfma_f32_16x16x32_bf16 v[74:77], v[182:185], v[232:235], v[74:77]
	v_mfma_f32_16x16x32_bf16 v[70:73], v[148:151], v[240:243], v[70:73]
	v_mfma_f32_16x16x32_bf16 v[66:69], v[182:185], v[240:243], v[66:69]
	v_mfma_f32_16x16x32_bf16 v[94:97], v[178:181], v[220:223], v[94:97]
	v_mfma_f32_16x16x32_bf16 v[90:93], v[212:215], v[220:223], v[90:93]
	v_mfma_f32_16x16x32_bf16 v[86:89], v[178:181], v[228:231], v[86:89]
	v_mfma_f32_16x16x32_bf16 v[82:85], v[212:215], v[228:231], v[82:85]
	v_mfma_f32_16x16x32_bf16 v[78:81], v[178:181], v[236:239], v[78:81]
	v_mfma_f32_16x16x32_bf16 v[74:77], v[212:215], v[236:239], v[74:77]
	v_mfma_f32_16x16x32_bf16 v[70:73], v[178:181], v[244:247], v[70:73]
	v_mfma_f32_16x16x32_bf16 v[66:69], v[212:215], v[244:247], v[66:69]
	s_barrier
	ds_read_b128 v[216:219], v205 offset:49152
	ds_read_b128 v[220:223], v205 offset:50176
	ds_read_b128 v[224:227], v205 offset:51200
	ds_read_b128 v[228:231], v205 offset:52224
	ds_read_b128 v[232:235], v205 offset:53248
	ds_read_b128 v[236:239], v205 offset:54272
	ds_read_b128 v[240:243], v205 offset:55296
	ds_read_b128 v[244:247], v205 offset:56320
	global_load_lds_dwordx4 v156, s[12:13]
	s_add_i32 m0, s66, 0x2000
	s_add_i32 s66, s69, s31
	global_load_lds_dwordx4 v158, s[12:13]
	s_add_u32 s12, s12, 0x40000
	s_addc_u32 s13, s13, 0
	s_mov_b32 m0, s66
	s_nop 0
	global_load_lds_dwordx4 v156, s[12:13]
	s_add_i32 m0, s66, 0x2000
	s_nop 0
	global_load_lds_dwordx4 v158, s[12:13]
	s_mov_b32 m0, s0
	s_nop 0
	global_load_lds_dwordx4 v251, s[100:101]
	s_mov_b32 m0, s1
	s_nop 0
	global_load_lds_dwordx4 v252, s[100:101]
	s_waitcnt vmcnt(8)
	s_waitcnt lgkmcnt(0)
	s_barrier
	s_waitcnt lgkmcnt(0)
	v_mfma_f32_16x16x32_bf16 v[62:65], v[132:135], v[216:219], v[62:65]
	v_mfma_f32_16x16x32_bf16 v[58:61], v[140:143], v[216:219], v[58:61]
	v_mfma_f32_16x16x32_bf16 v[54:57], v[132:135], v[224:227], v[54:57]
	v_mfma_f32_16x16x32_bf16 v[50:53], v[140:143], v[224:227], v[50:53]
	v_mfma_f32_16x16x32_bf16 v[46:49], v[132:135], v[232:235], v[46:49]
	v_mfma_f32_16x16x32_bf16 v[42:45], v[140:143], v[232:235], v[42:45]
	v_mfma_f32_16x16x32_bf16 v[38:41], v[132:135], v[240:243], v[38:41]
	v_mfma_f32_16x16x32_bf16 v[34:37], v[140:143], v[240:243], v[34:37]
	v_mfma_f32_16x16x32_bf16 v[62:65], v[136:139], v[220:223], v[62:65]
	v_mfma_f32_16x16x32_bf16 v[58:61], v[144:147], v[220:223], v[58:61]
	v_mfma_f32_16x16x32_bf16 v[54:57], v[136:139], v[228:231], v[54:57]
	v_mfma_f32_16x16x32_bf16 v[50:53], v[144:147], v[228:231], v[50:53]
	v_mfma_f32_16x16x32_bf16 v[46:49], v[136:139], v[236:239], v[46:49]
	v_mfma_f32_16x16x32_bf16 v[42:45], v[144:147], v[236:239], v[42:45]
	v_mfma_f32_16x16x32_bf16 v[38:41], v[136:139], v[244:247], v[38:41]
	v_mfma_f32_16x16x32_bf16 v[34:37], v[144:147], v[244:247], v[34:37]
	v_mfma_f32_16x16x32_bf16 v[30:33], v[148:151], v[216:219], v[30:33]
	s_add_i32 s65, s65, 2
	v_mfma_f32_16x16x32_bf16 v[26:29], v[182:185], v[216:219], v[26:29]
	s_add_u32 s63, s63, 0x100
	v_mfma_f32_16x16x32_bf16 v[22:25], v[148:151], v[224:227], v[22:25]
	s_addc_u32 s64, s64, 0
	v_mfma_f32_16x16x32_bf16 v[18:21], v[182:185], v[224:227], v[18:21]
	s_add_u32 s10, s10, 0x10000
	v_mfma_f32_16x16x32_bf16 v[14:17], v[148:151], v[232:235], v[14:17]
	s_addc_u32 s11, s11, 0
	v_mfma_f32_16x16x32_bf16 v[10:13], v[182:185], v[232:235], v[10:13]
	s_mov_b64 s[12:13], 0x10000
	v_mfma_f32_16x16x32_bf16 v[6:9], v[148:151], v[240:243], v[6:9]
	s_cmp_gt_u32 s65, 13
	v_mfma_f32_16x16x32_bf16 v[2:5], v[182:185], v[240:243], v[2:5]
	v_mfma_f32_16x16x32_bf16 v[30:33], v[178:181], v[220:223], v[30:33]
	v_mfma_f32_16x16x32_bf16 v[26:29], v[212:215], v[220:223], v[26:29]
	v_mfma_f32_16x16x32_bf16 v[22:25], v[178:181], v[228:231], v[22:25]
	v_mfma_f32_16x16x32_bf16 v[18:21], v[212:215], v[228:231], v[18:21]
	v_mfma_f32_16x16x32_bf16 v[14:17], v[178:181], v[236:239], v[14:17]
	v_mfma_f32_16x16x32_bf16 v[10:13], v[212:215], v[236:239], v[10:13]
	v_mfma_f32_16x16x32_bf16 v[6:9], v[178:181], v[244:247], v[6:9]
	v_mfma_f32_16x16x32_bf16 v[2:5], v[212:215], v[244:247], v[2:5]
	s_barrier
	s_cbranch_scc0 .LBB0_818
	s_and_b64 vcc, exec, s[52:53]
	s_cbranch_vccz .LBB0_821
	s_barrier

; #define PG8_STAGE(bufoff, gbase, voff) do { _Pragma("unroll") for (int _i = 0; _i < 2; ++_i) \
;         __builtin_amdgcn_global_load_lds((const unsigned*)((const char*)(gbase) + (voff)[_i]), (PG8_LAS unsigned*)(lds + (bufoff) + ldsw + _i * 8192), 16, 0, 0); } while (0)
; #define PG8_LDA(dst, b, h) do { _Pragma("unroll") for (int m = 0; m < 4; ++m) _Pragma("unroll") for (int k = 0; k < 2; ++k) dst[m][k] = *(const PG8_LAS bf16x8*)(lds + PG8_SA(b, h) + aoff + m * 2048 + k * 1024); } while (0)
; #define PG8_LDB(dst, b, h) do { _Pragma("unroll") for (int n = 0; n < 2; ++n) _Pragma("unroll") for (int k = 0; k < 2; ++k) dst[n][k] = *(const PG8_LAS bf16x8*)(lds + PG8_SB(b, h) + boff + n * 2048 + k * 1024); } while (0)
; #define PG8_MMA(ai, bj, At, Bt) do { __builtin_amdgcn_s_setprio(1); _Pragma("unroll") for (int m = 0; m < 4; ++m) _Pragma("unroll") for (int n = 0; n < 2; ++n) _Pragma("unroll") for (int k = 0; k < 2; ++k) \
;         acc[ai][bj][m][n] = __builtin_amdgcn_mfma_f32_16x16x32_bf16(Bt[n][k], At[m][k], acc[ai][bj][m][n], 0, 0, 0); __builtin_amdgcn_s_setprio(0); } while (0)
; template <class Epi, bool ALIGN_EPI, bool ABLK = false>
; __device__ __forceinline__ void gemm_phase(PG8_LAS unsigned char* lds, const Gemm g, const StaticOrder& S, const Epi& E) {
;     ...
;         for (int t = 0; t < nt; t += 2) {
;             const bool last = (t == nt - 2);
;             const char* a1 = cA + (size_t)(t + 1) * kstepA;
;             const char* a2 = last ? nA : cA + (size_t)(t + 2) * kstepA; const char* b2 = last ? nB : cB + (size_t)(t + 2) * kstepB;
;             const char* a3 = a2 + kstepA; const char* b3 = b2 + kstepB;
;             PG8_LDB(B0, 0, 0); PG8_LDB(B1, 0, 1); PG8_SCHED; PG8_LDA(At, 0, 0); PG8_STAGE(PG8_SA(1, 1), a1 + hstepA, voffA);
;             PG8_WAIT_V(8); PG8_WAIT_L(0); PG8_BAR; PG8_MMA(0, 0, At, B0); PG8_MMA(0, 1, At, B1); PG8_BAR; PG8_SCHED;
;             PG8_LDA(At, 0, 1); PG8_STAGE(PG8_SB(0, 0), b2, voffB); PG8_STAGE(PG8_SB(0, 1), b2 + hstepB, voffB); PG8_STAGE(PG8_SA(0, 0), a2, voffA);
;             PG8_WAIT_V(8); PG8_WAIT_L(0); PG8_BAR; PG8_MMA(1, 0, At, B0); PG8_MMA(1, 1, At, B1); PG8_BAR; PG8_SCHED;
;             PG8_LDB(B0, 1, 0); PG8_LDB(B1, 1, 1); PG8_SCHED; PG8_LDA(At, 1, 0); PG8_STAGE(PG8_SA(0, 1), a2 + hstepA, voffA);
;             PG8_WAIT_V(8); PG8_WAIT_L(0); PG8_BAR; PG8_MMA(0, 0, At, B0); PG8_MMA(0, 1, At, B1); PG8_BAR; PG8_SCHED;
.LBB0_1983:
	v_add_u32_e32 v136, s71, v179
	ds_read_b128 v[132:135], v136
	ds_read_b128 v[184:187], v136 offset:1024
	ds_read_b128 v[188:191], v136 offset:2048
	ds_read_b128 v[192:195], v136 offset:3072
	v_add_u32_e32 v136, s72, v179
	ds_read_b128 v[196:199], v136
	ds_read_b128 v[200:203], v136 offset:1024
	ds_read_b128 v[204:207], v136 offset:2048
	ds_read_b128 v[208:211], v136 offset:3072
	s_add_u32 s62, s26, s60
	s_addc_u32 s63, s27, s61
	s_cmp_eq_u32 s79, 12
	s_cselect_b32 s81, s55, s63
	s_cselect_b32 s80, s75, s62
	s_cselect_b32 s63, s53, s78
	s_cselect_b32 s62, s76, s77
	v_lshl_add_u64 v[136:137], s[26:27], 0, v[130:131]
	v_lshl_add_u64 v[244:245], v[136:137], 0, s[40:41]
	s_add_i32 m0, s23, 0xc000
	ds_read_b128 v[212:215], v182
	ds_read_b128 v[216:219], v182 offset:1024
	ds_read_b128 v[220:223], v182 offset:2048
	ds_read_b128 v[224:227], v182 offset:3072
	ds_read_b128 v[228:231], v182 offset:4096
	ds_read_b128 v[232:235], v182 offset:5120
	ds_read_b128 v[236:239], v182 offset:6144
	ds_read_b128 v[240:243], v182 offset:7168
	global_load_lds_dwordx4 v[244:245], off
	v_lshl_add_u64 v[136:137], v[136:137], 0, s[42:43]
	s_add_i32 m0, s23, 0xe000
	s_nop 0
	global_load_lds_dwordx4 v[136:137], off
	s_waitcnt vmcnt(8)
	s_waitcnt lgkmcnt(0)
	s_barrier
	s_waitcnt lgkmcnt(0)
	v_mfma_f32_16x16x32_bf16 v[126:129], v[132:135], v[212:215], v[126:129]
	v_mfma_f32_16x16x32_bf16 v[122:125], v[188:191], v[212:215], v[122:125]
	v_mfma_f32_16x16x32_bf16 v[118:121], v[132:135], v[220:223], v[118:121]
	v_mfma_f32_16x16x32_bf16 v[114:117], v[188:191], v[220:223], v[114:117]
	v_mfma_f32_16x16x32_bf16 v[110:113], v[132:135], v[228:231], v[110:113]
	v_mfma_f32_16x16x32_bf16 v[106:109], v[188:191], v[228:231], v[106:109]
	v_mfma_f32_16x16x32_bf16 v[102:105], v[132:135], v[236:239], v[102:105]
	v_mfma_f32_16x16x32_bf16 v[98:101], v[188:191], v[236:239], v[98:101]
	v_mfma_f32_16x16x32_bf16 v[126:129], v[184:187], v[216:219], v[126:129]
	v_mfma_f32_16x16x32_bf16 v[122:125], v[192:195], v[216:219], v[122:125]
	v_mfma_f32_16x16x32_bf16 v[118:121], v[184:187], v[224:227], v[118:121]
	v_mfma_f32_16x16x32_bf16 v[114:117], v[192:195], v[224:227], v[114:117]
	v_mfma_f32_16x16x32_bf16 v[110:113], v[184:187], v[232:235], v[110:113]
	v_mfma_f32_16x16x32_bf16 v[106:109], v[192:195], v[232:235], v[106:109]
	v_mfma_f32_16x16x32_bf16 v[102:105], v[184:187], v[240:243], v[102:105]
	v_mfma_f32_16x16x32_bf16 v[98:101], v[192:195], v[240:243], v[98:101]
	v_mfma_f32_16x16x32_bf16 v[94:97], v[196:199], v[212:215], v[94:97]
	s_add_i32 s82, s71, s21
	v_mfma_f32_16x16x32_bf16 v[90:93], v[204:207], v[212:215], v[90:93]
	s_mov_b32 m0, s82
	v_mfma_f32_16x16x32_bf16 v[86:89], v[196:199], v[220:223], v[86:89]
	v_mfma_f32_16x16x32_bf16 v[82:85], v[204:207], v[220:223], v[82:85]
	v_mfma_f32_16x16x32_bf16 v[78:81], v[196:199], v[228:231], v[78:81]
	v_mfma_f32_16x16x32_bf16 v[74:77], v[204:207], v[228:231], v[74:77]
	v_mfma_f32_16x16x32_bf16 v[70:73], v[196:199], v[236:239], v[70:73]
	v_mfma_f32_16x16x32_bf16 v[66:69], v[204:207], v[236:239], v[66:69]
	v_mfma_f32_16x16x32_bf16 v[94:97], v[200:203], v[216:219], v[94:97]
	v_mfma_f32_16x16x32_bf16 v[90:93], v[208:211], v[216:219], v[90:93]
	v_mfma_f32_16x16x32_bf16 v[86:89], v[200:203], v[224:227], v[86:89]
	v_mfma_f32_16x16x32_bf16 v[82:85], v[208:211], v[224:227], v[82:85]
	v_mfma_f32_16x16x32_bf16 v[78:81], v[200:203], v[232:235], v[78:81]
	v_mfma_f32_16x16x32_bf16 v[74:77], v[208:211], v[232:235], v[74:77]
	v_mfma_f32_16x16x32_bf16 v[70:73], v[200:203], v[240:243], v[70:73]
	v_mfma_f32_16x16x32_bf16 v[66:69], v[208:211], v[240:243], v[66:69]
	s_barrier
	v_lshl_add_u64 v[136:137], s[62:63], 0, v[140:141]
	ds_read_b128 v[212:215], v182 offset:16384
	ds_read_b128 v[216:219], v182 offset:17408
	ds_read_b128 v[220:223], v182 offset:18432
	ds_read_b128 v[224:227], v182 offset:19456
	ds_read_b128 v[228:231], v182 offset:20480
	ds_read_b128 v[232:235], v182 offset:21504
	ds_read_b128 v[236:239], v182 offset:22528
	ds_read_b128 v[240:243], v182 offset:23552
	global_load_lds_dwordx4 v[136:137], off
	s_add_i32 m0, s82, 0x2000
	s_add_u32 s82, s62, 0x40000
	v_lshl_add_u64 v[244:245], s[62:63], 0, v[142:143]
	s_addc_u32 s83, s63, 0
	s_add_i32 s84, s72, s21
	global_load_lds_dwordx4 v[244:245], off
	v_lshl_add_u64 v[246:247], s[82:83], 0, v[140:141]
	s_mov_b32 m0, s84
	s_nop 0
	global_load_lds_dwordx4 v[246:247], off
	v_lshl_add_u64 v[246:247], s[82:83], 0, v[142:143]
	s_add_i32 m0, s84, 0x2000
	s_nop 0
	global_load_lds_dwordx4 v[246:247], off
	v_lshl_add_u64 v[246:247], s[80:81], 0, v[138:139]
	s_mov_b32 m0, s23
	v_lshl_add_u64 v[248:249], v[246:247], 0, s[44:45]
	global_load_lds_dwordx4 v[246:247], off
	s_mov_b32 m0, s33
	s_nop 0
	global_load_lds_dwordx4 v[248:249], off
	s_waitcnt vmcnt(8)
	s_waitcnt lgkmcnt(0)
	s_barrier
; #define PG8_STAGE(bufoff, gbase, voff) do { _Pragma("unroll") for (int _i = 0; _i < 2; ++_i) \
;         __builtin_amdgcn_global_load_lds((const unsigned*)((const char*)(gbase) + (voff)[_i]), (PG8_LAS unsigned*)(lds + (bufoff) + ldsw + _i * 8192), 16, 0, 0); } while (0)
; #define PG8_LDA(dst, b, h) do { _Pragma("unroll") for (int m = 0; m < 4; ++m) _Pragma("unroll") for (int k = 0; k < 2; ++k) dst[m][k] = *(const PG8_LAS bf16x8*)(lds + PG8_SA(b, h) + aoff + m * 2048 + k * 1024); } while (0)
; #define PG8_LDB(dst, b, h) do { _Pragma("unroll") for (int n = 0; n < 2; ++n) _Pragma("unroll") for (int k = 0; k < 2; ++k) dst[n][k] = *(const PG8_LAS bf16x8*)(lds + PG8_SB(b, h) + boff + n * 2048 + k * 1024); } while (0)
; #define PG8_MMA(ai, bj, At, Bt) do { __builtin_amdgcn_s_setprio(1); _Pragma("unroll") for (int m = 0; m < 4; ++m) _Pragma("unroll") for (int n = 0; n < 2; ++n) _Pragma("unroll") for (int k = 0; k < 2; ++k) \
;         acc[ai][bj][m][n] = __builtin_amdgcn_mfma_f32_16x16x32_bf16(Bt[n][k], At[m][k], acc[ai][bj][m][n], 0, 0, 0); __builtin_amdgcn_s_setprio(0); } while (0)
; #define PG8_WAIT_V(n) asm volatile("s_waitcnt vmcnt(" #n ")" ::: "memory")
; #define PG8_WAIT_L(n) asm volatile("s_waitcnt lgkmcnt(" #n ")" ::: "memory")
; #define PG8_BAR __builtin_amdgcn_s_barrier()
; #define PG8_SCHED __builtin_amdgcn_sched_barrier(0)
; template <class Epi, bool ALIGN_EPI, bool ABLK = false>
; __device__ __forceinline__ void gemm_phase(PG8_LAS unsigned char* lds, const Gemm g, const StaticOrder& S, const Epi& E) {
;     ...
;             PG8_WAIT_V(8); PG8_WAIT_L(0); PG8_BAR; PG8_MMA(1, 0, At, B0); PG8_MMA(1, 1, At, B1); PG8_BAR; PG8_SCHED;
;             PG8_LDB(B0, 1, 0); PG8_LDB(B1, 1, 1); PG8_SCHED; PG8_LDA(At, 1, 0); PG8_STAGE(PG8_SA(0, 1), a2 + hstepA, voffA);
;             PG8_WAIT_V(8); PG8_WAIT_L(0); PG8_BAR; PG8_MMA(0, 0, At, B0); PG8_MMA(0, 1, At, B1); PG8_BAR; PG8_SCHED;
;             PG8_LDA(At, 1, 1); PG8_STAGE(PG8_SB(1, 0), b3, voffB); PG8_STAGE(PG8_SB(1, 1), b3 + hstepB, voffB); PG8_STAGE(PG8_SA(1, 0), a3, voffA);
	s_waitcnt lgkmcnt(0)
	v_mfma_f32_16x16x32_bf16 v[62:65], v[132:135], v[212:215], v[62:65]
	v_mfma_f32_16x16x32_bf16 v[58:61], v[188:191], v[212:215], v[58:61]
	v_mfma_f32_16x16x32_bf16 v[54:57], v[132:135], v[220:223], v[54:57]
	v_mfma_f32_16x16x32_bf16 v[50:53], v[188:191], v[220:223], v[50:53]
	v_mfma_f32_16x16x32_bf16 v[46:49], v[132:135], v[228:231], v[46:49]
	v_mfma_f32_16x16x32_bf16 v[42:45], v[188:191], v[228:231], v[42:45]
	v_mfma_f32_16x16x32_bf16 v[38:41], v[132:135], v[236:239], v[38:41]
	v_mfma_f32_16x16x32_bf16 v[34:37], v[188:191], v[236:239], v[34:37]
	v_mfma_f32_16x16x32_bf16 v[62:65], v[184:187], v[216:219], v[62:65]
	v_mfma_f32_16x16x32_bf16 v[58:61], v[192:195], v[216:219], v[58:61]
	v_mfma_f32_16x16x32_bf16 v[54:57], v[184:187], v[224:227], v[54:57]
	v_mfma_f32_16x16x32_bf16 v[50:53], v[192:195], v[224:227], v[50:53]
	v_mfma_f32_16x16x32_bf16 v[46:49], v[184:187], v[232:235], v[46:49]
	v_mfma_f32_16x16x32_bf16 v[42:45], v[192:195], v[232:235], v[42:45]
	v_mfma_f32_16x16x32_bf16 v[38:41], v[184:187], v[240:243], v[38:41]
	v_mfma_f32_16x16x32_bf16 v[34:37], v[192:195], v[240:243], v[34:37]
	v_mfma_f32_16x16x32_bf16 v[30:33], v[196:199], v[212:215], v[30:33]
	s_add_i32 s80, 0, 0x18000
	v_mfma_f32_16x16x32_bf16 v[26:29], v[204:207], v[212:215], v[26:29]
	s_add_i32 s81, 0, 0x1c000
	v_mfma_f32_16x16x32_bf16 v[22:25], v[196:199], v[220:223], v[22:25]
	v_mfma_f32_16x16x32_bf16 v[18:21], v[204:207], v[220:223], v[18:21]
	v_mfma_f32_16x16x32_bf16 v[14:17], v[196:199], v[228:231], v[14:17]
	v_mfma_f32_16x16x32_bf16 v[10:13], v[204:207], v[228:231], v[10:13]
	v_mfma_f32_16x16x32_bf16 v[6:9], v[196:199], v[236:239], v[6:9]
	v_mfma_f32_16x16x32_bf16 v[2:5], v[204:207], v[236:239], v[2:5]
	v_mfma_f32_16x16x32_bf16 v[30:33], v[200:203], v[216:219], v[30:33]
	v_mfma_f32_16x16x32_bf16 v[26:29], v[208:211], v[216:219], v[26:29]
	v_mfma_f32_16x16x32_bf16 v[22:25], v[200:203], v[224:227], v[22:25]
	v_mfma_f32_16x16x32_bf16 v[18:21], v[208:211], v[224:227], v[18:21]
	v_mfma_f32_16x16x32_bf16 v[14:17], v[200:203], v[232:235], v[14:17]
	v_mfma_f32_16x16x32_bf16 v[10:13], v[208:211], v[232:235], v[10:13]
	v_mfma_f32_16x16x32_bf16 v[6:9], v[200:203], v[240:243], v[6:9]
	v_mfma_f32_16x16x32_bf16 v[2:5], v[208:211], v[240:243], v[2:5]
	s_barrier
	v_add_u32_e32 v192, s80, v179
	v_add_u32_e32 v208, s81, v179
	ds_read_b128 v[132:135], v192
	ds_read_b128 v[184:187], v192 offset:1024
	ds_read_b128 v[188:191], v192 offset:2048
	ds_read_b128 v[192:195], v192 offset:3072
	ds_read_b128 v[196:199], v208
	ds_read_b128 v[200:203], v208 offset:1024
	ds_read_b128 v[204:207], v208 offset:2048
	ds_read_b128 v[208:211], v208 offset:3072
	s_mov_b32 m0, s67
	v_lshl_add_u64 v[248:249], v[246:247], 0, s[46:47]
	ds_read_b128 v[212:215], v182 offset:32768
	ds_read_b128 v[216:219], v182 offset:33792
	ds_read_b128 v[220:223], v182 offset:34816
	ds_read_b128 v[224:227], v182 offset:35840
	ds_read_b128 v[228:231], v182 offset:36864
	ds_read_b128 v[232:235], v182 offset:37888
	ds_read_b128 v[236:239], v182 offset:38912
	ds_read_b128 v[240:243], v182 offset:39936
	global_load_lds_dwordx4 v[248:249], off
	v_lshl_add_u64 v[248:249], v[246:247], 0, s[48:49]
	s_mov_b32 m0, s68
	s_nop 0
	global_load_lds_dwordx4 v[248:249], off
	s_waitcnt vmcnt(8)
	s_waitcnt lgkmcnt(0)
	s_barrier
	s_waitcnt lgkmcnt(0)
	v_mfma_f32_16x16x32_bf16 v[126:129], v[132:135], v[212:215], v[126:129]
	v_mfma_f32_16x16x32_bf16 v[122:125], v[188:191], v[212:215], v[122:125]
	v_mfma_f32_16x16x32_bf16 v[118:121], v[132:135], v[220:223], v[118:121]
	v_mfma_f32_16x16x32_bf16 v[114:117], v[188:191], v[220:223], v[114:117]
	v_mfma_f32_16x16x32_bf16 v[110:113], v[132:135], v[228:231], v[110:113]
	v_mfma_f32_16x16x32_bf16 v[106:109], v[188:191], v[228:231], v[106:109]
	v_mfma_f32_16x16x32_bf16 v[102:105], v[132:135], v[236:239], v[102:105]
	v_mfma_f32_16x16x32_bf16 v[98:101], v[188:191], v[236:239], v[98:101]
	v_mfma_f32_16x16x32_bf16 v[126:129], v[184:187], v[216:219], v[126:129]
	v_mfma_f32_16x16x32_bf16 v[122:125], v[192:195], v[216:219], v[122:125]
	v_mfma_f32_16x16x32_bf16 v[118:121], v[184:187], v[224:227], v[118:121]
	v_mfma_f32_16x16x32_bf16 v[114:117], v[192:195], v[224:227], v[114:117]
	v_mfma_f32_16x16x32_bf16 v[110:113], v[184:187], v[232:235], v[110:113]
	v_mfma_f32_16x16x32_bf16 v[106:109], v[192:195], v[232:235], v[106:109]
	v_mfma_f32_16x16x32_bf16 v[102:105], v[184:187], v[240:243], v[102:105]
	v_mfma_f32_16x16x32_bf16 v[98:101], v[192:195], v[240:243], v[98:101]
	v_mfma_f32_16x16x32_bf16 v[94:97], v[196:199], v[212:215], v[94:97]
	s_add_i32 s80, s80, s21
	v_mfma_f32_16x16x32_bf16 v[90:93], v[204:207], v[212:215], v[90:93]
	s_mov_b32 m0, s80
	v_mfma_f32_16x16x32_bf16 v[86:89], v[196:199], v[220:223], v[86:89]
	v_mfma_f32_16x16x32_bf16 v[82:85], v[204:207], v[220:223], v[82:85]
	v_mfma_f32_16x16x32_bf16 v[78:81], v[196:199], v[228:231], v[78:81]
	v_mfma_f32_16x16x32_bf16 v[74:77], v[204:207], v[228:231], v[74:77]
	v_mfma_f32_16x16x32_bf16 v[70:73], v[196:199], v[236:239], v[70:73]
	v_mfma_f32_16x16x32_bf16 v[66:69], v[204:207], v[236:239], v[66:69]
	v_mfma_f32_16x16x32_bf16 v[94:97], v[200:203], v[216:219], v[94:97]
	v_mfma_f32_16x16x32_bf16 v[90:93], v[208:211], v[216:219], v[90:93]
	v_mfma_f32_16x16x32_bf16 v[86:89], v[200:203], v[224:227], v[86:89]
	v_mfma_f32_16x16x32_bf16 v[82:85], v[208:211], v[224:227], v[82:85]
	v_mfma_f32_16x16x32_bf16 v[78:81], v[200:203], v[232:235], v[78:81]
	v_mfma_f32_16x16x32_bf16 v[74:77], v[208:211], v[232:235], v[74:77]
	v_mfma_f32_16x16x32_bf16 v[70:73], v[200:203], v[240:243], v[70:73]
	v_mfma_f32_16x16x32_bf16 v[66:69], v[208:211], v[240:243], v[66:69]
	s_barrier
; #define PG8_STAGE(bufoff, gbase, voff) do { _Pragma("unroll") for (int _i = 0; _i < 2; ++_i) \
;         __builtin_amdgcn_global_load_lds((const unsigned*)((const char*)(gbase) + (voff)[_i]), (PG8_LAS unsigned*)(lds + (bufoff) + ldsw + _i * 8192), 16, 0, 0); } while (0)
; #define PG8_LDA(dst, b, h) do { _Pragma("unroll") for (int m = 0; m < 4; ++m) _Pragma("unroll") for (int k = 0; k < 2; ++k) dst[m][k] = *(const PG8_LAS bf16x8*)(lds + PG8_SA(b, h) + aoff + m * 2048 + k * 1024); } while (0)
; #define PG8_MMA(ai, bj, At, Bt) do { __builtin_amdgcn_s_setprio(1); _Pragma("unroll") for (int m = 0; m < 4; ++m) _Pragma("unroll") for (int n = 0; n < 2; ++n) _Pragma("unroll") for (int k = 0; k < 2; ++k) \
;         acc[ai][bj][m][n] = __builtin_amdgcn_mfma_f32_16x16x32_bf16(Bt[n][k], At[m][k], acc[ai][bj][m][n], 0, 0, 0); __builtin_amdgcn_s_setprio(0); } while (0)
; #define PG8_WAIT_V(n) asm volatile("s_waitcnt vmcnt(" #n ")" ::: "memory")
; #define PG8_WAIT_L(n) asm volatile("s_waitcnt lgkmcnt(" #n ")" ::: "memory")
; #define PG8_BAR __builtin_amdgcn_s_barrier()
; #define PG8_SCHED __builtin_amdgcn_sched_barrier(0)
; template <class Epi, bool ALIGN_EPI, bool ABLK = false>
; __device__ __forceinline__ void gemm_phase(PG8_LAS unsigned char* lds, const Gemm g, const StaticOrder& S, const Epi& E) {
;     ...
;             PG8_LDA(At, 1, 1); PG8_STAGE(PG8_SB(1, 0), b3, voffB); PG8_STAGE(PG8_SB(1, 1), b3 + hstepB, voffB); PG8_STAGE(PG8_SA(1, 0), a3, voffA);
;             PG8_WAIT_V(8); PG8_WAIT_L(0); PG8_BAR; PG8_MMA(1, 0, At, B0); PG8_MMA(1, 1, At, B1); PG8_BAR; PG8_SCHED;
;         }
;         if constexpr (ALIGN_EPI) { if (wr == 0) PG8_BAR; }
	v_lshl_add_u64 v[136:137], v[136:137], 0, s[30:31]
	ds_read_b128 v[212:215], v182 offset:49152
	ds_read_b128 v[216:219], v182 offset:50176
	ds_read_b128 v[220:223], v182 offset:51200
	ds_read_b128 v[224:227], v182 offset:52224
	ds_read_b128 v[228:231], v182 offset:53248
	ds_read_b128 v[232:235], v182 offset:54272
	ds_read_b128 v[236:239], v182 offset:55296
	ds_read_b128 v[240:243], v182 offset:56320
	global_load_lds_dwordx4 v[136:137], off
	s_add_i32 m0, s80, 0x2000
	s_add_u32 s62, s62, 0x40080
	v_lshl_add_u64 v[136:137], v[244:245], 0, s[30:31]
	s_addc_u32 s63, s63, 0
	s_add_i32 s80, s81, s21
	global_load_lds_dwordx4 v[136:137], off
	v_lshl_add_u64 v[136:137], s[62:63], 0, v[140:141]
	s_mov_b32 m0, s80
	s_nop 0
	global_load_lds_dwordx4 v[136:137], off
	v_lshl_add_u64 v[136:137], s[62:63], 0, v[142:143]
	s_add_i32 m0, s80, 0x2000
	s_nop 0
	global_load_lds_dwordx4 v[136:137], off
	v_lshl_add_u64 v[136:137], v[246:247], 0, s[34:35]
	s_mov_b32 m0, s9
	s_nop 0
	global_load_lds_dwordx4 v[136:137], off
	v_lshl_add_u64 v[136:137], v[246:247], 0, s[36:37]
	s_mov_b32 m0, s70
	s_nop 0
	global_load_lds_dwordx4 v[136:137], off
	s_waitcnt vmcnt(8)
	s_waitcnt lgkmcnt(0)
	s_barrier
	s_waitcnt lgkmcnt(0)
	v_mfma_f32_16x16x32_bf16 v[62:65], v[132:135], v[212:215], v[62:65]
	v_mfma_f32_16x16x32_bf16 v[58:61], v[188:191], v[212:215], v[58:61]
	v_mfma_f32_16x16x32_bf16 v[54:57], v[132:135], v[220:223], v[54:57]
	v_mfma_f32_16x16x32_bf16 v[50:53], v[188:191], v[220:223], v[50:53]
	v_mfma_f32_16x16x32_bf16 v[46:49], v[132:135], v[228:231], v[46:49]
	v_mfma_f32_16x16x32_bf16 v[42:45], v[188:191], v[228:231], v[42:45]
	v_mfma_f32_16x16x32_bf16 v[38:41], v[132:135], v[236:239], v[38:41]
	v_mfma_f32_16x16x32_bf16 v[34:37], v[188:191], v[236:239], v[34:37]
	v_mfma_f32_16x16x32_bf16 v[62:65], v[184:187], v[216:219], v[62:65]
	v_mfma_f32_16x16x32_bf16 v[58:61], v[192:195], v[216:219], v[58:61]
	v_mfma_f32_16x16x32_bf16 v[54:57], v[184:187], v[224:227], v[54:57]
	v_mfma_f32_16x16x32_bf16 v[50:53], v[192:195], v[224:227], v[50:53]
	v_mfma_f32_16x16x32_bf16 v[46:49], v[184:187], v[232:235], v[46:49]
	v_mfma_f32_16x16x32_bf16 v[42:45], v[192:195], v[232:235], v[42:45]
	v_mfma_f32_16x16x32_bf16 v[38:41], v[184:187], v[240:243], v[38:41]
	v_mfma_f32_16x16x32_bf16 v[34:37], v[192:195], v[240:243], v[34:37]
	v_mfma_f32_16x16x32_bf16 v[30:33], v[196:199], v[212:215], v[30:33]
	s_add_i32 s79, s79, 2
	v_mfma_f32_16x16x32_bf16 v[26:29], v[204:207], v[212:215], v[26:29]
	s_add_u32 s77, s77, 0x100
	v_mfma_f32_16x16x32_bf16 v[22:25], v[196:199], v[220:223], v[22:25]
	s_addc_u32 s78, s78, 0
	v_mfma_f32_16x16x32_bf16 v[18:21], v[204:207], v[220:223], v[18:21]
	s_add_u32 s60, s60, 0x10000
	v_mfma_f32_16x16x32_bf16 v[14:17], v[196:199], v[228:231], v[14:17]
	s_addc_u32 s61, s61, 0
	v_mfma_f32_16x16x32_bf16 v[10:13], v[204:207], v[228:231], v[10:13]
	s_cmp_gt_u32 s79, 13
	v_mfma_f32_16x16x32_bf16 v[6:9], v[196:199], v[236:239], v[6:9]
	v_mfma_f32_16x16x32_bf16 v[2:5], v[204:207], v[236:239], v[2:5]
	v_mfma_f32_16x16x32_bf16 v[30:33], v[200:203], v[216:219], v[30:33]
	v_mfma_f32_16x16x32_bf16 v[26:29], v[208:211], v[216:219], v[26:29]
	v_mfma_f32_16x16x32_bf16 v[22:25], v[200:203], v[224:227], v[22:25]
	v_mfma_f32_16x16x32_bf16 v[18:21], v[208:211], v[224:227], v[18:21]
	v_mfma_f32_16x16x32_bf16 v[14:17], v[200:203], v[232:235], v[14:17]
	v_mfma_f32_16x16x32_bf16 v[10:13], v[208:211], v[232:235], v[10:13]
	v_mfma_f32_16x16x32_bf16 v[6:9], v[200:203], v[240:243], v[6:9]
	v_mfma_f32_16x16x32_bf16 v[2:5], v[208:211], v[240:243], v[2:5]
	s_barrier
	v_lshl_add_u64 v[130:131], v[130:131], 0, s[50:51]
	s_cbranch_scc0 .LBB0_1983
	s_and_b64 vcc, exec, s[38:39]
	s_cbranch_vccz .LBB0_1986
	s_barrier

; #define PG8_STAGE(bufoff, gbase, voff) do { _Pragma("unroll") for (int _i = 0; _i < 2; ++_i) \
;         __builtin_amdgcn_global_load_lds((const unsigned*)((const char*)(gbase) + (voff)[_i]), (PG8_LAS unsigned*)(lds + (bufoff) + ldsw + _i * 8192), 16, 0, 0); } while (0)
; #define PG8_LDA(dst, b, h) do { _Pragma("unroll") for (int m = 0; m < 4; ++m) _Pragma("unroll") for (int k = 0; k < 2; ++k) dst[m][k] = *(const PG8_LAS bf16x8*)(lds + PG8_SA(b, h) + aoff + m * 2048 + k * 1024); } while (0)
; #define PG8_LDB(dst, b, h) do { _Pragma("unroll") for (int n = 0; n < 2; ++n) _Pragma("unroll") for (int k = 0; k < 2; ++k) dst[n][k] = *(const PG8_LAS bf16x8*)(lds + PG8_SB(b, h) + boff + n * 2048 + k * 1024); } while (0)
; #define PG8_MMA(ai, bj, At, Bt) do { __builtin_amdgcn_s_setprio(1); _Pragma("unroll") for (int m = 0; m < 4; ++m) _Pragma("unroll") for (int n = 0; n < 2; ++n) _Pragma("unroll") for (int k = 0; k < 2; ++k) \
;         acc[ai][bj][m][n] = __builtin_amdgcn_mfma_f32_16x16x32_bf16(Bt[n][k], At[m][k], acc[ai][bj][m][n], 0, 0, 0); __builtin_amdgcn_s_setprio(0); } while (0)
; #define PG8_WAIT_V(n) asm volatile("s_waitcnt vmcnt(" #n ")" ::: "memory")
; #define PG8_WAIT_L(n) asm volatile("s_waitcnt lgkmcnt(" #n ")" ::: "memory")
; #define PG8_BAR __builtin_amdgcn_s_barrier()
; #define PG8_SCHED __builtin_amdgcn_sched_barrier(0)
; template <class Epi, bool ALIGN_EPI, bool ABLK = false>
; __device__ __forceinline__ void gemm_phase(PG8_LAS unsigned char* lds, const Gemm g, const StaticOrder& S, const Epi& E) {
;     ...
;             PG8_LDB(B0, 0, 0); PG8_LDB(B1, 0, 1); PG8_SCHED; PG8_LDA(At, 0, 0); PG8_STAGE(PG8_SA(1, 1), a1 + hstepA, voffA);
;             PG8_WAIT_V(8); PG8_WAIT_L(0); PG8_BAR; PG8_MMA(0, 0, At, B0); PG8_MMA(0, 1, At, B1); PG8_BAR; PG8_SCHED;
;             PG8_LDA(At, 0, 1); PG8_STAGE(PG8_SB(0, 0), b2, voffB); PG8_STAGE(PG8_SB(0, 1), b2 + hstepB, voffB); PG8_STAGE(PG8_SA(0, 0), a2, voffA);
;             PG8_WAIT_V(8); PG8_WAIT_L(0); PG8_BAR; PG8_MMA(1, 0, At, B0); PG8_MMA(1, 1, At, B1); PG8_BAR; PG8_SCHED;
;             PG8_LDB(B0, 1, 0); PG8_LDB(B1, 1, 1); PG8_SCHED; PG8_LDA(At, 1, 0); PG8_STAGE(PG8_SA(0, 1), a2 + hstepA, voffA);
.LBB0_2105:
	v_add_u32_e32 v3, s64, v239
	ds_read_b128 v[134:137], v3
	ds_read_b128 v[138:141], v3 offset:1024
	ds_read_b128 v[142:145], v3 offset:2048
	ds_read_b128 v[146:149], v3 offset:3072
	v_add_u32_e32 v3, s65, v239
	ds_read_b128 v[150:153], v3
	ds_read_b128 v[154:157], v3 offset:1024
	ds_read_b128 v[158:161], v3 offset:2048
	ds_read_b128 v[162:165], v3 offset:3072
	s_add_u32 s48, s6, 0xfffc0080
	s_addc_u32 s49, s7, -1
	s_cmp_eq_u32 s73, 12
	s_cselect_b32 s51, s43, s49
	s_cselect_b32 s50, s69, s48
	s_cselect_b32 s49, s41, s72
	s_cselect_b32 s48, s70, s71
	v_lshl_add_u64 v[4:5], s[6:7], 0, v[218:219]
	s_add_i32 m0, s37, 0xc000
	ds_read_b128 v[166:169], v240
	ds_read_b128 v[170:173], v240 offset:1024
	ds_read_b128 v[174:177], v240 offset:2048
	ds_read_b128 v[178:181], v240 offset:3072
	ds_read_b128 v[182:185], v240 offset:4096
	ds_read_b128 v[186:189], v240 offset:5120
	ds_read_b128 v[190:193], v240 offset:6144
	ds_read_b128 v[226:229], v240 offset:7168
	global_load_lds_dwordx4 v[4:5], off
	v_lshl_add_u64 v[4:5], s[6:7], 0, v[220:221]
	s_add_i32 m0, s37, 0xe000
	s_nop 0
	global_load_lds_dwordx4 v[4:5], off
	s_waitcnt vmcnt(8)
	s_waitcnt lgkmcnt(0)
	s_barrier
	s_waitcnt lgkmcnt(0)
	v_mfma_f32_16x16x32_bf16 v[130:133], v[134:137], v[166:169], v[130:133]
	v_mfma_f32_16x16x32_bf16 v[126:129], v[142:145], v[166:169], v[126:129]
	v_mfma_f32_16x16x32_bf16 v[122:125], v[134:137], v[174:177], v[122:125]
	v_mfma_f32_16x16x32_bf16 v[118:121], v[142:145], v[174:177], v[118:121]
	v_mfma_f32_16x16x32_bf16 v[114:117], v[134:137], v[182:185], v[114:117]
	v_mfma_f32_16x16x32_bf16 v[110:113], v[142:145], v[182:185], v[110:113]
	v_mfma_f32_16x16x32_bf16 v[106:109], v[134:137], v[190:193], v[106:109]
	v_mfma_f32_16x16x32_bf16 v[102:105], v[142:145], v[190:193], v[102:105]
	v_mfma_f32_16x16x32_bf16 v[130:133], v[138:141], v[170:173], v[130:133]
	v_mfma_f32_16x16x32_bf16 v[126:129], v[146:149], v[170:173], v[126:129]
	v_mfma_f32_16x16x32_bf16 v[122:125], v[138:141], v[178:181], v[122:125]
	v_mfma_f32_16x16x32_bf16 v[118:121], v[146:149], v[178:181], v[118:121]
	v_mfma_f32_16x16x32_bf16 v[114:117], v[138:141], v[186:189], v[114:117]
	v_mfma_f32_16x16x32_bf16 v[110:113], v[146:149], v[186:189], v[110:113]
	v_mfma_f32_16x16x32_bf16 v[106:109], v[138:141], v[226:229], v[106:109]
	v_mfma_f32_16x16x32_bf16 v[102:105], v[146:149], v[226:229], v[102:105]
	v_mfma_f32_16x16x32_bf16 v[98:101], v[150:153], v[166:169], v[98:101]
	s_add_i32 s74, s64, s54
	v_mfma_f32_16x16x32_bf16 v[94:97], v[158:161], v[166:169], v[94:97]
	s_mov_b32 m0, s74
	v_mfma_f32_16x16x32_bf16 v[90:93], v[150:153], v[174:177], v[90:93]
	v_mfma_f32_16x16x32_bf16 v[86:89], v[158:161], v[174:177], v[86:89]
	v_mfma_f32_16x16x32_bf16 v[82:85], v[150:153], v[182:185], v[82:85]
	v_mfma_f32_16x16x32_bf16 v[78:81], v[158:161], v[182:185], v[78:81]
	v_mfma_f32_16x16x32_bf16 v[74:77], v[150:153], v[190:193], v[74:77]
	v_mfma_f32_16x16x32_bf16 v[70:73], v[158:161], v[190:193], v[70:73]
	v_mfma_f32_16x16x32_bf16 v[98:101], v[154:157], v[170:173], v[98:101]
	v_mfma_f32_16x16x32_bf16 v[94:97], v[162:165], v[170:173], v[94:97]
	v_mfma_f32_16x16x32_bf16 v[90:93], v[154:157], v[178:181], v[90:93]
	v_mfma_f32_16x16x32_bf16 v[86:89], v[162:165], v[178:181], v[86:89]
	v_mfma_f32_16x16x32_bf16 v[82:85], v[154:157], v[186:189], v[82:85]
	v_mfma_f32_16x16x32_bf16 v[78:81], v[162:165], v[186:189], v[78:81]
	v_mfma_f32_16x16x32_bf16 v[74:77], v[154:157], v[226:229], v[74:77]
	v_mfma_f32_16x16x32_bf16 v[70:73], v[162:165], v[226:229], v[70:73]
	s_barrier
	v_lshl_add_u64 v[230:231], s[48:49], 0, v[196:197]
	ds_read_b128 v[166:169], v240 offset:16384
	ds_read_b128 v[170:173], v240 offset:17408
	ds_read_b128 v[174:177], v240 offset:18432
	ds_read_b128 v[178:181], v240 offset:19456
	ds_read_b128 v[182:185], v240 offset:20480
	ds_read_b128 v[186:189], v240 offset:21504
	ds_read_b128 v[190:193], v240 offset:22528
	ds_read_b128 v[226:229], v240 offset:23552
	global_load_lds_dwordx4 v[230:231], off
	s_add_i32 m0, s74, 0x2000
	s_add_u32 s74, s48, 0x80000
	v_lshl_add_u64 v[242:243], s[48:49], 0, v[200:201]
	s_addc_u32 s75, s49, 0
	s_add_i32 s76, s65, s54
	global_load_lds_dwordx4 v[242:243], off
	v_lshl_add_u64 v[4:5], s[74:75], 0, v[196:197]
	s_mov_b32 m0, s76
	v_lshl_add_u64 v[244:245], s[50:51], 0, v[194:195]
	global_load_lds_dwordx4 v[4:5], off
	v_lshl_add_u64 v[4:5], s[74:75], 0, v[200:201]
	s_add_i32 m0, s76, 0x2000
	v_lshl_add_u64 v[246:247], s[50:51], 0, v[198:199]
	global_load_lds_dwordx4 v[4:5], off
	s_mov_b32 m0, s37
	s_nop 0
	global_load_lds_dwordx4 v[244:245], off
	s_mov_b32 m0, s39
	s_nop 0
	global_load_lds_dwordx4 v[246:247], off
	s_waitcnt vmcnt(8)
	s_waitcnt lgkmcnt(0)
	s_barrier
; #define PG8_STAGE(bufoff, gbase, voff) do { _Pragma("unroll") for (int _i = 0; _i < 2; ++_i) \
;         __builtin_amdgcn_global_load_lds((const unsigned*)((const char*)(gbase) + (voff)[_i]), (PG8_LAS unsigned*)(lds + (bufoff) + ldsw + _i * 8192), 16, 0, 0); } while (0)
; #define PG8_LDA(dst, b, h) do { _Pragma("unroll") for (int m = 0; m < 4; ++m) _Pragma("unroll") for (int k = 0; k < 2; ++k) dst[m][k] = *(const PG8_LAS bf16x8*)(lds + PG8_SA(b, h) + aoff + m * 2048 + k * 1024); } while (0)
; #define PG8_LDB(dst, b, h) do { _Pragma("unroll") for (int n = 0; n < 2; ++n) _Pragma("unroll") for (int k = 0; k < 2; ++k) dst[n][k] = *(const PG8_LAS bf16x8*)(lds + PG8_SB(b, h) + boff + n * 2048 + k * 1024); } while (0)
; #define PG8_MMA(ai, bj, At, Bt) do { __builtin_amdgcn_s_setprio(1); _Pragma("unroll") for (int m = 0; m < 4; ++m) _Pragma("unroll") for (int n = 0; n < 2; ++n) _Pragma("unroll") for (int k = 0; k < 2; ++k) \
;         acc[ai][bj][m][n] = __builtin_amdgcn_mfma_f32_16x16x32_bf16(Bt[n][k], At[m][k], acc[ai][bj][m][n], 0, 0, 0); __builtin_amdgcn_s_setprio(0); } while (0)
; #define PG8_WAIT_V(n) asm volatile("s_waitcnt vmcnt(" #n ")" ::: "memory")
; #define PG8_WAIT_L(n) asm volatile("s_waitcnt lgkmcnt(" #n ")" ::: "memory")
; #define PG8_BAR __builtin_amdgcn_s_barrier()
; #define PG8_SCHED __builtin_amdgcn_sched_barrier(0)
; template <class Epi, bool ALIGN_EPI, bool ABLK = false>
; __device__ __forceinline__ void gemm_phase(PG8_LAS unsigned char* lds, const Gemm g, const StaticOrder& S, const Epi& E) {
;     ...
;             PG8_WAIT_V(8); PG8_WAIT_L(0); PG8_BAR; PG8_MMA(0, 0, At, B0); PG8_MMA(0, 1, At, B1); PG8_BAR; PG8_SCHED;
;             PG8_LDA(At, 0, 1); PG8_STAGE(PG8_SB(0, 0), b2, voffB); PG8_STAGE(PG8_SB(0, 1), b2 + hstepB, voffB); PG8_STAGE(PG8_SA(0, 0), a2, voffA);
;             PG8_WAIT_V(8); PG8_WAIT_L(0); PG8_BAR; PG8_MMA(1, 0, At, B0); PG8_MMA(1, 1, At, B1); PG8_BAR; PG8_SCHED;
;             PG8_LDB(B0, 1, 0); PG8_LDB(B1, 1, 1); PG8_SCHED; PG8_LDA(At, 1, 0); PG8_STAGE(PG8_SA(0, 1), a2 + hstepA, voffA);
;             PG8_WAIT_V(8); PG8_WAIT_L(0); PG8_BAR; PG8_MMA(0, 0, At, B0); PG8_MMA(0, 1, At, B1); PG8_BAR; PG8_SCHED;
	s_waitcnt lgkmcnt(0)
	v_mfma_f32_16x16x32_bf16 v[66:69], v[134:137], v[166:169], v[66:69]
	v_mfma_f32_16x16x32_bf16 v[62:65], v[142:145], v[166:169], v[62:65]
	v_mfma_f32_16x16x32_bf16 v[58:61], v[134:137], v[174:177], v[58:61]
	v_mfma_f32_16x16x32_bf16 v[54:57], v[142:145], v[174:177], v[54:57]
	v_mfma_f32_16x16x32_bf16 v[50:53], v[134:137], v[182:185], v[50:53]
	v_mfma_f32_16x16x32_bf16 v[46:49], v[142:145], v[182:185], v[46:49]
	v_mfma_f32_16x16x32_bf16 v[42:45], v[134:137], v[190:193], v[42:45]
	v_mfma_f32_16x16x32_bf16 v[38:41], v[142:145], v[190:193], v[38:41]
	v_mfma_f32_16x16x32_bf16 v[66:69], v[138:141], v[170:173], v[66:69]
	v_mfma_f32_16x16x32_bf16 v[62:65], v[146:149], v[170:173], v[62:65]
	v_mfma_f32_16x16x32_bf16 v[58:61], v[138:141], v[178:181], v[58:61]
	v_mfma_f32_16x16x32_bf16 v[54:57], v[146:149], v[178:181], v[54:57]
	v_mfma_f32_16x16x32_bf16 v[50:53], v[138:141], v[186:189], v[50:53]
	v_mfma_f32_16x16x32_bf16 v[46:49], v[146:149], v[186:189], v[46:49]
	v_mfma_f32_16x16x32_bf16 v[42:45], v[138:141], v[226:229], v[42:45]
	v_mfma_f32_16x16x32_bf16 v[38:41], v[146:149], v[226:229], v[38:41]
	v_mfma_f32_16x16x32_bf16 v[34:37], v[150:153], v[166:169], v[34:37]
	s_add_i32 s74, 0, 0x18000
	v_mfma_f32_16x16x32_bf16 v[30:33], v[158:161], v[166:169], v[30:33]
	s_add_i32 s75, 0, 0x1c000
	v_mfma_f32_16x16x32_bf16 v[26:29], v[150:153], v[174:177], v[26:29]
	v_mfma_f32_16x16x32_bf16 v[22:25], v[158:161], v[174:177], v[22:25]
	v_mfma_f32_16x16x32_bf16 v[18:21], v[150:153], v[182:185], v[18:21]
	v_mfma_f32_16x16x32_bf16 v[14:17], v[158:161], v[182:185], v[14:17]
	v_mfma_f32_16x16x32_bf16 v[10:13], v[150:153], v[190:193], v[10:13]
	v_mfma_f32_16x16x32_bf16 v[4:7], v[158:161], v[190:193], v[6:9]
	v_mfma_f32_16x16x32_bf16 v[34:37], v[154:157], v[170:173], v[34:37]
	v_mfma_f32_16x16x32_bf16 v[30:33], v[162:165], v[170:173], v[30:33]
	v_mfma_f32_16x16x32_bf16 v[26:29], v[154:157], v[178:181], v[26:29]
	v_mfma_f32_16x16x32_bf16 v[22:25], v[162:165], v[178:181], v[22:25]
	v_mfma_f32_16x16x32_bf16 v[18:21], v[154:157], v[186:189], v[18:21]
	v_mfma_f32_16x16x32_bf16 v[14:17], v[162:165], v[186:189], v[14:17]
	v_mfma_f32_16x16x32_bf16 v[10:13], v[154:157], v[226:229], v[10:13]
	v_mfma_f32_16x16x32_bf16 v[4:7], v[162:165], v[226:229], v[4:7]
	s_barrier
	v_add_u32_e32 v3, s74, v239
	ds_read_b128 v[134:137], v3
	ds_read_b128 v[138:141], v3 offset:1024
	ds_read_b128 v[142:145], v3 offset:2048
	ds_read_b128 v[146:149], v3 offset:3072
	v_add_u32_e32 v3, s75, v239
	ds_read_b128 v[150:153], v3
	ds_read_b128 v[154:157], v3 offset:1024
	ds_read_b128 v[158:161], v3 offset:2048
	ds_read_b128 v[162:165], v3 offset:3072
	s_add_u32 s50, s50, 0x40000
	s_addc_u32 s51, s51, 0
	s_mov_b32 m0, s55
	v_lshl_add_u64 v[8:9], s[50:51], 0, v[194:195]
	ds_read_b128 v[166:169], v240 offset:32768
	ds_read_b128 v[170:173], v240 offset:33792
	ds_read_b128 v[174:177], v240 offset:34816
	ds_read_b128 v[178:181], v240 offset:35840
	ds_read_b128 v[182:185], v240 offset:36864
	ds_read_b128 v[186:189], v240 offset:37888
	ds_read_b128 v[190:193], v240 offset:38912
	ds_read_b128 v[226:229], v240 offset:39936
	global_load_lds_dwordx4 v[8:9], off
	v_lshl_add_u64 v[8:9], s[50:51], 0, v[198:199]
	s_mov_b32 m0, s56
	s_nop 0
	global_load_lds_dwordx4 v[8:9], off
	s_waitcnt vmcnt(8)
	s_waitcnt lgkmcnt(0)
	s_barrier
	s_waitcnt lgkmcnt(0)
	v_mfma_f32_16x16x32_bf16 v[130:133], v[134:137], v[166:169], v[130:133]
	v_mfma_f32_16x16x32_bf16 v[126:129], v[142:145], v[166:169], v[126:129]
	v_mfma_f32_16x16x32_bf16 v[122:125], v[134:137], v[174:177], v[122:125]
	v_mfma_f32_16x16x32_bf16 v[118:121], v[142:145], v[174:177], v[118:121]
	v_mfma_f32_16x16x32_bf16 v[114:117], v[134:137], v[182:185], v[114:117]
	v_mfma_f32_16x16x32_bf16 v[110:113], v[142:145], v[182:185], v[110:113]
	v_mfma_f32_16x16x32_bf16 v[106:109], v[134:137], v[190:193], v[106:109]
	v_mfma_f32_16x16x32_bf16 v[102:105], v[142:145], v[190:193], v[102:105]
	v_mfma_f32_16x16x32_bf16 v[130:133], v[138:141], v[170:173], v[130:133]
	v_mfma_f32_16x16x32_bf16 v[126:129], v[146:149], v[170:173], v[126:129]
	v_mfma_f32_16x16x32_bf16 v[122:125], v[138:141], v[178:181], v[122:125]
	v_mfma_f32_16x16x32_bf16 v[118:121], v[146:149], v[178:181], v[118:121]
	v_mfma_f32_16x16x32_bf16 v[114:117], v[138:141], v[186:189], v[114:117]
	v_mfma_f32_16x16x32_bf16 v[110:113], v[146:149], v[186:189], v[110:113]
	v_mfma_f32_16x16x32_bf16 v[106:109], v[138:141], v[226:229], v[106:109]
	v_mfma_f32_16x16x32_bf16 v[102:105], v[146:149], v[226:229], v[102:105]
	v_mfma_f32_16x16x32_bf16 v[98:101], v[150:153], v[166:169], v[98:101]
	s_add_i32 s50, s74, s54
	v_mfma_f32_16x16x32_bf16 v[94:97], v[158:161], v[166:169], v[94:97]
	s_mov_b32 m0, s50
	v_mfma_f32_16x16x32_bf16 v[90:93], v[150:153], v[174:177], v[90:93]
	v_mfma_f32_16x16x32_bf16 v[86:89], v[158:161], v[174:177], v[86:89]
	v_mfma_f32_16x16x32_bf16 v[82:85], v[150:153], v[182:185], v[82:85]
	v_mfma_f32_16x16x32_bf16 v[78:81], v[158:161], v[182:185], v[78:81]
	v_mfma_f32_16x16x32_bf16 v[74:77], v[150:153], v[190:193], v[74:77]
	v_mfma_f32_16x16x32_bf16 v[70:73], v[158:161], v[190:193], v[70:73]
	v_mfma_f32_16x16x32_bf16 v[98:101], v[154:157], v[170:173], v[98:101]
	v_mfma_f32_16x16x32_bf16 v[94:97], v[162:165], v[170:173], v[94:97]
	v_mfma_f32_16x16x32_bf16 v[90:93], v[154:157], v[178:181], v[90:93]
	v_mfma_f32_16x16x32_bf16 v[86:89], v[162:165], v[178:181], v[86:89]
	v_mfma_f32_16x16x32_bf16 v[82:85], v[154:157], v[186:189], v[82:85]
	v_mfma_f32_16x16x32_bf16 v[78:81], v[162:165], v[186:189], v[78:81]
	v_mfma_f32_16x16x32_bf16 v[74:77], v[154:157], v[226:229], v[74:77]
	v_mfma_f32_16x16x32_bf16 v[70:73], v[162:165], v[226:229], v[70:73]
	s_barrier
; #define PG8_STAGE(bufoff, gbase, voff) do { _Pragma("unroll") for (int _i = 0; _i < 2; ++_i) \
;         __builtin_amdgcn_global_load_lds((const unsigned*)((const char*)(gbase) + (voff)[_i]), (PG8_LAS unsigned*)(lds + (bufoff) + ldsw + _i * 8192), 16, 0, 0); } while (0)
; #define PG8_LDA(dst, b, h) do { _Pragma("unroll") for (int m = 0; m < 4; ++m) _Pragma("unroll") for (int k = 0; k < 2; ++k) dst[m][k] = *(const PG8_LAS bf16x8*)(lds + PG8_SA(b, h) + aoff + m * 2048 + k * 1024); } while (0)
; #define PG8_MMA(ai, bj, At, Bt) do { __builtin_amdgcn_s_setprio(1); _Pragma("unroll") for (int m = 0; m < 4; ++m) _Pragma("unroll") for (int n = 0; n < 2; ++n) _Pragma("unroll") for (int k = 0; k < 2; ++k) \
;         acc[ai][bj][m][n] = __builtin_amdgcn_mfma_f32_16x16x32_bf16(Bt[n][k], At[m][k], acc[ai][bj][m][n], 0, 0, 0); __builtin_amdgcn_s_setprio(0); } while (0)
; #define PG8_WAIT_V(n) asm volatile("s_waitcnt vmcnt(" #n ")" ::: "memory")
; #define PG8_WAIT_L(n) asm volatile("s_waitcnt lgkmcnt(" #n ")" ::: "memory")
; #define PG8_BAR __builtin_amdgcn_s_barrier()
; #define PG8_SCHED __builtin_amdgcn_sched_barrier(0)
; template <class Epi, bool ALIGN_EPI, bool ABLK = false>
; __device__ __forceinline__ void gemm_phase(PG8_LAS unsigned char* lds, const Gemm g, const StaticOrder& S, const Epi& E) {
;     ...
;             PG8_LDA(At, 1, 1); PG8_STAGE(PG8_SB(1, 0), b3, voffB); PG8_STAGE(PG8_SB(1, 1), b3 + hstepB, voffB); PG8_STAGE(PG8_SA(1, 0), a3, voffA);
;             PG8_WAIT_V(8); PG8_WAIT_L(0); PG8_BAR; PG8_MMA(1, 0, At, B0); PG8_MMA(1, 1, At, B1); PG8_BAR; PG8_SCHED;
;         }
;         if constexpr (ALIGN_EPI) { if (wr == 0) PG8_BAR; }
	v_lshl_add_u64 v[8:9], v[230:231], 0, s[22:23]
	ds_read_b128 v[166:169], v240 offset:49152
	ds_read_b128 v[170:173], v240 offset:50176
	ds_read_b128 v[174:177], v240 offset:51200
	ds_read_b128 v[178:181], v240 offset:52224
	ds_read_b128 v[182:185], v240 offset:53248
	ds_read_b128 v[186:189], v240 offset:54272
	ds_read_b128 v[190:193], v240 offset:55296
	ds_read_b128 v[226:229], v240 offset:56320
	global_load_lds_dwordx4 v[8:9], off
	s_add_i32 m0, s50, 0x2000
	s_add_u32 s48, s48, 0x80080
	v_lshl_add_u64 v[8:9], v[242:243], 0, s[22:23]
	s_addc_u32 s49, s49, 0
	s_add_i32 s50, s75, s54
	global_load_lds_dwordx4 v[8:9], off
	v_lshl_add_u64 v[8:9], s[48:49], 0, v[196:197]
	s_mov_b32 m0, s50
	s_nop 0
	global_load_lds_dwordx4 v[8:9], off
	v_lshl_add_u64 v[8:9], s[48:49], 0, v[200:201]
	s_add_i32 m0, s50, 0x2000
	s_nop 0
	global_load_lds_dwordx4 v[8:9], off
	v_lshl_add_u64 v[8:9], v[244:245], 0, s[22:23]
	s_mov_b32 m0, s59
	s_nop 0
	global_load_lds_dwordx4 v[8:9], off
	v_lshl_add_u64 v[8:9], v[246:247], 0, s[22:23]
	s_mov_b32 m0, s60
	s_nop 0
	global_load_lds_dwordx4 v[8:9], off
	s_waitcnt vmcnt(8)
	s_waitcnt lgkmcnt(0)
	s_barrier
	s_waitcnt lgkmcnt(0)
	v_mfma_f32_16x16x32_bf16 v[66:69], v[134:137], v[166:169], v[66:69]
	v_mfma_f32_16x16x32_bf16 v[62:65], v[142:145], v[166:169], v[62:65]
	v_mfma_f32_16x16x32_bf16 v[58:61], v[134:137], v[174:177], v[58:61]
	v_mfma_f32_16x16x32_bf16 v[54:57], v[142:145], v[174:177], v[54:57]
	v_mfma_f32_16x16x32_bf16 v[50:53], v[134:137], v[182:185], v[50:53]
	v_mfma_f32_16x16x32_bf16 v[46:49], v[142:145], v[182:185], v[46:49]
	v_mfma_f32_16x16x32_bf16 v[42:45], v[134:137], v[190:193], v[42:45]
	v_mfma_f32_16x16x32_bf16 v[38:41], v[142:145], v[190:193], v[38:41]
	v_mfma_f32_16x16x32_bf16 v[66:69], v[138:141], v[170:173], v[66:69]
	v_mfma_f32_16x16x32_bf16 v[62:65], v[146:149], v[170:173], v[62:65]
	v_mfma_f32_16x16x32_bf16 v[58:61], v[138:141], v[178:181], v[58:61]
	v_mfma_f32_16x16x32_bf16 v[54:57], v[146:149], v[178:181], v[54:57]
	v_mfma_f32_16x16x32_bf16 v[50:53], v[138:141], v[186:189], v[50:53]
	v_mfma_f32_16x16x32_bf16 v[46:49], v[146:149], v[186:189], v[46:49]
	v_mfma_f32_16x16x32_bf16 v[42:45], v[138:141], v[226:229], v[42:45]
	v_mfma_f32_16x16x32_bf16 v[38:41], v[146:149], v[226:229], v[38:41]
	v_mfma_f32_16x16x32_bf16 v[34:37], v[150:153], v[166:169], v[34:37]
	s_add_i32 s73, s73, 2
	v_mfma_f32_16x16x32_bf16 v[30:33], v[158:161], v[166:169], v[30:33]
	s_add_u32 s6, s6, 0x100
	v_mfma_f32_16x16x32_bf16 v[26:29], v[150:153], v[174:177], v[26:29]
	s_addc_u32 s7, s7, 0
	v_mfma_f32_16x16x32_bf16 v[22:25], v[158:161], v[174:177], v[22:25]
	s_add_u32 s71, s71, 0x100
	v_mfma_f32_16x16x32_bf16 v[18:21], v[150:153], v[182:185], v[18:21]
	s_addc_u32 s72, s72, 0
	v_mfma_f32_16x16x32_bf16 v[14:17], v[158:161], v[182:185], v[14:17]
	s_cmp_gt_u32 s73, 13
	v_mfma_f32_16x16x32_bf16 v[8:11], v[150:153], v[190:193], v[10:13]
	v_mfma_f32_16x16x32_bf16 v[4:7], v[158:161], v[190:193], v[4:7]
	v_mfma_f32_16x16x32_bf16 v[34:37], v[154:157], v[170:173], v[34:37]
	v_mfma_f32_16x16x32_bf16 v[30:33], v[162:165], v[170:173], v[30:33]
	v_mfma_f32_16x16x32_bf16 v[26:29], v[154:157], v[178:181], v[26:29]
	v_mfma_f32_16x16x32_bf16 v[22:25], v[162:165], v[178:181], v[22:25]
	v_mfma_f32_16x16x32_bf16 v[18:21], v[154:157], v[186:189], v[18:21]
	v_mfma_f32_16x16x32_bf16 v[14:17], v[162:165], v[186:189], v[14:17]
	v_mfma_f32_16x16x32_bf16 v[10:13], v[154:157], v[226:229], v[8:11]
	v_mfma_f32_16x16x32_bf16 v[6:9], v[162:165], v[226:229], v[4:7]
	s_barrier
	s_cbranch_scc0 .LBB0_2105
	s_and_b64 vcc, exec, s[24:25]
	s_cbranch_vccz .LBB0_2108
	s_barrier

; #define PG8_STAGE(bufoff, gbase, voff) do { _Pragma("unroll") for (int _i = 0; _i < 2; ++_i) \
;         __builtin_amdgcn_global_load_lds((const unsigned*)((const char*)(gbase) + (voff)[_i]), (PG8_LAS unsigned*)(lds + (bufoff) + ldsw + _i * 8192), 16, 0, 0); } while (0)
; #define PG8_LDA(dst, b, h) do { _Pragma("unroll") for (int m = 0; m < 4; ++m) _Pragma("unroll") for (int k = 0; k < 2; ++k) dst[m][k] = *(const PG8_LAS bf16x8*)(lds + PG8_SA(b, h) + aoff + m * 2048 + k * 1024); } while (0)
; #define PG8_LDB(dst, b, h) do { _Pragma("unroll") for (int n = 0; n < 2; ++n) _Pragma("unroll") for (int k = 0; k < 2; ++k) dst[n][k] = *(const PG8_LAS bf16x8*)(lds + PG8_SB(b, h) + boff + n * 2048 + k * 1024); } while (0)
; #define PG8_MMA(ai, bj, At, Bt) do { __builtin_amdgcn_s_setprio(1); _Pragma("unroll") for (int m = 0; m < 4; ++m) _Pragma("unroll") for (int n = 0; n < 2; ++n) _Pragma("unroll") for (int k = 0; k < 2; ++k) \
;         acc[ai][bj][m][n] = __builtin_amdgcn_mfma_f32_16x16x32_bf16(Bt[n][k], At[m][k], acc[ai][bj][m][n], 0, 0, 0); __builtin_amdgcn_s_setprio(0); } while (0)
; #define PG8_WAIT_V(n) asm volatile("s_waitcnt vmcnt(" #n ")" ::: "memory")
; template <class Epi, bool ALIGN_EPI, bool ABLK = false>
; __device__ __forceinline__ void gemm_phase(PG8_LAS unsigned char* lds, const Gemm g, const StaticOrder& S, const Epi& E) {
;     ...
;         const bool has_next = S.next(ui + 1, nxt);
;         const char* nA = has_next ? PG8_ABASE(nxt) : cA; const char* nB = has_next ? PG8_BBASE(nxt) : cB;
;         for (int t = 0; t < nt; t += 2) {
;             const bool last = (t == nt - 2);
;             const char* a1 = cA + (size_t)(t + 1) * kstepA;
;             const char* a2 = last ? nA : cA + (size_t)(t + 2) * kstepA; const char* b2 = last ? nB : cB + (size_t)(t + 2) * kstepB;
;             const char* a3 = a2 + kstepA; const char* b3 = b2 + kstepB;
;             PG8_LDB(B0, 0, 0); PG8_LDB(B1, 0, 1); PG8_SCHED; PG8_LDA(At, 0, 0); PG8_STAGE(PG8_SA(1, 1), a1 + hstepA, voffA);
;             PG8_WAIT_V(8); PG8_WAIT_L(0); PG8_BAR; PG8_MMA(0, 0, At, B0); PG8_MMA(0, 1, At, B1); PG8_BAR; PG8_SCHED;
;             PG8_LDA(At, 0, 1); PG8_STAGE(PG8_SB(0, 0), b2, voffB); PG8_STAGE(PG8_SB(0, 1), b2 + hstepB, voffB); PG8_STAGE(PG8_SA(0, 0), a2, voffA);
;             PG8_WAIT_V(8); PG8_WAIT_L(0); PG8_BAR; PG8_MMA(1, 0, At, B0); PG8_MMA(1, 1, At, B1); PG8_BAR; PG8_SCHED;
.LBB0_2289:
	ds_read_b128 v[102:105], v232
	ds_read_b128 v[110:113], v232 offset:1024
	ds_read_b128 v[122:125], v232 offset:2048
	ds_read_b128 v[134:137], v232 offset:3072
	ds_read_b128 v[146:149], v233
	ds_read_b128 v[150:153], v233 offset:1024
	ds_read_b128 v[154:157], v233 offset:2048
	ds_read_b128 v[158:161], v233 offset:3072
	s_cmp_eq_u32 s82, 12
	s_cselect_b32 s85, s51, s57
	s_cselect_b32 s84, s60, s56
	s_cselect_b32 s59, s49, s81
	s_cselect_b32 s58, s61, s80
	s_movk_i32 s86, 0xc000
	v_lshl_add_u64 v[212:213], s[56:57], 0, v[186:187]
	s_mov_b32 s87, -1
	v_lshl_add_u64 v[244:245], v[212:213], 0, s[86:87]
	s_movk_i32 s86, 0xe000
	s_add_i32 m0, s9, 0xc000
	s_mov_b32 s87, -1
	ds_read_b128 v[162:165], v234
	ds_read_b128 v[166:169], v234 offset:1024
	ds_read_b128 v[170:173], v234 offset:2048
	ds_read_b128 v[174:177], v234 offset:3072
	ds_read_b128 v[178:181], v234 offset:4096
	ds_read_b128 v[182:185], v234 offset:5120
	ds_read_b128 v[236:239], v234 offset:6144
	ds_read_b128 v[240:243], v234 offset:7168
	global_load_lds_dwordx4 v[244:245], off
	v_lshl_add_u64 v[212:213], v[212:213], 0, s[86:87]
	s_add_i32 m0, s9, 0xe000
	s_nop 0
	global_load_lds_dwordx4 v[212:213], off
	s_waitcnt vmcnt(8)
	s_waitcnt lgkmcnt(0)
	s_barrier
	s_waitcnt lgkmcnt(0)
	v_mfma_f32_16x16x32_bf16 v[142:145], v[102:105], v[162:165], v[142:145]
	v_mfma_f32_16x16x32_bf16 v[138:141], v[122:125], v[162:165], v[138:141]
	v_mfma_f32_16x16x32_bf16 v[118:121], v[102:105], v[170:173], v[118:121]
	v_mfma_f32_16x16x32_bf16 v[114:117], v[122:125], v[170:173], v[114:117]
	v_mfma_f32_16x16x32_bf16 v[94:97], v[102:105], v[178:181], v[94:97]
	v_mfma_f32_16x16x32_bf16 v[90:93], v[122:125], v[178:181], v[90:93]
	v_mfma_f32_16x16x32_bf16 v[78:81], v[102:105], v[236:239], v[78:81]
	v_mfma_f32_16x16x32_bf16 v[74:77], v[122:125], v[236:239], v[74:77]
	v_mfma_f32_16x16x32_bf16 v[142:145], v[110:113], v[166:169], v[142:145]
	v_mfma_f32_16x16x32_bf16 v[138:141], v[134:137], v[166:169], v[138:141]
	v_mfma_f32_16x16x32_bf16 v[118:121], v[110:113], v[174:177], v[118:121]
	v_mfma_f32_16x16x32_bf16 v[114:117], v[134:137], v[174:177], v[114:117]
	v_mfma_f32_16x16x32_bf16 v[94:97], v[110:113], v[182:185], v[94:97]
	v_mfma_f32_16x16x32_bf16 v[90:93], v[134:137], v[182:185], v[90:93]
	v_mfma_f32_16x16x32_bf16 v[78:81], v[110:113], v[240:243], v[78:81]
	v_mfma_f32_16x16x32_bf16 v[74:77], v[134:137], v[240:243], v[74:77]
	v_mfma_f32_16x16x32_bf16 v[130:133], v[146:149], v[162:165], v[130:133]
	s_add_i32 s83, s77, s65
	v_mfma_f32_16x16x32_bf16 v[126:129], v[154:157], v[162:165], v[126:129]
	s_mov_b32 m0, s83
	v_mfma_f32_16x16x32_bf16 v[106:109], v[146:149], v[170:173], v[106:109]
	v_mfma_f32_16x16x32_bf16 v[98:101], v[154:157], v[170:173], v[98:101]
	v_mfma_f32_16x16x32_bf16 v[86:89], v[146:149], v[178:181], v[86:89]
	v_mfma_f32_16x16x32_bf16 v[82:85], v[154:157], v[178:181], v[82:85]
	v_mfma_f32_16x16x32_bf16 v[70:73], v[146:149], v[236:239], v[70:73]
	v_mfma_f32_16x16x32_bf16 v[66:69], v[154:157], v[236:239], v[66:69]
	v_mfma_f32_16x16x32_bf16 v[130:133], v[150:153], v[166:169], v[130:133]
	v_mfma_f32_16x16x32_bf16 v[126:129], v[158:161], v[166:169], v[126:129]
	v_mfma_f32_16x16x32_bf16 v[106:109], v[150:153], v[174:177], v[106:109]
	v_mfma_f32_16x16x32_bf16 v[98:101], v[158:161], v[174:177], v[98:101]
	v_mfma_f32_16x16x32_bf16 v[86:89], v[150:153], v[182:185], v[86:89]
	v_mfma_f32_16x16x32_bf16 v[82:85], v[158:161], v[182:185], v[82:85]
	v_mfma_f32_16x16x32_bf16 v[70:73], v[150:153], v[240:243], v[70:73]
	v_mfma_f32_16x16x32_bf16 v[66:69], v[158:161], v[240:243], v[66:69]
	s_barrier
	v_lshl_add_u64 v[212:213], s[58:59], 0, v[188:189]
	ds_read_b128 v[162:165], v234 offset:16384
	ds_read_b128 v[166:169], v234 offset:17408
	ds_read_b128 v[170:173], v234 offset:18432
	ds_read_b128 v[174:177], v234 offset:19456
	ds_read_b128 v[178:181], v234 offset:20480
	ds_read_b128 v[182:185], v234 offset:21504
	ds_read_b128 v[236:239], v234 offset:22528
	ds_read_b128 v[240:243], v234 offset:23552
	global_load_lds_dwordx4 v[212:213], off
	s_add_i32 m0, s83, 0x2000
	s_add_u32 s86, s58, 0x40000
	v_lshl_add_u64 v[244:245], s[58:59], 0, v[190:191]
	s_addc_u32 s87, s59, 0
	s_add_i32 s83, s78, s65
	global_load_lds_dwordx4 v[244:245], off
	v_lshl_add_u64 v[246:247], s[86:87], 0, v[188:189]
	s_mov_b32 m0, s83
	s_nop 0
	global_load_lds_dwordx4 v[246:247], off
	v_lshl_add_u64 v[246:247], s[86:87], 0, v[190:191]
	s_add_i32 m0, s83, 0x2000
	s_nop 0
	global_load_lds_dwordx4 v[246:247], off
	v_lshl_add_u64 v[246:247], s[84:85], 0, v[186:187]
	s_mov_b32 m0, s9
	v_lshl_add_u64 v[248:249], v[246:247], 0, s[10:11]
	global_load_lds_dwordx4 v[246:247], off
	s_mov_b32 m0, s66
	s_nop 0
	global_load_lds_dwordx4 v[248:249], off
	s_waitcnt vmcnt(8)
	s_waitcnt lgkmcnt(0)
	s_barrier
; #define PG8_STAGE(bufoff, gbase, voff) do { _Pragma("unroll") for (int _i = 0; _i < 2; ++_i) \
;         __builtin_amdgcn_global_load_lds((const unsigned*)((const char*)(gbase) + (voff)[_i]), (PG8_LAS unsigned*)(lds + (bufoff) + ldsw + _i * 8192), 16, 0, 0); } while (0)
; #define PG8_LDA(dst, b, h) do { _Pragma("unroll") for (int m = 0; m < 4; ++m) _Pragma("unroll") for (int k = 0; k < 2; ++k) dst[m][k] = *(const PG8_LAS bf16x8*)(lds + PG8_SA(b, h) + aoff + m * 2048 + k * 1024); } while (0)
; #define PG8_LDB(dst, b, h) do { _Pragma("unroll") for (int n = 0; n < 2; ++n) _Pragma("unroll") for (int k = 0; k < 2; ++k) dst[n][k] = *(const PG8_LAS bf16x8*)(lds + PG8_SB(b, h) + boff + n * 2048 + k * 1024); } while (0)
; #define PG8_MMA(ai, bj, At, Bt) do { __builtin_amdgcn_s_setprio(1); _Pragma("unroll") for (int m = 0; m < 4; ++m) _Pragma("unroll") for (int n = 0; n < 2; ++n) _Pragma("unroll") for (int k = 0; k < 2; ++k) \
;         acc[ai][bj][m][n] = __builtin_amdgcn_mfma_f32_16x16x32_bf16(Bt[n][k], At[m][k], acc[ai][bj][m][n], 0, 0, 0); __builtin_amdgcn_s_setprio(0); } while (0)
; #define PG8_WAIT_V(n) asm volatile("s_waitcnt vmcnt(" #n ")" ::: "memory")
; #define PG8_WAIT_L(n) asm volatile("s_waitcnt lgkmcnt(" #n ")" ::: "memory")
; #define PG8_BAR __builtin_amdgcn_s_barrier()
; #define PG8_SCHED __builtin_amdgcn_sched_barrier(0)
; template <class Epi, bool ALIGN_EPI, bool ABLK = false>
; __device__ __forceinline__ void gemm_phase(PG8_LAS unsigned char* lds, const Gemm g, const StaticOrder& S, const Epi& E) {
;     ...
;             PG8_WAIT_V(8); PG8_WAIT_L(0); PG8_BAR; PG8_MMA(1, 0, At, B0); PG8_MMA(1, 1, At, B1); PG8_BAR; PG8_SCHED;
;             PG8_LDB(B0, 1, 0); PG8_LDB(B1, 1, 1); PG8_SCHED; PG8_LDA(At, 1, 0); PG8_STAGE(PG8_SA(0, 1), a2 + hstepA, voffA);
;             PG8_WAIT_V(8); PG8_WAIT_L(0); PG8_BAR; PG8_MMA(0, 0, At, B0); PG8_MMA(0, 1, At, B1); PG8_BAR; PG8_SCHED;
	s_waitcnt lgkmcnt(0)
	v_mfma_f32_16x16x32_bf16 v[62:65], v[102:105], v[162:165], v[62:65]
	v_mfma_f32_16x16x32_bf16 v[58:61], v[122:125], v[162:165], v[58:61]
	v_mfma_f32_16x16x32_bf16 v[46:49], v[102:105], v[170:173], v[46:49]
	v_mfma_f32_16x16x32_bf16 v[42:45], v[122:125], v[170:173], v[42:45]
	v_mfma_f32_16x16x32_bf16 v[30:33], v[102:105], v[178:181], v[30:33]
	v_mfma_f32_16x16x32_bf16 v[26:29], v[122:125], v[178:181], v[26:29]
	v_mfma_f32_16x16x32_bf16 v[14:17], v[102:105], v[236:239], v[14:17]
	v_mfma_f32_16x16x32_bf16 v[10:13], v[122:125], v[236:239], v[10:13]
	v_mfma_f32_16x16x32_bf16 v[62:65], v[110:113], v[166:169], v[62:65]
	v_mfma_f32_16x16x32_bf16 v[58:61], v[134:137], v[166:169], v[58:61]
	v_mfma_f32_16x16x32_bf16 v[46:49], v[110:113], v[174:177], v[46:49]
	v_mfma_f32_16x16x32_bf16 v[42:45], v[134:137], v[174:177], v[42:45]
	v_mfma_f32_16x16x32_bf16 v[30:33], v[110:113], v[182:185], v[30:33]
	v_mfma_f32_16x16x32_bf16 v[26:29], v[134:137], v[182:185], v[26:29]
	v_mfma_f32_16x16x32_bf16 v[14:17], v[110:113], v[240:243], v[14:17]
	v_mfma_f32_16x16x32_bf16 v[10:13], v[134:137], v[240:243], v[10:13]
	v_mfma_f32_16x16x32_bf16 v[54:57], v[146:149], v[162:165], v[54:57]
	s_add_i32 s83, 0, 0x18000
	v_mfma_f32_16x16x32_bf16 v[50:53], v[154:157], v[162:165], v[50:53]
	s_add_i32 s84, 0, 0x1c000
	v_mfma_f32_16x16x32_bf16 v[38:41], v[146:149], v[170:173], v[38:41]
	v_mfma_f32_16x16x32_bf16 v[34:37], v[154:157], v[170:173], v[34:37]
	v_mfma_f32_16x16x32_bf16 v[22:25], v[146:149], v[178:181], v[22:25]
	v_mfma_f32_16x16x32_bf16 v[18:21], v[154:157], v[178:181], v[18:21]
	v_mfma_f32_16x16x32_bf16 v[6:9], v[146:149], v[236:239], v[6:9]
	v_mfma_f32_16x16x32_bf16 v[2:5], v[154:157], v[236:239], v[2:5]
	v_mfma_f32_16x16x32_bf16 v[54:57], v[150:153], v[166:169], v[54:57]
	v_mfma_f32_16x16x32_bf16 v[50:53], v[158:161], v[166:169], v[50:53]
	v_mfma_f32_16x16x32_bf16 v[38:41], v[150:153], v[174:177], v[38:41]
	v_mfma_f32_16x16x32_bf16 v[34:37], v[158:161], v[174:177], v[34:37]
	v_mfma_f32_16x16x32_bf16 v[22:25], v[150:153], v[182:185], v[22:25]
	v_mfma_f32_16x16x32_bf16 v[18:21], v[158:161], v[182:185], v[18:21]
	v_mfma_f32_16x16x32_bf16 v[6:9], v[150:153], v[240:243], v[6:9]
	v_mfma_f32_16x16x32_bf16 v[2:5], v[158:161], v[240:243], v[2:5]
	s_barrier
	v_add_u32_e32 v134, s83, v224
	v_add_u32_e32 v158, s84, v224
	ds_read_b128 v[102:105], v134
	ds_read_b128 v[110:113], v134 offset:1024
	ds_read_b128 v[122:125], v134 offset:2048
	ds_read_b128 v[134:137], v134 offset:3072
	ds_read_b128 v[146:149], v158
	ds_read_b128 v[150:153], v158 offset:1024
	ds_read_b128 v[154:157], v158 offset:2048
	ds_read_b128 v[158:161], v158 offset:3072
	s_mov_b32 m0, s67
	v_lshl_add_u64 v[248:249], v[246:247], 0, s[12:13]
	ds_read_b128 v[162:165], v234 offset:32768
	ds_read_b128 v[166:169], v234 offset:33792
	ds_read_b128 v[170:173], v234 offset:34816
	ds_read_b128 v[174:177], v234 offset:35840
	ds_read_b128 v[178:181], v234 offset:36864
	ds_read_b128 v[182:185], v234 offset:37888
	ds_read_b128 v[236:239], v234 offset:38912
	ds_read_b128 v[240:243], v234 offset:39936
	global_load_lds_dwordx4 v[248:249], off
	v_lshl_add_u64 v[248:249], v[246:247], 0, s[24:25]
	s_mov_b32 m0, s68
	s_nop 0
	global_load_lds_dwordx4 v[248:249], off
	s_waitcnt vmcnt(8)
	s_waitcnt lgkmcnt(0)
	s_barrier
	s_waitcnt lgkmcnt(0)
	v_mfma_f32_16x16x32_bf16 v[142:145], v[102:105], v[162:165], v[142:145]
	v_mfma_f32_16x16x32_bf16 v[138:141], v[122:125], v[162:165], v[138:141]
	v_mfma_f32_16x16x32_bf16 v[118:121], v[102:105], v[170:173], v[118:121]
	v_mfma_f32_16x16x32_bf16 v[114:117], v[122:125], v[170:173], v[114:117]
	v_mfma_f32_16x16x32_bf16 v[94:97], v[102:105], v[178:181], v[94:97]
	v_mfma_f32_16x16x32_bf16 v[90:93], v[122:125], v[178:181], v[90:93]
	v_mfma_f32_16x16x32_bf16 v[78:81], v[102:105], v[236:239], v[78:81]
	v_mfma_f32_16x16x32_bf16 v[74:77], v[122:125], v[236:239], v[74:77]
	v_mfma_f32_16x16x32_bf16 v[142:145], v[110:113], v[166:169], v[142:145]
	v_mfma_f32_16x16x32_bf16 v[138:141], v[134:137], v[166:169], v[138:141]
	v_mfma_f32_16x16x32_bf16 v[118:121], v[110:113], v[174:177], v[118:121]
	v_mfma_f32_16x16x32_bf16 v[114:117], v[134:137], v[174:177], v[114:117]
	v_mfma_f32_16x16x32_bf16 v[94:97], v[110:113], v[182:185], v[94:97]
	v_mfma_f32_16x16x32_bf16 v[90:93], v[134:137], v[182:185], v[90:93]
	v_mfma_f32_16x16x32_bf16 v[78:81], v[110:113], v[240:243], v[78:81]
	v_mfma_f32_16x16x32_bf16 v[74:77], v[134:137], v[240:243], v[74:77]
	v_mfma_f32_16x16x32_bf16 v[130:133], v[146:149], v[162:165], v[130:133]
	s_add_i32 s83, s83, s65
	v_mfma_f32_16x16x32_bf16 v[126:129], v[154:157], v[162:165], v[126:129]
	s_mov_b32 m0, s83
	v_mfma_f32_16x16x32_bf16 v[106:109], v[146:149], v[170:173], v[106:109]
	v_mfma_f32_16x16x32_bf16 v[98:101], v[154:157], v[170:173], v[98:101]
	v_mfma_f32_16x16x32_bf16 v[86:89], v[146:149], v[178:181], v[86:89]
	v_mfma_f32_16x16x32_bf16 v[82:85], v[154:157], v[178:181], v[82:85]
	v_mfma_f32_16x16x32_bf16 v[70:73], v[146:149], v[236:239], v[70:73]
	v_mfma_f32_16x16x32_bf16 v[66:69], v[154:157], v[236:239], v[66:69]
	v_mfma_f32_16x16x32_bf16 v[130:133], v[150:153], v[166:169], v[130:133]
	v_mfma_f32_16x16x32_bf16 v[126:129], v[158:161], v[166:169], v[126:129]
	v_mfma_f32_16x16x32_bf16 v[106:109], v[150:153], v[174:177], v[106:109]
	v_mfma_f32_16x16x32_bf16 v[98:101], v[158:161], v[174:177], v[98:101]
	v_mfma_f32_16x16x32_bf16 v[86:89], v[150:153], v[182:185], v[86:89]
	v_mfma_f32_16x16x32_bf16 v[82:85], v[158:161], v[182:185], v[82:85]
	v_mfma_f32_16x16x32_bf16 v[70:73], v[150:153], v[240:243], v[70:73]
	v_mfma_f32_16x16x32_bf16 v[66:69], v[158:161], v[240:243], v[66:69]
	s_barrier
; #define PG8_STAGE(bufoff, gbase, voff) do { _Pragma("unroll") for (int _i = 0; _i < 2; ++_i) \
;         __builtin_amdgcn_global_load_lds((const unsigned*)((const char*)(gbase) + (voff)[_i]), (PG8_LAS unsigned*)(lds + (bufoff) + ldsw + _i * 8192), 16, 0, 0); } while (0)
; #define PG8_LDA(dst, b, h) do { _Pragma("unroll") for (int m = 0; m < 4; ++m) _Pragma("unroll") for (int k = 0; k < 2; ++k) dst[m][k] = *(const PG8_LAS bf16x8*)(lds + PG8_SA(b, h) + aoff + m * 2048 + k * 1024); } while (0)
; #define PG8_MMA(ai, bj, At, Bt) do { __builtin_amdgcn_s_setprio(1); _Pragma("unroll") for (int m = 0; m < 4; ++m) _Pragma("unroll") for (int n = 0; n < 2; ++n) _Pragma("unroll") for (int k = 0; k < 2; ++k) \
;         acc[ai][bj][m][n] = __builtin_amdgcn_mfma_f32_16x16x32_bf16(Bt[n][k], At[m][k], acc[ai][bj][m][n], 0, 0, 0); __builtin_amdgcn_s_setprio(0); } while (0)
; #define PG8_WAIT_V(n) asm volatile("s_waitcnt vmcnt(" #n ")" ::: "memory")
; #define PG8_WAIT_L(n) asm volatile("s_waitcnt lgkmcnt(" #n ")" ::: "memory")
; #define PG8_BAR __builtin_amdgcn_s_barrier()
; #define PG8_SCHED __builtin_amdgcn_sched_barrier(0)
; template <class Epi, bool ALIGN_EPI, bool ABLK = false>
; __device__ __forceinline__ void gemm_phase(PG8_LAS unsigned char* lds, const Gemm g, const StaticOrder& S, const Epi& E) {
;     ...
;             PG8_LDA(At, 1, 1); PG8_STAGE(PG8_SB(1, 0), b3, voffB); PG8_STAGE(PG8_SB(1, 1), b3 + hstepB, voffB); PG8_STAGE(PG8_SA(1, 0), a3, voffA);
;             PG8_WAIT_V(8); PG8_WAIT_L(0); PG8_BAR; PG8_MMA(1, 0, At, B0); PG8_MMA(1, 1, At, B1); PG8_BAR; PG8_SCHED;
;         }
;         if constexpr (ALIGN_EPI) { if (wr == 0) PG8_BAR; }
	v_lshl_add_u64 v[212:213], v[212:213], 0, s[34:35]
	ds_read_b128 v[162:165], v234 offset:49152
	ds_read_b128 v[166:169], v234 offset:50176
	ds_read_b128 v[170:173], v234 offset:51200
	ds_read_b128 v[174:177], v234 offset:52224
	ds_read_b128 v[178:181], v234 offset:53248
	ds_read_b128 v[182:185], v234 offset:54272
	ds_read_b128 v[236:239], v234 offset:55296
	ds_read_b128 v[240:243], v234 offset:56320
	global_load_lds_dwordx4 v[212:213], off
	s_add_i32 m0, s83, 0x2000
	s_add_u32 s58, s58, 0x40080
	v_lshl_add_u64 v[212:213], v[244:245], 0, s[34:35]
	s_addc_u32 s59, s59, 0
	s_add_i32 s83, s84, s65
	global_load_lds_dwordx4 v[212:213], off
	v_lshl_add_u64 v[212:213], s[58:59], 0, v[188:189]
	s_mov_b32 m0, s83
	s_nop 0
	global_load_lds_dwordx4 v[212:213], off
	v_lshl_add_u64 v[212:213], s[58:59], 0, v[190:191]
	s_add_i32 m0, s83, 0x2000
	s_nop 0
	global_load_lds_dwordx4 v[212:213], off
	v_lshl_add_u64 v[212:213], v[246:247], 0, s[36:37]
	s_mov_b32 m0, s71
	s_nop 0
	global_load_lds_dwordx4 v[212:213], off
	v_lshl_add_u64 v[212:213], v[246:247], 0, s[38:39]
	s_mov_b32 m0, s72
	s_nop 0
	global_load_lds_dwordx4 v[212:213], off
	s_waitcnt vmcnt(8)
	s_waitcnt lgkmcnt(0)
	s_barrier
	s_waitcnt lgkmcnt(0)
	v_mfma_f32_16x16x32_bf16 v[62:65], v[102:105], v[162:165], v[62:65]
	v_mfma_f32_16x16x32_bf16 v[58:61], v[122:125], v[162:165], v[58:61]
	v_mfma_f32_16x16x32_bf16 v[46:49], v[102:105], v[170:173], v[46:49]
	v_mfma_f32_16x16x32_bf16 v[42:45], v[122:125], v[170:173], v[42:45]
	v_mfma_f32_16x16x32_bf16 v[30:33], v[102:105], v[178:181], v[30:33]
	v_mfma_f32_16x16x32_bf16 v[26:29], v[122:125], v[178:181], v[26:29]
	v_mfma_f32_16x16x32_bf16 v[14:17], v[102:105], v[236:239], v[14:17]
	v_mfma_f32_16x16x32_bf16 v[10:13], v[122:125], v[236:239], v[10:13]
	v_mfma_f32_16x16x32_bf16 v[62:65], v[110:113], v[166:169], v[62:65]
	v_mfma_f32_16x16x32_bf16 v[58:61], v[134:137], v[166:169], v[58:61]
	v_mfma_f32_16x16x32_bf16 v[46:49], v[110:113], v[174:177], v[46:49]
	v_mfma_f32_16x16x32_bf16 v[42:45], v[134:137], v[174:177], v[42:45]
	v_mfma_f32_16x16x32_bf16 v[30:33], v[110:113], v[182:185], v[30:33]
	v_mfma_f32_16x16x32_bf16 v[26:29], v[134:137], v[182:185], v[26:29]
	v_mfma_f32_16x16x32_bf16 v[14:17], v[110:113], v[240:243], v[14:17]
	v_mfma_f32_16x16x32_bf16 v[10:13], v[134:137], v[240:243], v[10:13]
	v_mfma_f32_16x16x32_bf16 v[54:57], v[146:149], v[162:165], v[54:57]
	s_add_i32 s82, s82, 2
	v_mfma_f32_16x16x32_bf16 v[50:53], v[154:157], v[162:165], v[50:53]
	s_add_u32 s80, s80, 0x100
	v_mfma_f32_16x16x32_bf16 v[38:41], v[146:149], v[170:173], v[38:41]
	s_addc_u32 s81, s81, 0
	v_mfma_f32_16x16x32_bf16 v[34:37], v[154:157], v[170:173], v[34:37]
	s_add_u32 s56, s56, 0x10000
	v_mfma_f32_16x16x32_bf16 v[22:25], v[146:149], v[178:181], v[22:25]
	s_addc_u32 s57, s57, 0
	v_mfma_f32_16x16x32_bf16 v[18:21], v[154:157], v[178:181], v[18:21]
	s_cmp_gt_u32 s82, 13
	v_mfma_f32_16x16x32_bf16 v[6:9], v[146:149], v[236:239], v[6:9]
	v_mfma_f32_16x16x32_bf16 v[2:5], v[154:157], v[236:239], v[2:5]
	v_mfma_f32_16x16x32_bf16 v[54:57], v[150:153], v[166:169], v[54:57]
	v_mfma_f32_16x16x32_bf16 v[50:53], v[158:161], v[166:169], v[50:53]
	v_mfma_f32_16x16x32_bf16 v[38:41], v[150:153], v[174:177], v[38:41]
	v_mfma_f32_16x16x32_bf16 v[34:37], v[158:161], v[174:177], v[34:37]
	v_mfma_f32_16x16x32_bf16 v[22:25], v[150:153], v[182:185], v[22:25]
	v_mfma_f32_16x16x32_bf16 v[18:21], v[158:161], v[182:185], v[18:21]
	v_mfma_f32_16x16x32_bf16 v[6:9], v[150:153], v[240:243], v[6:9]
	v_mfma_f32_16x16x32_bf16 v[2:5], v[158:161], v[240:243], v[2:5]
	s_barrier
	s_cbranch_scc0 .LBB0_2289
	s_and_b64 vcc, exec, s[40:41]
	s_cbranch_vccz .LBB0_2292
	s_barrier

; #define PG8_STAGE(bufoff, gbase, voff) do { _Pragma("unroll") for (int _i = 0; _i < 2; ++_i) \
;         __builtin_amdgcn_global_load_lds((const unsigned*)((const char*)(gbase) + (voff)[_i]), (PG8_LAS unsigned*)(lds + (bufoff) + ldsw + _i * 8192), 16, 0, 0); } while (0)
; #define PG8_LDA(dst, b, h) do { _Pragma("unroll") for (int m = 0; m < 4; ++m) _Pragma("unroll") for (int k = 0; k < 2; ++k) dst[m][k] = *(const PG8_LAS bf16x8*)(lds + PG8_SA(b, h) + aoff + m * 2048 + k * 1024); } while (0)
; #define PG8_LDB(dst, b, h) do { _Pragma("unroll") for (int n = 0; n < 2; ++n) _Pragma("unroll") for (int k = 0; k < 2; ++k) dst[n][k] = *(const PG8_LAS bf16x8*)(lds + PG8_SB(b, h) + boff + n * 2048 + k * 1024); } while (0)
; #define PG8_WAIT_V(n) asm volatile("s_waitcnt vmcnt(" #n ")" ::: "memory")
; #define PG8_WAIT_L(n) asm volatile("s_waitcnt lgkmcnt(" #n ")" ::: "memory")
; #define PG8_BAR __builtin_amdgcn_s_barrier()
; template <class Epi, bool ALIGN_EPI, bool ABLK = false>
; __device__ __forceinline__ void gemm_phase(PG8_LAS unsigned char* lds, const Gemm g, const StaticOrder& S, const Epi& E) {
;     ...
;         const bool has_next = S.next(ui + 1, nxt);
;         const char* nA = has_next ? PG8_ABASE(nxt) : cA; const char* nB = has_next ? PG8_BBASE(nxt) : cB;
;         for (int t = 0; t < nt; t += 2) {
;             const bool last = (t == nt - 2);
;             const char* a1 = cA + (size_t)(t + 1) * kstepA;
;             const char* a2 = last ? nA : cA + (size_t)(t + 2) * kstepA; const char* b2 = last ? nB : cB + (size_t)(t + 2) * kstepB;
;             const char* a3 = a2 + kstepA; const char* b3 = b2 + kstepB;
;             PG8_LDB(B0, 0, 0); PG8_LDB(B1, 0, 1); PG8_SCHED; PG8_LDA(At, 0, 0); PG8_STAGE(PG8_SA(1, 1), a1 + hstepA, voffA);
;             PG8_WAIT_V(8); PG8_WAIT_L(0); PG8_BAR; PG8_MMA(0, 0, At, B0); PG8_MMA(0, 1, At, B1); PG8_BAR; PG8_SCHED;
;             PG8_LDA(At, 0, 1); PG8_STAGE(PG8_SB(0, 0), b2, voffB); PG8_STAGE(PG8_SB(0, 1), b2 + hstepB, voffB); PG8_STAGE(PG8_SA(0, 0), a2, voffA);
;             PG8_WAIT_V(8); PG8_WAIT_L(0); PG8_BAR; PG8_MMA(1, 0, At, B0); PG8_MMA(1, 1, At, B1); PG8_BAR; PG8_SCHED;
;             PG8_LDB(B0, 1, 0); PG8_LDB(B1, 1, 1); PG8_SCHED; PG8_LDA(At, 1, 0); PG8_STAGE(PG8_SA(0, 1), a2 + hstepA, voffA);
;             PG8_WAIT_V(8); PG8_WAIT_L(0); PG8_BAR; PG8_MMA(0, 0, At, B0); PG8_MMA(0, 1, At, B1); PG8_BAR; PG8_SCHED;
.LBB0_2495:
	ds_read_b128 v[132:135], v251
	ds_read_b128 v[178:181], v251 offset:1024
	ds_read_b128 v[182:185], v251 offset:2048
	ds_read_b128 v[186:189], v251 offset:3072
	ds_read_b128 v[190:193], v251 offset:16384
	ds_read_b128 v[194:197], v251 offset:17408
	ds_read_b128 v[198:201], v251 offset:18432
	ds_read_b128 v[202:205], v251 offset:19456
	s_add_u32 s60, s24, s58
	s_addc_u32 s61, s25, s59
	s_sub_u32 s98, s60, 0x10000
	s_subb_u32 s99, s61, 0
	s_cmp_eq_u32 s83, 12
	s_cselect_b32 s101, s53, s61
	s_cselect_b32 s100, s79, s60
	s_cselect_b32 s61, s51, s82
	s_cselect_b32 s60, s80, s81
	s_add_i32 m0, s66, 0xc000
	ds_read_b128 v[206:209], v176
	ds_read_b128 v[210:213], v176 offset:1024
	ds_read_b128 v[214:217], v176 offset:2048
	ds_read_b128 v[218:221], v176 offset:3072
	ds_read_b128 v[222:225], v176 offset:4096
	ds_read_b128 v[226:229], v176 offset:5120
	ds_read_b128 v[230:233], v176 offset:6144
	ds_read_b128 v[234:237], v176 offset:7168
	global_load_lds_dwordx4 v249, s[98:99]
	s_add_i32 m0, s66, 0xe000
	s_nop 0
	global_load_lds_dwordx4 v250, s[98:99]
	s_waitcnt vmcnt(8)
	s_waitcnt lgkmcnt(0)
	s_barrier
	s_waitcnt lgkmcnt(0)
	v_mfma_f32_16x16x32_bf16 v[126:129], v[132:135], v[206:209], v[126:129]
	v_mfma_f32_16x16x32_bf16 v[122:125], v[182:185], v[206:209], v[122:125]
	v_mfma_f32_16x16x32_bf16 v[118:121], v[132:135], v[214:217], v[118:121]
	v_mfma_f32_16x16x32_bf16 v[114:117], v[182:185], v[214:217], v[114:117]
	v_mfma_f32_16x16x32_bf16 v[110:113], v[132:135], v[222:225], v[110:113]
	v_mfma_f32_16x16x32_bf16 v[106:109], v[182:185], v[222:225], v[106:109]
	v_mfma_f32_16x16x32_bf16 v[102:105], v[132:135], v[230:233], v[102:105]
	v_mfma_f32_16x16x32_bf16 v[98:101], v[182:185], v[230:233], v[98:101]
	v_mfma_f32_16x16x32_bf16 v[126:129], v[178:181], v[210:213], v[126:129]
	v_mfma_f32_16x16x32_bf16 v[122:125], v[186:189], v[210:213], v[122:125]
	v_mfma_f32_16x16x32_bf16 v[118:121], v[178:181], v[218:221], v[118:121]
	v_mfma_f32_16x16x32_bf16 v[114:117], v[186:189], v[218:221], v[114:117]
	v_mfma_f32_16x16x32_bf16 v[110:113], v[178:181], v[226:229], v[110:113]
	v_mfma_f32_16x16x32_bf16 v[106:109], v[186:189], v[226:229], v[106:109]
	v_mfma_f32_16x16x32_bf16 v[102:105], v[178:181], v[234:237], v[102:105]
	v_mfma_f32_16x16x32_bf16 v[98:101], v[186:189], v[234:237], v[98:101]
	v_mfma_f32_16x16x32_bf16 v[94:97], v[190:193], v[206:209], v[94:97]
	s_add_i32 s86, s75, s9
	v_mfma_f32_16x16x32_bf16 v[90:93], v[198:201], v[206:209], v[90:93]
	s_mov_b32 m0, s86
	v_mfma_f32_16x16x32_bf16 v[86:89], v[190:193], v[214:217], v[86:89]
	v_mfma_f32_16x16x32_bf16 v[82:85], v[198:201], v[214:217], v[82:85]
	v_mfma_f32_16x16x32_bf16 v[78:81], v[190:193], v[222:225], v[78:81]
	v_mfma_f32_16x16x32_bf16 v[74:77], v[198:201], v[222:225], v[74:77]
	v_mfma_f32_16x16x32_bf16 v[70:73], v[190:193], v[230:233], v[70:73]
	v_mfma_f32_16x16x32_bf16 v[66:69], v[198:201], v[230:233], v[66:69]
	v_mfma_f32_16x16x32_bf16 v[94:97], v[194:197], v[210:213], v[94:97]
	v_mfma_f32_16x16x32_bf16 v[90:93], v[202:205], v[210:213], v[90:93]
	v_mfma_f32_16x16x32_bf16 v[86:89], v[194:197], v[218:221], v[86:89]
	v_mfma_f32_16x16x32_bf16 v[82:85], v[202:205], v[218:221], v[82:85]
	v_mfma_f32_16x16x32_bf16 v[78:81], v[194:197], v[226:229], v[78:81]
	v_mfma_f32_16x16x32_bf16 v[74:77], v[202:205], v[226:229], v[74:77]
	v_mfma_f32_16x16x32_bf16 v[70:73], v[194:197], v[234:237], v[70:73]
	v_mfma_f32_16x16x32_bf16 v[66:69], v[202:205], v[234:237], v[66:69]
	s_barrier
	ds_read_b128 v[206:209], v176 offset:16384
	ds_read_b128 v[210:213], v176 offset:17408
	ds_read_b128 v[214:217], v176 offset:18432
	ds_read_b128 v[218:221], v176 offset:19456
	ds_read_b128 v[222:225], v176 offset:20480
	ds_read_b128 v[226:229], v176 offset:21504
	ds_read_b128 v[230:233], v176 offset:22528
	ds_read_b128 v[234:237], v176 offset:23552
	global_load_lds_dwordx4 v140, s[60:61]
	s_add_i32 m0, s86, 0x2000
	s_add_u32 s86, s60, 0x40000
	s_addc_u32 s87, s61, 0
	s_add_i32 s88, s76, s9
	global_load_lds_dwordx4 v142, s[60:61]
	s_mov_b32 m0, s88
	s_nop 0
	global_load_lds_dwordx4 v140, s[86:87]
	s_add_i32 m0, s88, 0x2000
	s_nop 0
	global_load_lds_dwordx4 v142, s[86:87]
	s_mov_b32 m0, s66
	s_nop 0
	global_load_lds_dwordx4 v138, s[100:101]
	s_mov_b32 m0, s67
	s_nop 0
	global_load_lds_dwordx4 v244, s[100:101]
	s_waitcnt vmcnt(8)
	s_waitcnt lgkmcnt(0)
	s_barrier
	s_waitcnt lgkmcnt(0)
	v_mfma_f32_16x16x32_bf16 v[62:65], v[132:135], v[206:209], v[62:65]
	v_mfma_f32_16x16x32_bf16 v[58:61], v[182:185], v[206:209], v[58:61]
	v_mfma_f32_16x16x32_bf16 v[54:57], v[132:135], v[214:217], v[54:57]
	v_mfma_f32_16x16x32_bf16 v[50:53], v[182:185], v[214:217], v[50:53]
	v_mfma_f32_16x16x32_bf16 v[46:49], v[132:135], v[222:225], v[46:49]
	v_mfma_f32_16x16x32_bf16 v[42:45], v[182:185], v[222:225], v[42:45]
	v_mfma_f32_16x16x32_bf16 v[38:41], v[132:135], v[230:233], v[38:41]
	v_mfma_f32_16x16x32_bf16 v[34:37], v[182:185], v[230:233], v[34:37]
	v_mfma_f32_16x16x32_bf16 v[62:65], v[178:181], v[210:213], v[62:65]
	v_mfma_f32_16x16x32_bf16 v[58:61], v[186:189], v[210:213], v[58:61]
	v_mfma_f32_16x16x32_bf16 v[54:57], v[178:181], v[218:221], v[54:57]
	v_mfma_f32_16x16x32_bf16 v[50:53], v[186:189], v[218:221], v[50:53]
	v_mfma_f32_16x16x32_bf16 v[46:49], v[178:181], v[226:229], v[46:49]
	v_mfma_f32_16x16x32_bf16 v[42:45], v[186:189], v[226:229], v[42:45]
	v_mfma_f32_16x16x32_bf16 v[38:41], v[178:181], v[234:237], v[38:41]
	v_mfma_f32_16x16x32_bf16 v[34:37], v[186:189], v[234:237], v[34:37]
	v_mfma_f32_16x16x32_bf16 v[30:33], v[190:193], v[206:209], v[30:33]
	s_add_i32 s84, 0, 0x18000
	v_mfma_f32_16x16x32_bf16 v[26:29], v[198:201], v[206:209], v[26:29]
	s_add_i32 s85, 0, 0x1c000
	v_mfma_f32_16x16x32_bf16 v[22:25], v[190:193], v[214:217], v[22:25]
	v_mfma_f32_16x16x32_bf16 v[18:21], v[198:201], v[214:217], v[18:21]
	v_mfma_f32_16x16x32_bf16 v[14:17], v[190:193], v[222:225], v[14:17]
	v_mfma_f32_16x16x32_bf16 v[10:13], v[198:201], v[222:225], v[10:13]
	v_mfma_f32_16x16x32_bf16 v[6:9], v[190:193], v[230:233], v[6:9]
	v_mfma_f32_16x16x32_bf16 v[2:5], v[198:201], v[230:233], v[2:5]
	v_mfma_f32_16x16x32_bf16 v[30:33], v[194:197], v[210:213], v[30:33]
	v_mfma_f32_16x16x32_bf16 v[26:29], v[202:205], v[210:213], v[26:29]
	v_mfma_f32_16x16x32_bf16 v[22:25], v[194:197], v[218:221], v[22:25]
	v_mfma_f32_16x16x32_bf16 v[18:21], v[202:205], v[218:221], v[18:21]
	v_mfma_f32_16x16x32_bf16 v[14:17], v[194:197], v[226:229], v[14:17]
	v_mfma_f32_16x16x32_bf16 v[10:13], v[202:205], v[226:229], v[10:13]
	v_mfma_f32_16x16x32_bf16 v[6:9], v[194:197], v[234:237], v[6:9]
	v_mfma_f32_16x16x32_bf16 v[2:5], v[202:205], v[234:237], v[2:5]
	s_barrier
; #define PG8_STAGE(bufoff, gbase, voff) do { _Pragma("unroll") for (int _i = 0; _i < 2; ++_i) \
;         __builtin_amdgcn_global_load_lds((const unsigned*)((const char*)(gbase) + (voff)[_i]), (PG8_LAS unsigned*)(lds + (bufoff) + ldsw + _i * 8192), 16, 0, 0); } while (0)
; #define PG8_LDA(dst, b, h) do { _Pragma("unroll") for (int m = 0; m < 4; ++m) _Pragma("unroll") for (int k = 0; k < 2; ++k) dst[m][k] = *(const PG8_LAS bf16x8*)(lds + PG8_SA(b, h) + aoff + m * 2048 + k * 1024); } while (0)
; #define PG8_LDB(dst, b, h) do { _Pragma("unroll") for (int n = 0; n < 2; ++n) _Pragma("unroll") for (int k = 0; k < 2; ++k) dst[n][k] = *(const PG8_LAS bf16x8*)(lds + PG8_SB(b, h) + boff + n * 2048 + k * 1024); } while (0)
; #define PG8_MMA(ai, bj, At, Bt) do { __builtin_amdgcn_s_setprio(1); _Pragma("unroll") for (int m = 0; m < 4; ++m) _Pragma("unroll") for (int n = 0; n < 2; ++n) _Pragma("unroll") for (int k = 0; k < 2; ++k) \
;         acc[ai][bj][m][n] = __builtin_amdgcn_mfma_f32_16x16x32_bf16(Bt[n][k], At[m][k], acc[ai][bj][m][n], 0, 0, 0); __builtin_amdgcn_s_setprio(0); } while (0)
; #define PG8_WAIT_V(n) asm volatile("s_waitcnt vmcnt(" #n ")" ::: "memory")
; #define PG8_WAIT_L(n) asm volatile("s_waitcnt lgkmcnt(" #n ")" ::: "memory")
; #define PG8_BAR __builtin_amdgcn_s_barrier()
; #define PG8_SCHED __builtin_amdgcn_sched_barrier(0)
; template <class Epi, bool ALIGN_EPI, bool ABLK = false>
; __device__ __forceinline__ void gemm_phase(PG8_LAS unsigned char* lds, const Gemm g, const StaticOrder& S, const Epi& E) {
;     ...
;             PG8_LDB(B0, 1, 0); PG8_LDB(B1, 1, 1); PG8_SCHED; PG8_LDA(At, 1, 0); PG8_STAGE(PG8_SA(0, 1), a2 + hstepA, voffA);
;             PG8_WAIT_V(8); PG8_WAIT_L(0); PG8_BAR; PG8_MMA(0, 0, At, B0); PG8_MMA(0, 1, At, B1); PG8_BAR; PG8_SCHED;
;             PG8_LDA(At, 1, 1); PG8_STAGE(PG8_SB(1, 0), b3, voffB); PG8_STAGE(PG8_SB(1, 1), b3 + hstepB, voffB); PG8_STAGE(PG8_SA(1, 0), a3, voffA);
;             PG8_WAIT_V(8); PG8_WAIT_L(0); PG8_BAR; PG8_MMA(1, 0, At, B0); PG8_MMA(1, 1, At, B1); PG8_BAR; PG8_SCHED;
;         }
;         if constexpr (ALIGN_EPI) { if (wr == 0) PG8_BAR; }
	ds_read_b128 v[132:135], v251 offset:32768
	ds_read_b128 v[178:181], v251 offset:33792
	ds_read_b128 v[182:185], v251 offset:34816
	ds_read_b128 v[186:189], v251 offset:35840
	ds_read_b128 v[190:193], v251 offset:49152
	ds_read_b128 v[194:197], v251 offset:50176
	ds_read_b128 v[198:201], v251 offset:51200
	ds_read_b128 v[202:205], v251 offset:52224
	s_mov_b32 m0, s68
	ds_read_b128 v[206:209], v176 offset:32768
	ds_read_b128 v[210:213], v176 offset:33792
	ds_read_b128 v[214:217], v176 offset:34816
	ds_read_b128 v[218:221], v176 offset:35840
	ds_read_b128 v[222:225], v176 offset:36864
	ds_read_b128 v[226:229], v176 offset:37888
	ds_read_b128 v[230:233], v176 offset:38912
	ds_read_b128 v[234:237], v176 offset:39936
	global_load_lds_dwordx4 v245, s[100:101]
	s_mov_b32 m0, s69
	s_nop 0
	global_load_lds_dwordx4 v246, s[100:101]
	s_waitcnt vmcnt(8)
	s_waitcnt lgkmcnt(0)
	s_barrier
	s_waitcnt lgkmcnt(0)
	v_mfma_f32_16x16x32_bf16 v[126:129], v[132:135], v[206:209], v[126:129]
	v_mfma_f32_16x16x32_bf16 v[122:125], v[182:185], v[206:209], v[122:125]
	v_mfma_f32_16x16x32_bf16 v[118:121], v[132:135], v[214:217], v[118:121]
	v_mfma_f32_16x16x32_bf16 v[114:117], v[182:185], v[214:217], v[114:117]
	v_mfma_f32_16x16x32_bf16 v[110:113], v[132:135], v[222:225], v[110:113]
	v_mfma_f32_16x16x32_bf16 v[106:109], v[182:185], v[222:225], v[106:109]
	v_mfma_f32_16x16x32_bf16 v[102:105], v[132:135], v[230:233], v[102:105]
	v_mfma_f32_16x16x32_bf16 v[98:101], v[182:185], v[230:233], v[98:101]
	v_mfma_f32_16x16x32_bf16 v[126:129], v[178:181], v[210:213], v[126:129]
	v_mfma_f32_16x16x32_bf16 v[122:125], v[186:189], v[210:213], v[122:125]
	v_mfma_f32_16x16x32_bf16 v[118:121], v[178:181], v[218:221], v[118:121]
	v_mfma_f32_16x16x32_bf16 v[114:117], v[186:189], v[218:221], v[114:117]
	v_mfma_f32_16x16x32_bf16 v[110:113], v[178:181], v[226:229], v[110:113]
	v_mfma_f32_16x16x32_bf16 v[106:109], v[186:189], v[226:229], v[106:109]
	v_mfma_f32_16x16x32_bf16 v[102:105], v[178:181], v[234:237], v[102:105]
	v_mfma_f32_16x16x32_bf16 v[98:101], v[186:189], v[234:237], v[98:101]
	v_mfma_f32_16x16x32_bf16 v[94:97], v[190:193], v[206:209], v[94:97]
	s_add_i32 s84, s84, s9
	v_mfma_f32_16x16x32_bf16 v[90:93], v[198:201], v[206:209], v[90:93]
	s_add_u32 s60, s60, s28
	v_mfma_f32_16x16x32_bf16 v[86:89], v[190:193], v[214:217], v[86:89]
	s_addc_u32 s61, s61, s29
	v_mfma_f32_16x16x32_bf16 v[82:85], v[198:201], v[214:217], v[82:85]
	s_mov_b32 m0, s84
	v_mfma_f32_16x16x32_bf16 v[78:81], v[190:193], v[222:225], v[78:81]
	v_mfma_f32_16x16x32_bf16 v[74:77], v[198:201], v[222:225], v[74:77]
	v_mfma_f32_16x16x32_bf16 v[70:73], v[190:193], v[230:233], v[70:73]
	v_mfma_f32_16x16x32_bf16 v[66:69], v[198:201], v[230:233], v[66:69]
	v_mfma_f32_16x16x32_bf16 v[94:97], v[194:197], v[210:213], v[94:97]
	v_mfma_f32_16x16x32_bf16 v[90:93], v[202:205], v[210:213], v[90:93]
	v_mfma_f32_16x16x32_bf16 v[86:89], v[194:197], v[218:221], v[86:89]
	v_mfma_f32_16x16x32_bf16 v[82:85], v[202:205], v[218:221], v[82:85]
	v_mfma_f32_16x16x32_bf16 v[78:81], v[194:197], v[226:229], v[78:81]
	v_mfma_f32_16x16x32_bf16 v[74:77], v[202:205], v[226:229], v[74:77]
	v_mfma_f32_16x16x32_bf16 v[70:73], v[194:197], v[234:237], v[70:73]
	v_mfma_f32_16x16x32_bf16 v[66:69], v[202:205], v[234:237], v[66:69]
	s_barrier
	ds_read_b128 v[206:209], v176 offset:49152
	ds_read_b128 v[210:213], v176 offset:50176
	ds_read_b128 v[214:217], v176 offset:51200
	ds_read_b128 v[218:221], v176 offset:52224
	ds_read_b128 v[222:225], v176 offset:53248
	ds_read_b128 v[226:229], v176 offset:54272
	ds_read_b128 v[230:233], v176 offset:55296
	ds_read_b128 v[234:237], v176 offset:56320
	global_load_lds_dwordx4 v140, s[60:61]
	s_add_i32 m0, s84, 0x2000
	s_add_i32 s84, s85, s9
	global_load_lds_dwordx4 v142, s[60:61]
	s_add_u32 s60, s60, 0x40000
	s_addc_u32 s61, s61, 0
	s_mov_b32 m0, s84
	s_nop 0
	global_load_lds_dwordx4 v140, s[60:61]
	s_add_i32 m0, s84, 0x2000
	s_nop 0
	global_load_lds_dwordx4 v142, s[60:61]
	s_mov_b32 m0, s70
	s_nop 0
	global_load_lds_dwordx4 v247, s[100:101]
	s_mov_b32 m0, s72
	s_nop 0
	global_load_lds_dwordx4 v248, s[100:101]
	s_waitcnt vmcnt(8)
	s_waitcnt lgkmcnt(0)
	s_barrier
	s_waitcnt lgkmcnt(0)
	v_mfma_f32_16x16x32_bf16 v[62:65], v[132:135], v[206:209], v[62:65]
	v_mfma_f32_16x16x32_bf16 v[58:61], v[182:185], v[206:209], v[58:61]
	v_mfma_f32_16x16x32_bf16 v[54:57], v[132:135], v[214:217], v[54:57]
	v_mfma_f32_16x16x32_bf16 v[50:53], v[182:185], v[214:217], v[50:53]
	v_mfma_f32_16x16x32_bf16 v[46:49], v[132:135], v[222:225], v[46:49]
	v_mfma_f32_16x16x32_bf16 v[42:45], v[182:185], v[222:225], v[42:45]
	v_mfma_f32_16x16x32_bf16 v[38:41], v[132:135], v[230:233], v[38:41]
	v_mfma_f32_16x16x32_bf16 v[34:37], v[182:185], v[230:233], v[34:37]
	v_mfma_f32_16x16x32_bf16 v[62:65], v[178:181], v[210:213], v[62:65]
	v_mfma_f32_16x16x32_bf16 v[58:61], v[186:189], v[210:213], v[58:61]
	v_mfma_f32_16x16x32_bf16 v[54:57], v[178:181], v[218:221], v[54:57]
	v_mfma_f32_16x16x32_bf16 v[50:53], v[186:189], v[218:221], v[50:53]
	v_mfma_f32_16x16x32_bf16 v[46:49], v[178:181], v[226:229], v[46:49]
	v_mfma_f32_16x16x32_bf16 v[42:45], v[186:189], v[226:229], v[42:45]
	v_mfma_f32_16x16x32_bf16 v[38:41], v[178:181], v[234:237], v[38:41]
	v_mfma_f32_16x16x32_bf16 v[34:37], v[186:189], v[234:237], v[34:37]
	v_mfma_f32_16x16x32_bf16 v[30:33], v[190:193], v[206:209], v[30:33]
	s_add_i32 s83, s83, 2
	v_mfma_f32_16x16x32_bf16 v[26:29], v[198:201], v[206:209], v[26:29]
	s_add_u32 s81, s81, 0x100
	v_mfma_f32_16x16x32_bf16 v[22:25], v[190:193], v[214:217], v[22:25]
	s_addc_u32 s82, s82, 0
	v_mfma_f32_16x16x32_bf16 v[18:21], v[198:201], v[214:217], v[18:21]
	s_add_u32 s58, s58, 0x10000
	v_mfma_f32_16x16x32_bf16 v[14:17], v[190:193], v[222:225], v[14:17]
	s_addc_u32 s59, s59, 0
	v_mfma_f32_16x16x32_bf16 v[10:13], v[198:201], v[222:225], v[10:13]
	s_cmp_gt_u32 s83, 13
	v_mfma_f32_16x16x32_bf16 v[6:9], v[190:193], v[230:233], v[6:9]
	v_mfma_f32_16x16x32_bf16 v[2:5], v[198:201], v[230:233], v[2:5]
	v_mfma_f32_16x16x32_bf16 v[30:33], v[194:197], v[210:213], v[30:33]
	v_mfma_f32_16x16x32_bf16 v[26:29], v[202:205], v[210:213], v[26:29]
	v_mfma_f32_16x16x32_bf16 v[22:25], v[194:197], v[218:221], v[22:25]
	v_mfma_f32_16x16x32_bf16 v[18:21], v[202:205], v[218:221], v[18:21]
	v_mfma_f32_16x16x32_bf16 v[14:17], v[194:197], v[226:229], v[14:17]
	v_mfma_f32_16x16x32_bf16 v[10:13], v[202:205], v[226:229], v[10:13]
	v_mfma_f32_16x16x32_bf16 v[6:9], v[194:197], v[234:237], v[6:9]
	v_mfma_f32_16x16x32_bf16 v[2:5], v[202:205], v[234:237], v[2:5]
	s_barrier
	s_cbranch_scc0 .LBB0_2495
	s_and_b64 vcc, exec, s[36:37]
	s_cbranch_vccz .LBB0_2498
	s_barrier

; #define PG8_STAGE(bufoff, gbase, voff) do { _Pragma("unroll") for (int _i = 0; _i < 2; ++_i) \
;         __builtin_amdgcn_global_load_lds((const unsigned*)((const char*)(gbase) + (voff)[_i]), (PG8_LAS unsigned*)(lds + (bufoff) + ldsw + _i * 8192), 16, 0, 0); } while (0)
; #define PG8_LDA(dst, b, h) do { _Pragma("unroll") for (int m = 0; m < 4; ++m) _Pragma("unroll") for (int k = 0; k < 2; ++k) dst[m][k] = *(const PG8_LAS bf16x8*)(lds + PG8_SA(b, h) + aoff + m * 2048 + k * 1024); } while (0)
; #define PG8_LDB(dst, b, h) do { _Pragma("unroll") for (int n = 0; n < 2; ++n) _Pragma("unroll") for (int k = 0; k < 2; ++k) dst[n][k] = *(const PG8_LAS bf16x8*)(lds + PG8_SB(b, h) + boff + n * 2048 + k * 1024); } while (0)
; #define PG8_MMA(ai, bj, At, Bt) do { __builtin_amdgcn_s_setprio(1); _Pragma("unroll") for (int m = 0; m < 4; ++m) _Pragma("unroll") for (int n = 0; n < 2; ++n) _Pragma("unroll") for (int k = 0; k < 2; ++k) \
;         acc[ai][bj][m][n] = __builtin_amdgcn_mfma_f32_16x16x32_bf16(Bt[n][k], At[m][k], acc[ai][bj][m][n], 0, 0, 0); __builtin_amdgcn_s_setprio(0); } while (0)
; #define PG8_WAIT_V(n) asm volatile("s_waitcnt vmcnt(" #n ")" ::: "memory")
; template <class Epi, bool ALIGN_EPI, bool ABLK = false>
; __device__ __forceinline__ void gemm_phase(PG8_LAS unsigned char* lds, const Gemm g, const StaticOrder& S, const Epi& E) {
;     ...
;         const bool has_next = S.next(ui + 1, nxt);
;         const char* nA = has_next ? PG8_ABASE(nxt) : cA; const char* nB = has_next ? PG8_BBASE(nxt) : cB;
;         for (int t = 0; t < nt; t += 2) {
;             const bool last = (t == nt - 2);
;             const char* a1 = cA + (size_t)(t + 1) * kstepA;
;             const char* a2 = last ? nA : cA + (size_t)(t + 2) * kstepA; const char* b2 = last ? nB : cB + (size_t)(t + 2) * kstepB;
;             const char* a3 = a2 + kstepA; const char* b3 = b2 + kstepB;
;             PG8_LDB(B0, 0, 0); PG8_LDB(B1, 0, 1); PG8_SCHED; PG8_LDA(At, 0, 0); PG8_STAGE(PG8_SA(1, 1), a1 + hstepA, voffA);
;             PG8_WAIT_V(8); PG8_WAIT_L(0); PG8_BAR; PG8_MMA(0, 0, At, B0); PG8_MMA(0, 1, At, B1); PG8_BAR; PG8_SCHED;
;             PG8_LDA(At, 0, 1); PG8_STAGE(PG8_SB(0, 0), b2, voffB); PG8_STAGE(PG8_SB(0, 1), b2 + hstepB, voffB); PG8_STAGE(PG8_SA(0, 0), a2, voffA);
;             PG8_WAIT_V(8); PG8_WAIT_L(0); PG8_BAR; PG8_MMA(1, 0, At, B0); PG8_MMA(1, 1, At, B1); PG8_BAR; PG8_SCHED;
.LBB0_2631:
	ds_read_b128 v[130:133], v234
	ds_read_b128 v[134:137], v234 offset:1024
	ds_read_b128 v[138:141], v234 offset:2048
	ds_read_b128 v[142:145], v234 offset:3072
	ds_read_b128 v[146:149], v235
	ds_read_b128 v[150:153], v235 offset:1024
	ds_read_b128 v[154:157], v235 offset:2048
	ds_read_b128 v[158:161], v235 offset:3072
	s_cmp_eq_u32 s57, 40
	s_cselect_b32 s81, s13, s53
	s_cselect_b32 s80, s12, s52
	s_cselect_b32 s55, s49, s56
	s_cselect_b32 s54, s48, s51
	v_lshl_add_u64 v[248:249], s[52:53], 0, v[186:187]
	v_lshl_add_u64 v[250:251], v[248:249], 0, s[44:45]
	s_add_i32 m0, s62, 0xc000
	ds_read_b128 v[162:165], v236
	ds_read_b128 v[166:169], v236 offset:1024
	ds_read_b128 v[170:173], v236 offset:2048
	ds_read_b128 v[174:177], v236 offset:3072
	ds_read_b128 v[178:181], v236 offset:4096
	ds_read_b128 v[182:185], v236 offset:5120
	ds_read_b128 v[240:243], v236 offset:6144
	ds_read_b128 v[244:247], v236 offset:7168
	global_load_lds_dwordx4 v[250:251], off
	v_lshl_add_u64 v[248:249], v[248:249], 0, s[46:47]
	s_add_i32 m0, s62, 0xe000
	s_nop 0
	global_load_lds_dwordx4 v[248:249], off
	s_waitcnt vmcnt(8)
	s_waitcnt lgkmcnt(0)
	s_barrier
	s_waitcnt lgkmcnt(0)
	v_mfma_f32_16x16x32_bf16 v[126:129], v[130:133], v[162:165], v[126:129]
	v_mfma_f32_16x16x32_bf16 v[122:125], v[138:141], v[162:165], v[122:125]
	v_mfma_f32_16x16x32_bf16 v[110:113], v[130:133], v[170:173], v[110:113]
	v_mfma_f32_16x16x32_bf16 v[106:109], v[138:141], v[170:173], v[106:109]
	v_mfma_f32_16x16x32_bf16 v[94:97], v[130:133], v[178:181], v[94:97]
	v_mfma_f32_16x16x32_bf16 v[90:93], v[138:141], v[178:181], v[90:93]
	v_mfma_f32_16x16x32_bf16 v[78:81], v[130:133], v[240:243], v[78:81]
	v_mfma_f32_16x16x32_bf16 v[74:77], v[138:141], v[240:243], v[74:77]
	v_mfma_f32_16x16x32_bf16 v[126:129], v[134:137], v[166:169], v[126:129]
	v_mfma_f32_16x16x32_bf16 v[122:125], v[142:145], v[166:169], v[122:125]
	v_mfma_f32_16x16x32_bf16 v[110:113], v[134:137], v[174:177], v[110:113]
	v_mfma_f32_16x16x32_bf16 v[106:109], v[142:145], v[174:177], v[106:109]
	v_mfma_f32_16x16x32_bf16 v[94:97], v[134:137], v[182:185], v[94:97]
	v_mfma_f32_16x16x32_bf16 v[90:93], v[142:145], v[182:185], v[90:93]
	v_mfma_f32_16x16x32_bf16 v[78:81], v[134:137], v[244:247], v[78:81]
	v_mfma_f32_16x16x32_bf16 v[74:77], v[142:145], v[244:247], v[74:77]
	v_mfma_f32_16x16x32_bf16 v[118:121], v[146:149], v[162:165], v[118:121]
	s_add_i32 s79, s74, s61
	v_mfma_f32_16x16x32_bf16 v[114:117], v[154:157], v[162:165], v[114:117]
	s_mov_b32 m0, s79
	v_mfma_f32_16x16x32_bf16 v[102:105], v[146:149], v[170:173], v[102:105]
	v_mfma_f32_16x16x32_bf16 v[98:101], v[154:157], v[170:173], v[98:101]
	v_mfma_f32_16x16x32_bf16 v[86:89], v[146:149], v[178:181], v[86:89]
	v_mfma_f32_16x16x32_bf16 v[82:85], v[154:157], v[178:181], v[82:85]
	v_mfma_f32_16x16x32_bf16 v[70:73], v[146:149], v[240:243], v[70:73]
	v_mfma_f32_16x16x32_bf16 v[66:69], v[154:157], v[240:243], v[66:69]
	v_mfma_f32_16x16x32_bf16 v[118:121], v[150:153], v[166:169], v[118:121]
	v_mfma_f32_16x16x32_bf16 v[114:117], v[158:161], v[166:169], v[114:117]
	v_mfma_f32_16x16x32_bf16 v[102:105], v[150:153], v[174:177], v[102:105]
	v_mfma_f32_16x16x32_bf16 v[98:101], v[158:161], v[174:177], v[98:101]
	v_mfma_f32_16x16x32_bf16 v[86:89], v[150:153], v[182:185], v[86:89]
	v_mfma_f32_16x16x32_bf16 v[82:85], v[158:161], v[182:185], v[82:85]
	v_mfma_f32_16x16x32_bf16 v[70:73], v[150:153], v[244:247], v[70:73]
	v_mfma_f32_16x16x32_bf16 v[66:69], v[158:161], v[244:247], v[66:69]
	s_barrier
	v_lshl_add_u64 v[248:249], s[54:55], 0, v[188:189]
	ds_read_b128 v[162:165], v236 offset:16384
	ds_read_b128 v[166:169], v236 offset:17408
	ds_read_b128 v[170:173], v236 offset:18432
	ds_read_b128 v[174:177], v236 offset:19456
	ds_read_b128 v[178:181], v236 offset:20480
	ds_read_b128 v[182:185], v236 offset:21504
	ds_read_b128 v[240:243], v236 offset:22528
	ds_read_b128 v[244:247], v236 offset:23552
	global_load_lds_dwordx4 v[248:249], off
	s_add_i32 m0, s79, 0x2000
	s_add_u32 s82, s54, 0xb0000
	v_lshl_add_u64 v[250:251], s[54:55], 0, v[190:191]
	s_addc_u32 s83, s55, 0
	s_add_i32 s79, s75, s61
	global_load_lds_dwordx4 v[250:251], off
	v_lshl_add_u64 v[252:253], s[82:83], 0, v[188:189]
	s_mov_b32 m0, s79
	s_nop 0
	global_load_lds_dwordx4 v[252:253], off
	v_lshl_add_u64 v[252:253], s[82:83], 0, v[190:191]
	s_add_i32 m0, s79, 0x2000
	s_nop 0
	global_load_lds_dwordx4 v[252:253], off
	v_lshl_add_u64 v[252:253], s[80:81], 0, v[186:187]
	s_mov_b32 m0, s62
	v_lshl_add_u64 v[208:209], v[252:253], 0, s[22:23]
	global_load_lds_dwordx4 v[252:253], off
	s_mov_b32 m0, s63
	s_nop 0
	global_load_lds_dwordx4 v[208:209], off
	s_waitcnt vmcnt(8)
	s_waitcnt lgkmcnt(0)
	s_barrier
; #define PG8_STAGE(bufoff, gbase, voff) do { _Pragma("unroll") for (int _i = 0; _i < 2; ++_i) \
;         __builtin_amdgcn_global_load_lds((const unsigned*)((const char*)(gbase) + (voff)[_i]), (PG8_LAS unsigned*)(lds + (bufoff) + ldsw + _i * 8192), 16, 0, 0); } while (0)
; #define PG8_LDA(dst, b, h) do { _Pragma("unroll") for (int m = 0; m < 4; ++m) _Pragma("unroll") for (int k = 0; k < 2; ++k) dst[m][k] = *(const PG8_LAS bf16x8*)(lds + PG8_SA(b, h) + aoff + m * 2048 + k * 1024); } while (0)
; #define PG8_LDB(dst, b, h) do { _Pragma("unroll") for (int n = 0; n < 2; ++n) _Pragma("unroll") for (int k = 0; k < 2; ++k) dst[n][k] = *(const PG8_LAS bf16x8*)(lds + PG8_SB(b, h) + boff + n * 2048 + k * 1024); } while (0)
; #define PG8_MMA(ai, bj, At, Bt) do { __builtin_amdgcn_s_setprio(1); _Pragma("unroll") for (int m = 0; m < 4; ++m) _Pragma("unroll") for (int n = 0; n < 2; ++n) _Pragma("unroll") for (int k = 0; k < 2; ++k) \
;         acc[ai][bj][m][n] = __builtin_amdgcn_mfma_f32_16x16x32_bf16(Bt[n][k], At[m][k], acc[ai][bj][m][n], 0, 0, 0); __builtin_amdgcn_s_setprio(0); } while (0)
; #define PG8_WAIT_V(n) asm volatile("s_waitcnt vmcnt(" #n ")" ::: "memory")
; #define PG8_WAIT_L(n) asm volatile("s_waitcnt lgkmcnt(" #n ")" ::: "memory")
; #define PG8_BAR __builtin_amdgcn_s_barrier()
; #define PG8_SCHED __builtin_amdgcn_sched_barrier(0)
; template <class Epi, bool ALIGN_EPI, bool ABLK = false>
; __device__ __forceinline__ void gemm_phase(PG8_LAS unsigned char* lds, const Gemm g, const StaticOrder& S, const Epi& E) {
;     ...
;             PG8_WAIT_V(8); PG8_WAIT_L(0); PG8_BAR; PG8_MMA(1, 0, At, B0); PG8_MMA(1, 1, At, B1); PG8_BAR; PG8_SCHED;
;             PG8_LDB(B0, 1, 0); PG8_LDB(B1, 1, 1); PG8_SCHED; PG8_LDA(At, 1, 0); PG8_STAGE(PG8_SA(0, 1), a2 + hstepA, voffA);
;             PG8_WAIT_V(8); PG8_WAIT_L(0); PG8_BAR; PG8_MMA(0, 0, At, B0); PG8_MMA(0, 1, At, B1); PG8_BAR; PG8_SCHED;
	s_waitcnt lgkmcnt(0)
	v_mfma_f32_16x16x32_bf16 v[62:65], v[130:133], v[162:165], v[62:65]
	v_mfma_f32_16x16x32_bf16 v[58:61], v[138:141], v[162:165], v[58:61]
	v_mfma_f32_16x16x32_bf16 v[46:49], v[130:133], v[170:173], v[46:49]
	v_mfma_f32_16x16x32_bf16 v[42:45], v[138:141], v[170:173], v[42:45]
	v_mfma_f32_16x16x32_bf16 v[30:33], v[130:133], v[178:181], v[30:33]
	v_mfma_f32_16x16x32_bf16 v[26:29], v[138:141], v[178:181], v[26:29]
	v_mfma_f32_16x16x32_bf16 v[14:17], v[130:133], v[240:243], v[14:17]
	v_mfma_f32_16x16x32_bf16 v[10:13], v[138:141], v[240:243], v[10:13]
	v_mfma_f32_16x16x32_bf16 v[62:65], v[134:137], v[166:169], v[62:65]
	v_mfma_f32_16x16x32_bf16 v[58:61], v[142:145], v[166:169], v[58:61]
	v_mfma_f32_16x16x32_bf16 v[46:49], v[134:137], v[174:177], v[46:49]
	v_mfma_f32_16x16x32_bf16 v[42:45], v[142:145], v[174:177], v[42:45]
	v_mfma_f32_16x16x32_bf16 v[30:33], v[134:137], v[182:185], v[30:33]
	v_mfma_f32_16x16x32_bf16 v[26:29], v[142:145], v[182:185], v[26:29]
	v_mfma_f32_16x16x32_bf16 v[14:17], v[134:137], v[244:247], v[14:17]
	v_mfma_f32_16x16x32_bf16 v[10:13], v[142:145], v[244:247], v[10:13]
	v_mfma_f32_16x16x32_bf16 v[54:57], v[146:149], v[162:165], v[54:57]
	s_add_i32 s79, 0, 0x18000
	v_mfma_f32_16x16x32_bf16 v[50:53], v[154:157], v[162:165], v[50:53]
	s_add_i32 s80, 0, 0x1c000
	v_mfma_f32_16x16x32_bf16 v[38:41], v[146:149], v[170:173], v[38:41]
	v_mfma_f32_16x16x32_bf16 v[34:37], v[154:157], v[170:173], v[34:37]
	v_mfma_f32_16x16x32_bf16 v[22:25], v[146:149], v[178:181], v[22:25]
	v_mfma_f32_16x16x32_bf16 v[18:21], v[154:157], v[178:181], v[18:21]
	v_mfma_f32_16x16x32_bf16 v[6:9], v[146:149], v[240:243], v[6:9]
	v_mfma_f32_16x16x32_bf16 v[2:5], v[154:157], v[240:243], v[2:5]
	v_mfma_f32_16x16x32_bf16 v[54:57], v[150:153], v[166:169], v[54:57]
	v_mfma_f32_16x16x32_bf16 v[50:53], v[158:161], v[166:169], v[50:53]
	v_mfma_f32_16x16x32_bf16 v[38:41], v[150:153], v[174:177], v[38:41]
	v_mfma_f32_16x16x32_bf16 v[34:37], v[158:161], v[174:177], v[34:37]
	v_mfma_f32_16x16x32_bf16 v[22:25], v[150:153], v[182:185], v[22:25]
	v_mfma_f32_16x16x32_bf16 v[18:21], v[158:161], v[182:185], v[18:21]
	v_mfma_f32_16x16x32_bf16 v[6:9], v[150:153], v[244:247], v[6:9]
	v_mfma_f32_16x16x32_bf16 v[2:5], v[158:161], v[244:247], v[2:5]
	s_barrier
	v_add_u32_e32 v142, s79, v215
	v_add_u32_e32 v158, s80, v215
	ds_read_b128 v[130:133], v142
	ds_read_b128 v[134:137], v142 offset:1024
	ds_read_b128 v[138:141], v142 offset:2048
	ds_read_b128 v[142:145], v142 offset:3072
	ds_read_b128 v[146:149], v158
	ds_read_b128 v[150:153], v158 offset:1024
	ds_read_b128 v[154:157], v158 offset:2048
	ds_read_b128 v[158:161], v158 offset:3072
	s_mov_b32 m0, s64
	v_lshl_add_u64 v[208:209], v[252:253], 0, s[24:25]
	ds_read_b128 v[162:165], v236 offset:32768
	ds_read_b128 v[166:169], v236 offset:33792
	ds_read_b128 v[170:173], v236 offset:34816
	ds_read_b128 v[174:177], v236 offset:35840
	ds_read_b128 v[178:181], v236 offset:36864
	ds_read_b128 v[182:185], v236 offset:37888
	ds_read_b128 v[240:243], v236 offset:38912
	ds_read_b128 v[244:247], v236 offset:39936
	global_load_lds_dwordx4 v[208:209], off
	v_lshl_add_u64 v[208:209], v[252:253], 0, s[26:27]
	s_mov_b32 m0, s65
	s_nop 0
	global_load_lds_dwordx4 v[208:209], off
	s_waitcnt vmcnt(8)
	s_waitcnt lgkmcnt(0)
	s_barrier
	s_waitcnt lgkmcnt(0)
	v_mfma_f32_16x16x32_bf16 v[126:129], v[130:133], v[162:165], v[126:129]
	v_mfma_f32_16x16x32_bf16 v[122:125], v[138:141], v[162:165], v[122:125]
	v_mfma_f32_16x16x32_bf16 v[110:113], v[130:133], v[170:173], v[110:113]
	v_mfma_f32_16x16x32_bf16 v[106:109], v[138:141], v[170:173], v[106:109]
	v_mfma_f32_16x16x32_bf16 v[94:97], v[130:133], v[178:181], v[94:97]
	v_mfma_f32_16x16x32_bf16 v[90:93], v[138:141], v[178:181], v[90:93]
	v_mfma_f32_16x16x32_bf16 v[78:81], v[130:133], v[240:243], v[78:81]
	v_mfma_f32_16x16x32_bf16 v[74:77], v[138:141], v[240:243], v[74:77]
	v_mfma_f32_16x16x32_bf16 v[126:129], v[134:137], v[166:169], v[126:129]
	v_mfma_f32_16x16x32_bf16 v[122:125], v[142:145], v[166:169], v[122:125]
	v_mfma_f32_16x16x32_bf16 v[110:113], v[134:137], v[174:177], v[110:113]
	v_mfma_f32_16x16x32_bf16 v[106:109], v[142:145], v[174:177], v[106:109]
	v_mfma_f32_16x16x32_bf16 v[94:97], v[134:137], v[182:185], v[94:97]
	v_mfma_f32_16x16x32_bf16 v[90:93], v[142:145], v[182:185], v[90:93]
	v_mfma_f32_16x16x32_bf16 v[78:81], v[134:137], v[244:247], v[78:81]
	v_mfma_f32_16x16x32_bf16 v[74:77], v[142:145], v[244:247], v[74:77]
	v_mfma_f32_16x16x32_bf16 v[118:121], v[146:149], v[162:165], v[118:121]
	s_add_i32 s79, s79, s61
	v_mfma_f32_16x16x32_bf16 v[114:117], v[154:157], v[162:165], v[114:117]
	s_mov_b32 m0, s79
	v_mfma_f32_16x16x32_bf16 v[102:105], v[146:149], v[170:173], v[102:105]
	v_mfma_f32_16x16x32_bf16 v[98:101], v[154:157], v[170:173], v[98:101]
	v_mfma_f32_16x16x32_bf16 v[86:89], v[146:149], v[178:181], v[86:89]
	v_mfma_f32_16x16x32_bf16 v[82:85], v[154:157], v[178:181], v[82:85]
	v_mfma_f32_16x16x32_bf16 v[70:73], v[146:149], v[240:243], v[70:73]
	v_mfma_f32_16x16x32_bf16 v[66:69], v[154:157], v[240:243], v[66:69]
	v_mfma_f32_16x16x32_bf16 v[118:121], v[150:153], v[166:169], v[118:121]
	v_mfma_f32_16x16x32_bf16 v[114:117], v[158:161], v[166:169], v[114:117]
	v_mfma_f32_16x16x32_bf16 v[102:105], v[150:153], v[174:177], v[102:105]
	v_mfma_f32_16x16x32_bf16 v[98:101], v[158:161], v[174:177], v[98:101]
	v_mfma_f32_16x16x32_bf16 v[86:89], v[150:153], v[182:185], v[86:89]
	v_mfma_f32_16x16x32_bf16 v[82:85], v[158:161], v[182:185], v[82:85]
	v_mfma_f32_16x16x32_bf16 v[70:73], v[150:153], v[244:247], v[70:73]
	v_mfma_f32_16x16x32_bf16 v[66:69], v[158:161], v[244:247], v[66:69]
	s_barrier
; #define PG8_STAGE(bufoff, gbase, voff) do { _Pragma("unroll") for (int _i = 0; _i < 2; ++_i) \
;         __builtin_amdgcn_global_load_lds((const unsigned*)((const char*)(gbase) + (voff)[_i]), (PG8_LAS unsigned*)(lds + (bufoff) + ldsw + _i * 8192), 16, 0, 0); } while (0)
; #define PG8_LDA(dst, b, h) do { _Pragma("unroll") for (int m = 0; m < 4; ++m) _Pragma("unroll") for (int k = 0; k < 2; ++k) dst[m][k] = *(const PG8_LAS bf16x8*)(lds + PG8_SA(b, h) + aoff + m * 2048 + k * 1024); } while (0)
; #define PG8_MMA(ai, bj, At, Bt) do { __builtin_amdgcn_s_setprio(1); _Pragma("unroll") for (int m = 0; m < 4; ++m) _Pragma("unroll") for (int n = 0; n < 2; ++n) _Pragma("unroll") for (int k = 0; k < 2; ++k) \
;         acc[ai][bj][m][n] = __builtin_amdgcn_mfma_f32_16x16x32_bf16(Bt[n][k], At[m][k], acc[ai][bj][m][n], 0, 0, 0); __builtin_amdgcn_s_setprio(0); } while (0)
; #define PG8_WAIT_V(n) asm volatile("s_waitcnt vmcnt(" #n ")" ::: "memory")
; #define PG8_WAIT_L(n) asm volatile("s_waitcnt lgkmcnt(" #n ")" ::: "memory")
; #define PG8_BAR __builtin_amdgcn_s_barrier()
; #define PG8_SCHED __builtin_amdgcn_sched_barrier(0)
; template <class Epi, bool ALIGN_EPI, bool ABLK = false>
; __device__ __forceinline__ void gemm_phase(PG8_LAS unsigned char* lds, const Gemm g, const StaticOrder& S, const Epi& E) {
;     ...
;             PG8_LDA(At, 1, 1); PG8_STAGE(PG8_SB(1, 0), b3, voffB); PG8_STAGE(PG8_SB(1, 1), b3 + hstepB, voffB); PG8_STAGE(PG8_SA(1, 0), a3, voffA);
;             PG8_WAIT_V(8); PG8_WAIT_L(0); PG8_BAR; PG8_MMA(1, 0, At, B0); PG8_MMA(1, 1, At, B1); PG8_BAR; PG8_SCHED;
;         }
;         if constexpr (ALIGN_EPI) { if (wr == 0) PG8_BAR; }
	v_lshl_add_u64 v[208:209], v[248:249], 0, s[34:35]
	ds_read_b128 v[162:165], v236 offset:49152
	ds_read_b128 v[166:169], v236 offset:50176
	ds_read_b128 v[170:173], v236 offset:51200
	ds_read_b128 v[174:177], v236 offset:52224
	ds_read_b128 v[178:181], v236 offset:53248
	ds_read_b128 v[182:185], v236 offset:54272
	ds_read_b128 v[240:243], v236 offset:55296
	ds_read_b128 v[244:247], v236 offset:56320
	global_load_lds_dwordx4 v[208:209], off
	s_add_i32 m0, s79, 0x2000
	s_add_u32 s54, s54, 0xb0080
	v_lshl_add_u64 v[208:209], v[250:251], 0, s[34:35]
	s_addc_u32 s55, s55, 0
	s_add_i32 s79, s80, s61
	global_load_lds_dwordx4 v[208:209], off
	v_lshl_add_u64 v[208:209], s[54:55], 0, v[188:189]
	s_mov_b32 m0, s79
	s_nop 0
	global_load_lds_dwordx4 v[208:209], off
	v_lshl_add_u64 v[208:209], s[54:55], 0, v[190:191]
	s_add_i32 m0, s79, 0x2000
	s_nop 0
	global_load_lds_dwordx4 v[208:209], off
	v_lshl_add_u64 v[208:209], v[252:253], 0, s[36:37]
	s_mov_b32 m0, s69
	s_nop 0
	global_load_lds_dwordx4 v[208:209], off
	v_lshl_add_u64 v[208:209], v[252:253], 0, s[38:39]
	s_mov_b32 m0, s70
	s_nop 0
	global_load_lds_dwordx4 v[208:209], off
	s_waitcnt vmcnt(8)
	s_waitcnt lgkmcnt(0)
	s_barrier
	s_waitcnt lgkmcnt(0)
	v_mfma_f32_16x16x32_bf16 v[62:65], v[130:133], v[162:165], v[62:65]
	v_mfma_f32_16x16x32_bf16 v[58:61], v[138:141], v[162:165], v[58:61]
	v_mfma_f32_16x16x32_bf16 v[46:49], v[130:133], v[170:173], v[46:49]
	v_mfma_f32_16x16x32_bf16 v[42:45], v[138:141], v[170:173], v[42:45]
	v_mfma_f32_16x16x32_bf16 v[30:33], v[130:133], v[178:181], v[30:33]
	v_mfma_f32_16x16x32_bf16 v[26:29], v[138:141], v[178:181], v[26:29]
	v_mfma_f32_16x16x32_bf16 v[14:17], v[130:133], v[240:243], v[14:17]
	v_mfma_f32_16x16x32_bf16 v[10:13], v[138:141], v[240:243], v[10:13]
	v_mfma_f32_16x16x32_bf16 v[62:65], v[134:137], v[166:169], v[62:65]
	v_mfma_f32_16x16x32_bf16 v[58:61], v[142:145], v[166:169], v[58:61]
	v_mfma_f32_16x16x32_bf16 v[46:49], v[134:137], v[174:177], v[46:49]
	v_mfma_f32_16x16x32_bf16 v[42:45], v[142:145], v[174:177], v[42:45]
	v_mfma_f32_16x16x32_bf16 v[30:33], v[134:137], v[182:185], v[30:33]
	v_mfma_f32_16x16x32_bf16 v[26:29], v[142:145], v[182:185], v[26:29]
	v_mfma_f32_16x16x32_bf16 v[14:17], v[134:137], v[244:247], v[14:17]
	v_mfma_f32_16x16x32_bf16 v[10:13], v[142:145], v[244:247], v[10:13]
	v_mfma_f32_16x16x32_bf16 v[54:57], v[146:149], v[162:165], v[54:57]
	s_add_i32 s57, s57, 2
	v_mfma_f32_16x16x32_bf16 v[50:53], v[154:157], v[162:165], v[50:53]
	s_add_u32 s51, s51, 0x100
	v_mfma_f32_16x16x32_bf16 v[38:41], v[146:149], v[170:173], v[38:41]
	s_addc_u32 s56, s56, 0
	v_mfma_f32_16x16x32_bf16 v[34:37], v[154:157], v[170:173], v[34:37]
	s_add_u32 s52, s52, 0x10000
	v_mfma_f32_16x16x32_bf16 v[22:25], v[146:149], v[178:181], v[22:25]
	s_addc_u32 s53, s53, 0
	v_mfma_f32_16x16x32_bf16 v[18:21], v[154:157], v[178:181], v[18:21]
	s_cmp_gt_u32 s57, 41
	v_mfma_f32_16x16x32_bf16 v[6:9], v[146:149], v[240:243], v[6:9]
	v_mfma_f32_16x16x32_bf16 v[2:5], v[154:157], v[240:243], v[2:5]
	v_mfma_f32_16x16x32_bf16 v[54:57], v[150:153], v[166:169], v[54:57]
	v_mfma_f32_16x16x32_bf16 v[50:53], v[158:161], v[166:169], v[50:53]
	v_mfma_f32_16x16x32_bf16 v[38:41], v[150:153], v[174:177], v[38:41]
	v_mfma_f32_16x16x32_bf16 v[34:37], v[158:161], v[174:177], v[34:37]
	v_mfma_f32_16x16x32_bf16 v[22:25], v[150:153], v[182:185], v[22:25]
	v_mfma_f32_16x16x32_bf16 v[18:21], v[158:161], v[182:185], v[18:21]
	v_mfma_f32_16x16x32_bf16 v[6:9], v[150:153], v[244:247], v[6:9]
	v_mfma_f32_16x16x32_bf16 v[2:5], v[158:161], v[244:247], v[2:5]
	s_barrier
	s_cbranch_scc0 .LBB0_2631
	s_and_b64 vcc, exec, s[40:41]
	s_cbranch_vccz .LBB0_2634
	s_barrier
